# GEMM MMA blocks: the mid-block s_setprio 0 / s_setprio 1 flip between the two 16-MFMA groups removed (priority stays raised across the 32 MFMAs)
# speedup vs baseline: 1.0015x; 1.0015x over previous
.LBB0_398:
	s_add_u32 s48, s10, 0xfffc0080
	s_addc_u32 s49, s11, -1
	s_add_i32 s83, 0, 0x10000
	s_cmp_eq_u32 s67, 12
	s_cselect_b32 s61, s9, s49
	s_cselect_b32 s60, s55, s48
	v_add_u32_e32 v128, s83, v173
	s_cselect_b32 s49, s53, s66
	s_cselect_b32 s48, s64, s65
	s_add_i32 s85, 0, 0x14000
	ds_read_b128 v[168:171], v128
	ds_read_b128 v[176:179], v128 offset:1024
	ds_read_b128 v[180:183], v128 offset:2048
	ds_read_b128 v[184:187], v128 offset:3072
	v_add_u32_e32 v128, s85, v173
	ds_read_b128 v[188:191], v128
	ds_read_b128 v[192:195], v128 offset:1024
	ds_read_b128 v[196:199], v128 offset:2048
	ds_read_b128 v[202:205], v128 offset:3072
	s_add_i32 m0, s63, 0xc000
	ds_read_b128 v[206:209], v200
	ds_read_b128 v[210:213], v200 offset:1024
	ds_read_b128 v[218:221], v200 offset:2048
	ds_read_b128 v[222:225], v200 offset:3072
	ds_read_b128 v[226:229], v200 offset:4096
	ds_read_b128 v[234:237], v200 offset:5120
	ds_read_b128 v[238:241], v200 offset:6144
	ds_read_b128 v[242:245], v200 offset:7168
	global_load_lds_dwordx4 v148, s[10:11]
	s_add_i32 m0, s63, 0xe000
	s_nop 0
	global_load_lds_dwordx4 v150, s[10:11]
	s_waitcnt vmcnt(8)
	s_waitcnt lgkmcnt(0)
	s_barrier
	s_setprio 1
	s_waitcnt lgkmcnt(0)
	v_mfma_f32_16x16x32_bf16 v[124:127], v[168:171], v[206:209], v[124:127]
	v_mfma_f32_16x16x32_bf16 v[120:123], v[180:183], v[206:209], v[120:123]
	v_mfma_f32_16x16x32_bf16 v[108:111], v[168:171], v[218:221], v[108:111]
	v_mfma_f32_16x16x32_bf16 v[104:107], v[180:183], v[218:221], v[104:107]
	v_mfma_f32_16x16x32_bf16 v[92:95], v[168:171], v[226:229], v[92:95]
	v_mfma_f32_16x16x32_bf16 v[88:91], v[180:183], v[226:229], v[88:91]
	v_mfma_f32_16x16x32_bf16 v[76:79], v[168:171], v[238:241], v[76:79]
	v_mfma_f32_16x16x32_bf16 v[72:75], v[180:183], v[238:241], v[72:75]
	v_mfma_f32_16x16x32_bf16 v[124:127], v[176:179], v[210:213], v[124:127]
	v_mfma_f32_16x16x32_bf16 v[120:123], v[184:187], v[210:213], v[120:123]
	v_mfma_f32_16x16x32_bf16 v[108:111], v[176:179], v[222:225], v[108:111]
	v_mfma_f32_16x16x32_bf16 v[104:107], v[184:187], v[222:225], v[104:107]
	v_mfma_f32_16x16x32_bf16 v[92:95], v[176:179], v[234:237], v[92:95]
	v_mfma_f32_16x16x32_bf16 v[88:91], v[184:187], v[234:237], v[88:91]
	v_mfma_f32_16x16x32_bf16 v[76:79], v[176:179], v[242:245], v[76:79]
	v_mfma_f32_16x16x32_bf16 v[72:75], v[184:187], v[242:245], v[72:75]
	v_mfma_f32_16x16x32_bf16 v[116:119], v[188:191], v[206:209], v[116:119]
	v_mfma_f32_16x16x32_bf16 v[112:115], v[196:199], v[206:209], v[112:115]
	v_mfma_f32_16x16x32_bf16 v[100:103], v[188:191], v[218:221], v[100:103]
	v_mfma_f32_16x16x32_bf16 v[96:99], v[196:199], v[218:221], v[96:99]
	v_mfma_f32_16x16x32_bf16 v[84:87], v[188:191], v[226:229], v[84:87]
	v_mfma_f32_16x16x32_bf16 v[80:83], v[196:199], v[226:229], v[80:83]
	v_mfma_f32_16x16x32_bf16 v[68:71], v[188:191], v[238:241], v[68:71]
	v_mfma_f32_16x16x32_bf16 v[64:67], v[196:199], v[238:241], v[64:67]
	v_mfma_f32_16x16x32_bf16 v[116:119], v[192:195], v[210:213], v[116:119]
	v_mfma_f32_16x16x32_bf16 v[112:115], v[202:205], v[210:213], v[112:115]
	v_mfma_f32_16x16x32_bf16 v[100:103], v[192:195], v[222:225], v[100:103]
	v_mfma_f32_16x16x32_bf16 v[96:99], v[202:205], v[222:225], v[96:99]
	v_mfma_f32_16x16x32_bf16 v[84:87], v[192:195], v[234:237], v[84:87]
	v_mfma_f32_16x16x32_bf16 v[80:83], v[202:205], v[234:237], v[80:83]
	v_mfma_f32_16x16x32_bf16 v[68:71], v[192:195], v[242:245], v[68:71]
	v_mfma_f32_16x16x32_bf16 v[64:67], v[202:205], v[242:245], v[64:67]
	s_setprio 0
	s_barrier
	s_add_i32 s83, s83, s74
	s_mov_b64 s[98:99], s[48:49]
	s_mov_b32 m0, s83
	ds_read_b128 v[206:209], v200 offset:16384
	ds_read_b128 v[210:213], v200 offset:17408
	ds_read_b128 v[218:221], v200 offset:18432
	ds_read_b128 v[222:225], v200 offset:19456
	ds_read_b128 v[226:229], v200 offset:20480
	ds_read_b128 v[234:237], v200 offset:21504
	ds_read_b128 v[238:241], v200 offset:22528
	ds_read_b128 v[242:245], v200 offset:23552
	global_load_lds_dwordx4 v136, s[48:49]
	s_add_i32 m0, s83, 0x2000
	s_add_u32 s86, s48, 0x40000
	s_addc_u32 s87, s49, 0
	s_add_i32 s83, s85, s74
	global_load_lds_dwordx4 v140, s[48:49]
	s_mov_b32 m0, s83
	s_mov_b64 s[100:101], s[60:61]
	global_load_lds_dwordx4 v136, s[86:87]
	s_add_i32 m0, s83, 0x2000
	s_nop 0
	global_load_lds_dwordx4 v140, s[86:87]
	s_mov_b32 m0, s63
	s_nop 0
	global_load_lds_dwordx4 v134, s[60:61]
	s_mov_b32 m0, s75
	s_nop 0
	global_load_lds_dwordx4 v138, s[60:61]
	s_waitcnt vmcnt(8)
	s_waitcnt lgkmcnt(0)
	s_barrier
	s_setprio 1
	s_waitcnt lgkmcnt(0)
	v_mfma_f32_16x16x32_bf16 v[60:63], v[168:171], v[206:209], v[60:63]
	v_mfma_f32_16x16x32_bf16 v[56:59], v[180:183], v[206:209], v[56:59]
	v_mfma_f32_16x16x32_bf16 v[44:47], v[168:171], v[218:221], v[44:47]
	v_mfma_f32_16x16x32_bf16 v[40:43], v[180:183], v[218:221], v[40:43]
	v_mfma_f32_16x16x32_bf16 v[28:31], v[168:171], v[226:229], v[28:31]
	v_mfma_f32_16x16x32_bf16 v[24:27], v[180:183], v[226:229], v[24:27]
	v_mfma_f32_16x16x32_bf16 v[12:15], v[168:171], v[238:241], v[12:15]
	v_mfma_f32_16x16x32_bf16 v[8:11], v[180:183], v[238:241], v[8:11]
	v_mfma_f32_16x16x32_bf16 v[60:63], v[176:179], v[210:213], v[60:63]
	v_mfma_f32_16x16x32_bf16 v[56:59], v[184:187], v[210:213], v[56:59]
	v_mfma_f32_16x16x32_bf16 v[44:47], v[176:179], v[222:225], v[44:47]
	v_mfma_f32_16x16x32_bf16 v[40:43], v[184:187], v[222:225], v[40:43]
	v_mfma_f32_16x16x32_bf16 v[28:31], v[176:179], v[234:237], v[28:31]
	v_mfma_f32_16x16x32_bf16 v[24:27], v[184:187], v[234:237], v[24:27]
	v_mfma_f32_16x16x32_bf16 v[12:15], v[176:179], v[242:245], v[12:15]
	v_mfma_f32_16x16x32_bf16 v[8:11], v[184:187], v[242:245], v[8:11]
	v_mfma_f32_16x16x32_bf16 v[52:55], v[188:191], v[206:209], v[52:55]
	v_mfma_f32_16x16x32_bf16 v[48:51], v[196:199], v[206:209], v[48:51]
	v_mfma_f32_16x16x32_bf16 v[36:39], v[188:191], v[218:221], v[36:39]
	v_mfma_f32_16x16x32_bf16 v[32:35], v[196:199], v[218:221], v[32:35]
	v_mfma_f32_16x16x32_bf16 v[20:23], v[188:191], v[226:229], v[20:23]
	v_mfma_f32_16x16x32_bf16 v[16:19], v[196:199], v[226:229], v[16:19]
	v_mfma_f32_16x16x32_bf16 v[4:7], v[188:191], v[238:241], v[4:7]
	v_mfma_f32_16x16x32_bf16 v[0:3], v[196:199], v[238:241], v[0:3]
	v_mfma_f32_16x16x32_bf16 v[52:55], v[192:195], v[210:213], v[52:55]
	v_mfma_f32_16x16x32_bf16 v[48:51], v[202:205], v[210:213], v[48:51]
	v_mfma_f32_16x16x32_bf16 v[36:39], v[192:195], v[222:225], v[36:39]
	v_mfma_f32_16x16x32_bf16 v[32:35], v[202:205], v[222:225], v[32:35]
	v_mfma_f32_16x16x32_bf16 v[20:23], v[192:195], v[234:237], v[20:23]
	v_mfma_f32_16x16x32_bf16 v[16:19], v[202:205], v[234:237], v[16:19]
	v_mfma_f32_16x16x32_bf16 v[4:7], v[192:195], v[242:245], v[4:7]
	v_mfma_f32_16x16x32_bf16 v[0:3], v[202:205], v[242:245], v[0:3]
	s_setprio 0
	s_barrier
	v_add_u32_e32 v128, s0, v173
	s_add_i32 s83, 0, 0x1c000
	ds_read_b128 v[168:171], v128
	ds_read_b128 v[176:179], v128 offset:1024
	ds_read_b128 v[180:183], v128 offset:2048
	ds_read_b128 v[184:187], v128 offset:3072
	v_add_u32_e32 v128, s83, v173
	ds_read_b128 v[188:191], v128
	ds_read_b128 v[192:195], v128 offset:1024
	ds_read_b128 v[196:199], v128 offset:2048
	ds_read_b128 v[202:205], v128 offset:3072
	s_add_u32 s60, s60, 0x40000
	s_addc_u32 s61, s61, 0
	s_mov_b32 m0, s76
	ds_read_b128 v[206:209], v200 offset:32768
	ds_read_b128 v[210:213], v200 offset:33792
	ds_read_b128 v[218:221], v200 offset:34816
	ds_read_b128 v[222:225], v200 offset:35840
	ds_read_b128 v[226:229], v200 offset:36864
	ds_read_b128 v[234:237], v200 offset:37888
	ds_read_b128 v[238:241], v200 offset:38912
	ds_read_b128 v[242:245], v200 offset:39936
	global_load_lds_dwordx4 v134, s[60:61]
	v_lshl_add_u64 v[250:251], s[60:61], 0, v[138:139]
	s_mov_b32 m0, s77
	s_nop 0
	global_load_lds_dwordx4 v[250:251], off
	s_waitcnt vmcnt(8)
	s_waitcnt lgkmcnt(0)
	s_barrier
	s_setprio 1
	s_waitcnt lgkmcnt(0)
	v_mfma_f32_16x16x32_bf16 v[124:127], v[168:171], v[206:209], v[124:127]
	v_mfma_f32_16x16x32_bf16 v[120:123], v[180:183], v[206:209], v[120:123]
	v_mfma_f32_16x16x32_bf16 v[108:111], v[168:171], v[218:221], v[108:111]
	v_mfma_f32_16x16x32_bf16 v[104:107], v[180:183], v[218:221], v[104:107]
	v_mfma_f32_16x16x32_bf16 v[92:95], v[168:171], v[226:229], v[92:95]
	v_mfma_f32_16x16x32_bf16 v[88:91], v[180:183], v[226:229], v[88:91]
	v_mfma_f32_16x16x32_bf16 v[76:79], v[168:171], v[238:241], v[76:79]
	v_mfma_f32_16x16x32_bf16 v[72:75], v[180:183], v[238:241], v[72:75]
	v_mfma_f32_16x16x32_bf16 v[124:127], v[176:179], v[210:213], v[124:127]
	v_mfma_f32_16x16x32_bf16 v[120:123], v[184:187], v[210:213], v[120:123]
	v_mfma_f32_16x16x32_bf16 v[108:111], v[176:179], v[222:225], v[108:111]
	v_mfma_f32_16x16x32_bf16 v[104:107], v[184:187], v[222:225], v[104:107]
	v_mfma_f32_16x16x32_bf16 v[92:95], v[176:179], v[234:237], v[92:95]
	v_mfma_f32_16x16x32_bf16 v[88:91], v[184:187], v[234:237], v[88:91]
	v_mfma_f32_16x16x32_bf16 v[76:79], v[176:179], v[242:245], v[76:79]
	v_mfma_f32_16x16x32_bf16 v[72:75], v[184:187], v[242:245], v[72:75]
	v_mfma_f32_16x16x32_bf16 v[116:119], v[188:191], v[206:209], v[116:119]
	v_mfma_f32_16x16x32_bf16 v[112:115], v[196:199], v[206:209], v[112:115]
	v_mfma_f32_16x16x32_bf16 v[100:103], v[188:191], v[218:221], v[100:103]
	v_mfma_f32_16x16x32_bf16 v[96:99], v[196:199], v[218:221], v[96:99]
	v_mfma_f32_16x16x32_bf16 v[84:87], v[188:191], v[226:229], v[84:87]
	v_mfma_f32_16x16x32_bf16 v[80:83], v[196:199], v[226:229], v[80:83]
	v_mfma_f32_16x16x32_bf16 v[68:71], v[188:191], v[238:241], v[68:71]
	v_mfma_f32_16x16x32_bf16 v[64:67], v[196:199], v[238:241], v[64:67]
	v_mfma_f32_16x16x32_bf16 v[116:119], v[192:195], v[210:213], v[116:119]
	v_mfma_f32_16x16x32_bf16 v[112:115], v[202:205], v[210:213], v[112:115]
	v_mfma_f32_16x16x32_bf16 v[100:103], v[192:195], v[222:225], v[100:103]
	v_mfma_f32_16x16x32_bf16 v[96:99], v[202:205], v[222:225], v[96:99]
	v_mfma_f32_16x16x32_bf16 v[84:87], v[192:195], v[234:237], v[84:87]
	v_mfma_f32_16x16x32_bf16 v[80:83], v[202:205], v[234:237], v[80:83]
	v_mfma_f32_16x16x32_bf16 v[68:71], v[192:195], v[242:245], v[68:71]
	v_mfma_f32_16x16x32_bf16 v[64:67], v[202:205], v[242:245], v[64:67]
	s_setprio 0
	s_barrier
	s_add_i32 s60, s0, s74
	s_add_u32 s98, s98, s12
	s_addc_u32 s99, s99, s13
	s_mov_b32 m0, s60
	ds_read_b128 v[206:209], v200 offset:49152
	ds_read_b128 v[210:213], v200 offset:50176
	ds_read_b128 v[218:221], v200 offset:51200
	ds_read_b128 v[222:225], v200 offset:52224
	ds_read_b128 v[226:229], v200 offset:53248
	ds_read_b128 v[234:237], v200 offset:54272
	ds_read_b128 v[238:241], v200 offset:55296
	ds_read_b128 v[242:245], v200 offset:56320
	global_load_lds_dwordx4 v136, s[98:99]
	s_add_i32 m0, s60, 0x2000
	s_add_u32 s48, s48, 0x40080
	s_addc_u32 s49, s49, 0
	s_add_i32 s60, s83, s74
	global_load_lds_dwordx4 v140, s[98:99]
	s_mov_b32 m0, s60
	s_nop 0
	global_load_lds_dwordx4 v136, s[48:49]
	s_add_i32 m0, s60, 0x2000
	s_nop 0
	global_load_lds_dwordx4 v140, s[48:49]
	s_add_u32 s100, s100, s12
	s_addc_u32 s101, s101, s13
	s_mov_b32 m0, s78
	s_nop 0
	global_load_lds_dwordx4 v134, s[100:101]
	s_mov_b32 m0, s79
	s_nop 0
	global_load_lds_dwordx4 v138, s[100:101]
	s_waitcnt vmcnt(8)
	s_waitcnt lgkmcnt(0)
	s_barrier
	s_setprio 1
	s_waitcnt lgkmcnt(0)
	v_mfma_f32_16x16x32_bf16 v[60:63], v[168:171], v[206:209], v[60:63]
	v_mfma_f32_16x16x32_bf16 v[56:59], v[180:183], v[206:209], v[56:59]
	v_mfma_f32_16x16x32_bf16 v[44:47], v[168:171], v[218:221], v[44:47]
	v_mfma_f32_16x16x32_bf16 v[40:43], v[180:183], v[218:221], v[40:43]
	v_mfma_f32_16x16x32_bf16 v[28:31], v[168:171], v[226:229], v[28:31]
	v_mfma_f32_16x16x32_bf16 v[24:27], v[180:183], v[226:229], v[24:27]
	v_mfma_f32_16x16x32_bf16 v[12:15], v[168:171], v[238:241], v[12:15]
	v_mfma_f32_16x16x32_bf16 v[8:11], v[180:183], v[238:241], v[8:11]
	v_mfma_f32_16x16x32_bf16 v[60:63], v[176:179], v[210:213], v[60:63]
	v_mfma_f32_16x16x32_bf16 v[56:59], v[184:187], v[210:213], v[56:59]
	v_mfma_f32_16x16x32_bf16 v[44:47], v[176:179], v[222:225], v[44:47]
	v_mfma_f32_16x16x32_bf16 v[40:43], v[184:187], v[222:225], v[40:43]
	v_mfma_f32_16x16x32_bf16 v[28:31], v[176:179], v[234:237], v[28:31]
	v_mfma_f32_16x16x32_bf16 v[24:27], v[184:187], v[234:237], v[24:27]
	v_mfma_f32_16x16x32_bf16 v[12:15], v[176:179], v[242:245], v[12:15]
	v_mfma_f32_16x16x32_bf16 v[8:11], v[184:187], v[242:245], v[8:11]
	v_mfma_f32_16x16x32_bf16 v[52:55], v[188:191], v[206:209], v[52:55]
	v_mfma_f32_16x16x32_bf16 v[48:51], v[196:199], v[206:209], v[48:51]
	v_mfma_f32_16x16x32_bf16 v[36:39], v[188:191], v[218:221], v[36:39]
	v_mfma_f32_16x16x32_bf16 v[32:35], v[196:199], v[218:221], v[32:35]
	v_mfma_f32_16x16x32_bf16 v[20:23], v[188:191], v[226:229], v[20:23]
	v_mfma_f32_16x16x32_bf16 v[16:19], v[196:199], v[226:229], v[16:19]
	v_mfma_f32_16x16x32_bf16 v[4:7], v[188:191], v[238:241], v[4:7]
	v_mfma_f32_16x16x32_bf16 v[0:3], v[196:199], v[238:241], v[0:3]
	v_mfma_f32_16x16x32_bf16 v[52:55], v[192:195], v[210:213], v[52:55]
	v_mfma_f32_16x16x32_bf16 v[48:51], v[202:205], v[210:213], v[48:51]
	v_mfma_f32_16x16x32_bf16 v[36:39], v[192:195], v[222:225], v[36:39]
	v_mfma_f32_16x16x32_bf16 v[32:35], v[202:205], v[222:225], v[32:35]
	v_mfma_f32_16x16x32_bf16 v[20:23], v[192:195], v[234:237], v[20:23]
	v_mfma_f32_16x16x32_bf16 v[16:19], v[202:205], v[234:237], v[16:19]
	v_mfma_f32_16x16x32_bf16 v[4:7], v[192:195], v[242:245], v[4:7]
	v_mfma_f32_16x16x32_bf16 v[0:3], v[202:205], v[242:245], v[0:3]
	s_setprio 0
	s_barrier
	s_add_i32 s67, s67, 2
	s_add_u32 s10, s10, 0x100
	s_addc_u32 s11, s11, 0
	s_add_u32 s65, s65, 0x100
	s_addc_u32 s66, s66, 0
	s_cmp_gt_u32 s67, 13
	s_cbranch_scc0 .LBB0_398
	s_and_b64 vcc, exec, s[50:51]
	s_cbranch_vccz .LBB0_401
	s_barrier

.LBB0_479:
	s_add_u32 s66, s48, 0xfffe0080
	s_addc_u32 s67, s49, -1
	s_add_i32 s90, 0, 0x10000
	s_cmp_eq_u32 vcc_lo, 4
	s_cselect_b32 s71, s9, s67
	s_cselect_b32 s70, s61, s66
	s_cselect_b32 s67, s59, s83
	s_cselect_b32 s66, s72, s73
	s_add_i32 vcc_hi, 0, 0x14000
	v_add_u32_e32 v140, s90, v225
	v_add_u32_e32 v144, vcc_hi, v225
	ds_read_b128 v[128:131], v140
	ds_read_b128 v[132:135], v140 offset:1024
	ds_read_b128 v[136:139], v140 offset:2048
	ds_read_b128 v[140:143], v140 offset:3072
	ds_read_b128 v[174:177], v144
	ds_read_b128 v[178:181], v144 offset:1024
	ds_read_b128 v[182:185], v144 offset:2048
	ds_read_b128 v[186:189], v144 offset:3072
	s_add_i32 m0, s4, 0xc000
	ds_read_b128 v[190:193], v228
	ds_read_b128 v[194:197], v228 offset:1024
	ds_read_b128 v[198:201], v228 offset:2048
	ds_read_b128 v[202:205], v228 offset:3072
	ds_read_b128 v[206:209], v228 offset:4096
	ds_read_b128 v[210:213], v228 offset:5120
	ds_read_b128 v[234:237], v228 offset:6144
	ds_read_b128 v[238:241], v228 offset:7168
	global_load_lds_dwordx4 v168, s[48:49]
	s_add_i32 m0, s4, 0xe000
	s_nop 0
	global_load_lds_dwordx4 v170, s[48:49]
	s_waitcnt vmcnt(8)
	s_waitcnt lgkmcnt(0)
	s_barrier
	s_setprio 1
	s_waitcnt lgkmcnt(0)
	v_mfma_i32_16x16x64_i8 v[124:127], v[128:131], v[190:193], v[124:127]
	v_mfma_i32_16x16x64_i8 v[120:123], v[136:139], v[190:193], v[120:123]
	v_mfma_i32_16x16x64_i8 v[116:119], v[128:131], v[198:201], v[116:119]
	v_mfma_i32_16x16x64_i8 v[112:115], v[136:139], v[198:201], v[112:115]
	v_mfma_i32_16x16x64_i8 v[108:111], v[128:131], v[206:209], v[108:111]
	v_mfma_i32_16x16x64_i8 v[104:107], v[136:139], v[206:209], v[104:107]
	v_mfma_i32_16x16x64_i8 v[100:103], v[128:131], v[234:237], v[100:103]
	v_mfma_i32_16x16x64_i8 v[96:99], v[136:139], v[234:237], v[96:99]
	v_mfma_i32_16x16x64_i8 v[124:127], v[132:135], v[194:197], v[124:127]
	v_mfma_i32_16x16x64_i8 v[120:123], v[140:143], v[194:197], v[120:123]
	v_mfma_i32_16x16x64_i8 v[116:119], v[132:135], v[202:205], v[116:119]
	v_mfma_i32_16x16x64_i8 v[112:115], v[140:143], v[202:205], v[112:115]
	v_mfma_i32_16x16x64_i8 v[108:111], v[132:135], v[210:213], v[108:111]
	v_mfma_i32_16x16x64_i8 v[104:107], v[140:143], v[210:213], v[104:107]
	v_mfma_i32_16x16x64_i8 v[100:103], v[132:135], v[238:241], v[100:103]
	v_mfma_i32_16x16x64_i8 v[96:99], v[140:143], v[238:241], v[96:99]
	v_mfma_i32_16x16x64_i8 v[92:95], v[174:177], v[190:193], v[92:95]
	v_mfma_i32_16x16x64_i8 v[88:91], v[182:185], v[190:193], v[88:91]
	v_mfma_i32_16x16x64_i8 v[84:87], v[174:177], v[198:201], v[84:87]
	v_mfma_i32_16x16x64_i8 v[80:83], v[182:185], v[198:201], v[80:83]
	v_mfma_i32_16x16x64_i8 v[76:79], v[174:177], v[206:209], v[76:79]
	v_mfma_i32_16x16x64_i8 v[72:75], v[182:185], v[206:209], v[72:75]
	v_mfma_i32_16x16x64_i8 v[68:71], v[174:177], v[234:237], v[68:71]
	v_mfma_i32_16x16x64_i8 v[64:67], v[182:185], v[234:237], v[64:67]
	v_mfma_i32_16x16x64_i8 v[92:95], v[178:181], v[194:197], v[92:95]
	v_mfma_i32_16x16x64_i8 v[88:91], v[186:189], v[194:197], v[88:91]
	v_mfma_i32_16x16x64_i8 v[84:87], v[178:181], v[202:205], v[84:87]
	v_mfma_i32_16x16x64_i8 v[80:83], v[186:189], v[202:205], v[80:83]
	v_mfma_i32_16x16x64_i8 v[76:79], v[178:181], v[210:213], v[76:79]
	v_mfma_i32_16x16x64_i8 v[72:75], v[186:189], v[210:213], v[72:75]
	v_mfma_i32_16x16x64_i8 v[68:71], v[178:181], v[238:241], v[68:71]
	v_mfma_i32_16x16x64_i8 v[64:67], v[186:189], v[238:241], v[64:67]
	s_setprio 0
	s_barrier
	s_add_i32 s90, s90, s77
	s_mov_b64 s[98:99], s[66:67]
	s_mov_b32 m0, s90
	ds_read_b128 v[190:193], v228 offset:16384
	ds_read_b128 v[194:197], v228 offset:17408
	ds_read_b128 v[198:201], v228 offset:18432
	ds_read_b128 v[202:205], v228 offset:19456
	ds_read_b128 v[206:209], v228 offset:20480
	ds_read_b128 v[210:213], v228 offset:21504
	ds_read_b128 v[234:237], v228 offset:22528
	ds_read_b128 v[238:241], v228 offset:23552
	global_load_lds_dwordx4 v154, s[66:67]
	s_add_i32 m0, s90, 0x2000
	s_add_u32 s90, s66, 0x20000
	s_addc_u32 s91, s67, 0
	s_add_i32 vcc_hi, vcc_hi, s77
	global_load_lds_dwordx4 v158, s[66:67]
	s_mov_b32 m0, vcc_hi
	s_mov_b64 s[100:101], s[70:71]
	global_load_lds_dwordx4 v154, s[90:91]
	s_add_i32 m0, vcc_hi, 0x2000
	s_nop 0
	global_load_lds_dwordx4 v158, s[90:91]
	s_mov_b32 m0, s4
	s_nop 0
	global_load_lds_dwordx4 v152, s[70:71]
	s_mov_b32 m0, s5
	s_nop 0
	global_load_lds_dwordx4 v156, s[70:71]
	s_waitcnt vmcnt(8)
	s_waitcnt lgkmcnt(0)
	s_barrier
	s_setprio 1
	s_waitcnt lgkmcnt(0)
	v_mfma_i32_16x16x64_i8 v[60:63], v[128:131], v[190:193], v[60:63]
	v_mfma_i32_16x16x64_i8 v[56:59], v[136:139], v[190:193], v[56:59]
	v_mfma_i32_16x16x64_i8 v[52:55], v[128:131], v[198:201], v[52:55]
	v_mfma_i32_16x16x64_i8 v[48:51], v[136:139], v[198:201], v[48:51]
	v_mfma_i32_16x16x64_i8 v[44:47], v[128:131], v[206:209], v[44:47]
	v_mfma_i32_16x16x64_i8 v[40:43], v[136:139], v[206:209], v[40:43]
	v_mfma_i32_16x16x64_i8 v[36:39], v[128:131], v[234:237], v[36:39]
	v_mfma_i32_16x16x64_i8 v[32:35], v[136:139], v[234:237], v[32:35]
	v_mfma_i32_16x16x64_i8 v[60:63], v[132:135], v[194:197], v[60:63]
	v_mfma_i32_16x16x64_i8 v[56:59], v[140:143], v[194:197], v[56:59]
	v_mfma_i32_16x16x64_i8 v[52:55], v[132:135], v[202:205], v[52:55]
	v_mfma_i32_16x16x64_i8 v[48:51], v[140:143], v[202:205], v[48:51]
	v_mfma_i32_16x16x64_i8 v[44:47], v[132:135], v[210:213], v[44:47]
	v_mfma_i32_16x16x64_i8 v[40:43], v[140:143], v[210:213], v[40:43]
	v_mfma_i32_16x16x64_i8 v[36:39], v[132:135], v[238:241], v[36:39]
	v_mfma_i32_16x16x64_i8 v[32:35], v[140:143], v[238:241], v[32:35]
	v_mfma_i32_16x16x64_i8 v[28:31], v[174:177], v[190:193], v[28:31]
	v_mfma_i32_16x16x64_i8 v[24:27], v[182:185], v[190:193], v[24:27]
	v_mfma_i32_16x16x64_i8 v[20:23], v[174:177], v[198:201], v[20:23]
	v_mfma_i32_16x16x64_i8 v[16:19], v[182:185], v[198:201], v[16:19]
	v_mfma_i32_16x16x64_i8 v[12:15], v[174:177], v[206:209], v[12:15]
	v_mfma_i32_16x16x64_i8 v[8:11], v[182:185], v[206:209], v[8:11]
	v_mfma_i32_16x16x64_i8 v[4:7], v[174:177], v[234:237], v[4:7]
	v_mfma_i32_16x16x64_i8 v[0:3], v[182:185], v[234:237], v[0:3]
	v_mfma_i32_16x16x64_i8 v[28:31], v[178:181], v[194:197], v[28:31]
	v_mfma_i32_16x16x64_i8 v[24:27], v[186:189], v[194:197], v[24:27]
	v_mfma_i32_16x16x64_i8 v[20:23], v[178:181], v[202:205], v[20:23]
	v_mfma_i32_16x16x64_i8 v[16:19], v[186:189], v[202:205], v[16:19]
	v_mfma_i32_16x16x64_i8 v[12:15], v[178:181], v[210:213], v[12:15]
	v_mfma_i32_16x16x64_i8 v[8:11], v[186:189], v[210:213], v[8:11]
	v_mfma_i32_16x16x64_i8 v[4:7], v[178:181], v[238:241], v[4:7]
	v_mfma_i32_16x16x64_i8 v[0:3], v[186:189], v[238:241], v[0:3]
	s_setprio 0
	s_barrier
	s_add_i32 s90, 0, 0x1c000
	v_add_u32_e32 v140, s0, v225
	v_add_u32_e32 v144, s90, v225
	ds_read_b128 v[128:131], v140
	ds_read_b128 v[132:135], v140 offset:1024
	ds_read_b128 v[136:139], v140 offset:2048
	ds_read_b128 v[140:143], v140 offset:3072
	ds_read_b128 v[174:177], v144
	ds_read_b128 v[178:181], v144 offset:1024
	ds_read_b128 v[182:185], v144 offset:2048
	ds_read_b128 v[186:189], v144 offset:3072
	s_add_u32 s70, s70, 0x20000
	s_addc_u32 s71, s71, 0
	s_mov_b32 m0, s80
	ds_read_b128 v[190:193], v228 offset:32768
	ds_read_b128 v[194:197], v228 offset:33792
	ds_read_b128 v[198:201], v228 offset:34816
	ds_read_b128 v[202:205], v228 offset:35840
	ds_read_b128 v[206:209], v228 offset:36864
	ds_read_b128 v[210:213], v228 offset:37888
	ds_read_b128 v[234:237], v228 offset:38912
	ds_read_b128 v[238:241], v228 offset:39936
	global_load_lds_dwordx4 v152, s[70:71]
	v_lshl_add_u64 v[248:249], s[70:71], 0, v[156:157]
	s_mov_b32 m0, s82
	s_nop 0
	global_load_lds_dwordx4 v[248:249], off
	s_waitcnt vmcnt(8)
	s_waitcnt lgkmcnt(0)
	s_barrier
	s_setprio 1
	s_waitcnt lgkmcnt(0)
	v_mfma_i32_16x16x64_i8 v[124:127], v[128:131], v[190:193], v[124:127]
	v_mfma_i32_16x16x64_i8 v[120:123], v[136:139], v[190:193], v[120:123]
	v_mfma_i32_16x16x64_i8 v[116:119], v[128:131], v[198:201], v[116:119]
	v_mfma_i32_16x16x64_i8 v[112:115], v[136:139], v[198:201], v[112:115]
	v_mfma_i32_16x16x64_i8 v[108:111], v[128:131], v[206:209], v[108:111]
	v_mfma_i32_16x16x64_i8 v[104:107], v[136:139], v[206:209], v[104:107]
	v_mfma_i32_16x16x64_i8 v[100:103], v[128:131], v[234:237], v[100:103]
	v_mfma_i32_16x16x64_i8 v[96:99], v[136:139], v[234:237], v[96:99]
	v_mfma_i32_16x16x64_i8 v[124:127], v[132:135], v[194:197], v[124:127]
	v_mfma_i32_16x16x64_i8 v[120:123], v[140:143], v[194:197], v[120:123]
	v_mfma_i32_16x16x64_i8 v[116:119], v[132:135], v[202:205], v[116:119]
	v_mfma_i32_16x16x64_i8 v[112:115], v[140:143], v[202:205], v[112:115]
	v_mfma_i32_16x16x64_i8 v[108:111], v[132:135], v[210:213], v[108:111]
	v_mfma_i32_16x16x64_i8 v[104:107], v[140:143], v[210:213], v[104:107]
	v_mfma_i32_16x16x64_i8 v[100:103], v[132:135], v[238:241], v[100:103]
	v_mfma_i32_16x16x64_i8 v[96:99], v[140:143], v[238:241], v[96:99]
	v_mfma_i32_16x16x64_i8 v[92:95], v[174:177], v[190:193], v[92:95]
	v_mfma_i32_16x16x64_i8 v[88:91], v[182:185], v[190:193], v[88:91]
	v_mfma_i32_16x16x64_i8 v[84:87], v[174:177], v[198:201], v[84:87]
	v_mfma_i32_16x16x64_i8 v[80:83], v[182:185], v[198:201], v[80:83]
	v_mfma_i32_16x16x64_i8 v[76:79], v[174:177], v[206:209], v[76:79]
	v_mfma_i32_16x16x64_i8 v[72:75], v[182:185], v[206:209], v[72:75]
	v_mfma_i32_16x16x64_i8 v[68:71], v[174:177], v[234:237], v[68:71]
	v_mfma_i32_16x16x64_i8 v[64:67], v[182:185], v[234:237], v[64:67]
	v_mfma_i32_16x16x64_i8 v[92:95], v[178:181], v[194:197], v[92:95]
	v_mfma_i32_16x16x64_i8 v[88:91], v[186:189], v[194:197], v[88:91]
	v_mfma_i32_16x16x64_i8 v[84:87], v[178:181], v[202:205], v[84:87]
	v_mfma_i32_16x16x64_i8 v[80:83], v[186:189], v[202:205], v[80:83]
	v_mfma_i32_16x16x64_i8 v[76:79], v[178:181], v[210:213], v[76:79]
	v_mfma_i32_16x16x64_i8 v[72:75], v[186:189], v[210:213], v[72:75]
	v_mfma_i32_16x16x64_i8 v[68:71], v[178:181], v[238:241], v[68:71]
	v_mfma_i32_16x16x64_i8 v[64:67], v[186:189], v[238:241], v[64:67]
	s_setprio 0
	s_barrier
	s_add_i32 s70, s0, s77
	s_add_u32 s98, s98, s14
	s_addc_u32 s99, s99, s15
	s_mov_b32 m0, s70
	ds_read_b128 v[190:193], v228 offset:49152
	ds_read_b128 v[194:197], v228 offset:50176
	ds_read_b128 v[198:201], v228 offset:51200
	ds_read_b128 v[202:205], v228 offset:52224
	ds_read_b128 v[206:209], v228 offset:53248
	ds_read_b128 v[210:213], v228 offset:54272
	ds_read_b128 v[234:237], v228 offset:55296
	ds_read_b128 v[238:241], v228 offset:56320
	global_load_lds_dwordx4 v154, s[98:99]
	s_add_i32 m0, s70, 0x2000
	s_add_u32 s66, s66, 0x20080
	s_addc_u32 s67, s67, 0
	s_add_i32 s70, s90, s77
	global_load_lds_dwordx4 v158, s[98:99]
	s_mov_b32 m0, s70
	s_nop 0
	global_load_lds_dwordx4 v154, s[66:67]
	s_add_i32 m0, s70, 0x2000
	s_nop 0
	global_load_lds_dwordx4 v158, s[66:67]
	s_add_u32 s100, s100, s14
	s_addc_u32 s101, s101, s15
	s_mov_b32 m0, s84
	s_nop 0
	global_load_lds_dwordx4 v152, s[100:101]
	s_mov_b32 m0, s74
	s_nop 0
	global_load_lds_dwordx4 v156, s[100:101]
	s_waitcnt vmcnt(8)
	s_waitcnt lgkmcnt(0)
	s_barrier
	s_setprio 1
	s_waitcnt lgkmcnt(0)
	v_mfma_i32_16x16x64_i8 v[60:63], v[128:131], v[190:193], v[60:63]
	v_mfma_i32_16x16x64_i8 v[56:59], v[136:139], v[190:193], v[56:59]
	v_mfma_i32_16x16x64_i8 v[52:55], v[128:131], v[198:201], v[52:55]
	v_mfma_i32_16x16x64_i8 v[48:51], v[136:139], v[198:201], v[48:51]
	v_mfma_i32_16x16x64_i8 v[44:47], v[128:131], v[206:209], v[44:47]
	v_mfma_i32_16x16x64_i8 v[40:43], v[136:139], v[206:209], v[40:43]
	v_mfma_i32_16x16x64_i8 v[36:39], v[128:131], v[234:237], v[36:39]
	v_mfma_i32_16x16x64_i8 v[32:35], v[136:139], v[234:237], v[32:35]
	v_mfma_i32_16x16x64_i8 v[60:63], v[132:135], v[194:197], v[60:63]
	v_mfma_i32_16x16x64_i8 v[56:59], v[140:143], v[194:197], v[56:59]
	v_mfma_i32_16x16x64_i8 v[52:55], v[132:135], v[202:205], v[52:55]
	v_mfma_i32_16x16x64_i8 v[48:51], v[140:143], v[202:205], v[48:51]
	v_mfma_i32_16x16x64_i8 v[44:47], v[132:135], v[210:213], v[44:47]
	v_mfma_i32_16x16x64_i8 v[40:43], v[140:143], v[210:213], v[40:43]
	v_mfma_i32_16x16x64_i8 v[36:39], v[132:135], v[238:241], v[36:39]
	v_mfma_i32_16x16x64_i8 v[32:35], v[140:143], v[238:241], v[32:35]
	v_mfma_i32_16x16x64_i8 v[28:31], v[174:177], v[190:193], v[28:31]
	v_mfma_i32_16x16x64_i8 v[24:27], v[182:185], v[190:193], v[24:27]
	v_mfma_i32_16x16x64_i8 v[20:23], v[174:177], v[198:201], v[20:23]
	v_mfma_i32_16x16x64_i8 v[16:19], v[182:185], v[198:201], v[16:19]
	v_mfma_i32_16x16x64_i8 v[12:15], v[174:177], v[206:209], v[12:15]
	v_mfma_i32_16x16x64_i8 v[8:11], v[182:185], v[206:209], v[8:11]
	v_mfma_i32_16x16x64_i8 v[4:7], v[174:177], v[234:237], v[4:7]
	v_mfma_i32_16x16x64_i8 v[0:3], v[182:185], v[234:237], v[0:3]
	v_mfma_i32_16x16x64_i8 v[28:31], v[178:181], v[194:197], v[28:31]
	v_mfma_i32_16x16x64_i8 v[24:27], v[186:189], v[194:197], v[24:27]
	v_mfma_i32_16x16x64_i8 v[20:23], v[178:181], v[202:205], v[20:23]
	v_mfma_i32_16x16x64_i8 v[16:19], v[186:189], v[202:205], v[16:19]
	v_mfma_i32_16x16x64_i8 v[12:15], v[178:181], v[210:213], v[12:15]
	v_mfma_i32_16x16x64_i8 v[8:11], v[186:189], v[210:213], v[8:11]
	v_mfma_i32_16x16x64_i8 v[4:7], v[178:181], v[238:241], v[4:7]
	v_mfma_i32_16x16x64_i8 v[0:3], v[186:189], v[238:241], v[0:3]
	s_setprio 0
	s_barrier
	s_add_i32 vcc_lo, vcc_lo, 2
	s_add_u32 s48, s48, 0x100
	s_addc_u32 s49, s49, 0
	s_add_u32 s73, s73, 0x100
	s_addc_u32 s83, s83, 0
	s_cmp_gt_u32 vcc_lo, 5
	s_cbranch_scc0 .LBB0_479
	s_and_b64 vcc, exec, s[56:57]
	s_cbranch_vccz .LBB0_482
	s_barrier

.LBB0_925:
	s_add_u32 s58, s56, 0xfffe0080
	s_addc_u32 s59, s57, -1
	s_add_i32 s83, 0, 0x10000
	s_cmp_eq_u32 s82, 4
	s_cselect_b32 s61, s51, s59
	s_cselect_b32 s60, s79, s58
	s_cselect_b32 s59, s43, s81
	s_cselect_b32 s58, s45, s80
	s_add_i32 s86, 0, 0x14000
	v_add_u32_e32 v150, s83, v182
	v_add_u32_e32 v154, s86, v182
	ds_read_b128 v[138:141], v150
	ds_read_b128 v[142:145], v150 offset:1024
	ds_read_b128 v[146:149], v150 offset:2048
	ds_read_b128 v[150:153], v150 offset:3072
	ds_read_b128 v[166:169], v154
	ds_read_b128 v[190:193], v154 offset:1024
	ds_read_b128 v[194:197], v154 offset:2048
	ds_read_b128 v[198:201], v154 offset:3072
	s_add_i32 m0, s12, 0xc000
	ds_read_b128 v[202:205], v185
	ds_read_b128 v[206:209], v185 offset:1024
	ds_read_b128 v[210:213], v185 offset:2048
	ds_read_b128 v[214:217], v185 offset:3072
	ds_read_b128 v[218:221], v185 offset:4096
	ds_read_b128 v[222:225], v185 offset:5120
	ds_read_b128 v[226:229], v185 offset:6144
	ds_read_b128 v[234:237], v185 offset:7168
	global_load_lds_dwordx4 v134, s[56:57]
	s_add_i32 m0, s12, 0xe000
	s_nop 0
	global_load_lds_dwordx4 v136, s[56:57]
	s_waitcnt vmcnt(8)
	s_waitcnt lgkmcnt(0)
	s_barrier
	s_setprio 1
	s_waitcnt lgkmcnt(0)
	v_mfma_i32_16x16x64_i8 v[126:129], v[138:141], v[202:205], v[126:129]
	v_mfma_i32_16x16x64_i8 v[122:125], v[146:149], v[202:205], v[122:125]
	v_mfma_i32_16x16x64_i8 v[110:113], v[138:141], v[210:213], v[110:113]
	v_mfma_i32_16x16x64_i8 v[106:109], v[146:149], v[210:213], v[106:109]
	v_mfma_i32_16x16x64_i8 v[94:97], v[138:141], v[218:221], v[94:97]
	v_mfma_i32_16x16x64_i8 v[90:93], v[146:149], v[218:221], v[90:93]
	v_mfma_i32_16x16x64_i8 v[78:81], v[138:141], v[226:229], v[78:81]
	v_mfma_i32_16x16x64_i8 v[74:77], v[146:149], v[226:229], v[74:77]
	v_mfma_i32_16x16x64_i8 v[126:129], v[142:145], v[206:209], v[126:129]
	v_mfma_i32_16x16x64_i8 v[122:125], v[150:153], v[206:209], v[122:125]
	v_mfma_i32_16x16x64_i8 v[110:113], v[142:145], v[214:217], v[110:113]
	v_mfma_i32_16x16x64_i8 v[106:109], v[150:153], v[214:217], v[106:109]
	v_mfma_i32_16x16x64_i8 v[94:97], v[142:145], v[222:225], v[94:97]
	v_mfma_i32_16x16x64_i8 v[90:93], v[150:153], v[222:225], v[90:93]
	v_mfma_i32_16x16x64_i8 v[78:81], v[142:145], v[234:237], v[78:81]
	v_mfma_i32_16x16x64_i8 v[74:77], v[150:153], v[234:237], v[74:77]
	v_mfma_i32_16x16x64_i8 v[118:121], v[166:169], v[202:205], v[118:121]
	v_mfma_i32_16x16x64_i8 v[114:117], v[194:197], v[202:205], v[114:117]
	v_mfma_i32_16x16x64_i8 v[102:105], v[166:169], v[210:213], v[102:105]
	v_mfma_i32_16x16x64_i8 v[98:101], v[194:197], v[210:213], v[98:101]
	v_mfma_i32_16x16x64_i8 v[86:89], v[166:169], v[218:221], v[86:89]
	v_mfma_i32_16x16x64_i8 v[82:85], v[194:197], v[218:221], v[82:85]
	v_mfma_i32_16x16x64_i8 v[70:73], v[166:169], v[226:229], v[70:73]
	v_mfma_i32_16x16x64_i8 v[66:69], v[194:197], v[226:229], v[66:69]
	v_mfma_i32_16x16x64_i8 v[118:121], v[190:193], v[206:209], v[118:121]
	v_mfma_i32_16x16x64_i8 v[114:117], v[198:201], v[206:209], v[114:117]
	v_mfma_i32_16x16x64_i8 v[102:105], v[190:193], v[214:217], v[102:105]
	v_mfma_i32_16x16x64_i8 v[98:101], v[198:201], v[214:217], v[98:101]
	v_mfma_i32_16x16x64_i8 v[86:89], v[190:193], v[222:225], v[86:89]
	v_mfma_i32_16x16x64_i8 v[82:85], v[198:201], v[222:225], v[82:85]
	v_mfma_i32_16x16x64_i8 v[70:73], v[190:193], v[234:237], v[70:73]
	v_mfma_i32_16x16x64_i8 v[66:69], v[198:201], v[234:237], v[66:69]
	s_setprio 0
	s_barrier
	s_add_i32 s83, s83, s69
	s_mov_b64 s[98:99], s[58:59]
	s_mov_b32 m0, s83
	ds_read_b128 v[202:205], v185 offset:16384
	ds_read_b128 v[206:209], v185 offset:17408
	ds_read_b128 v[210:213], v185 offset:18432
	ds_read_b128 v[214:217], v185 offset:19456
	ds_read_b128 v[218:221], v185 offset:20480
	ds_read_b128 v[222:225], v185 offset:21504
	ds_read_b128 v[226:229], v185 offset:22528
	ds_read_b128 v[234:237], v185 offset:23552
	global_load_lds_dwordx4 v0, s[58:59]
	s_add_i32 m0, s83, 0x2000
	s_add_u32 s84, s58, 0x20000
	s_addc_u32 s85, s59, 0
	s_add_i32 s83, s86, s69
	global_load_lds_dwordx4 v164, s[58:59]
	s_mov_b32 m0, s83
	s_mov_b64 s[100:101], s[60:61]
	global_load_lds_dwordx4 v0, s[84:85]
	s_add_i32 m0, s83, 0x2000
	s_nop 0
	global_load_lds_dwordx4 v164, s[84:85]
	s_mov_b32 m0, s12
	s_nop 0
	global_load_lds_dwordx4 v160, s[60:61]
	s_mov_b32 m0, s49
	s_nop 0
	global_load_lds_dwordx4 v162, s[60:61]
	s_waitcnt vmcnt(8)
	s_waitcnt lgkmcnt(0)
	s_barrier
	s_setprio 1
	s_waitcnt lgkmcnt(0)
	v_mfma_i32_16x16x64_i8 v[62:65], v[138:141], v[202:205], v[62:65]
	v_mfma_i32_16x16x64_i8 v[58:61], v[146:149], v[202:205], v[58:61]
	v_mfma_i32_16x16x64_i8 v[46:49], v[138:141], v[210:213], v[46:49]
	v_mfma_i32_16x16x64_i8 v[42:45], v[146:149], v[210:213], v[42:45]
	v_mfma_i32_16x16x64_i8 v[30:33], v[138:141], v[218:221], v[30:33]
	v_mfma_i32_16x16x64_i8 v[26:29], v[146:149], v[218:221], v[26:29]
	v_mfma_i32_16x16x64_i8 v[10:13], v[138:141], v[226:229], v[10:13]
	v_mfma_i32_16x16x64_i8 v[2:5], v[146:149], v[226:229], v[2:5]
	v_mfma_i32_16x16x64_i8 v[62:65], v[142:145], v[206:209], v[62:65]
	v_mfma_i32_16x16x64_i8 v[58:61], v[150:153], v[206:209], v[58:61]
	v_mfma_i32_16x16x64_i8 v[46:49], v[142:145], v[214:217], v[46:49]
	v_mfma_i32_16x16x64_i8 v[42:45], v[150:153], v[214:217], v[42:45]
	v_mfma_i32_16x16x64_i8 v[30:33], v[142:145], v[222:225], v[30:33]
	v_mfma_i32_16x16x64_i8 v[26:29], v[150:153], v[222:225], v[26:29]
	v_mfma_i32_16x16x64_i8 v[10:13], v[142:145], v[234:237], v[10:13]
	v_mfma_i32_16x16x64_i8 v[2:5], v[150:153], v[234:237], v[2:5]
	v_mfma_i32_16x16x64_i8 v[54:57], v[166:169], v[202:205], v[54:57]
	v_mfma_i32_16x16x64_i8 v[50:53], v[194:197], v[202:205], v[50:53]
	v_mfma_i32_16x16x64_i8 v[38:41], v[166:169], v[210:213], v[38:41]
	v_mfma_i32_16x16x64_i8 v[34:37], v[194:197], v[210:213], v[34:37]
	v_mfma_i32_16x16x64_i8 v[22:25], v[166:169], v[218:221], v[22:25]
	v_mfma_i32_16x16x64_i8 v[18:21], v[194:197], v[218:221], v[18:21]
	v_mfma_i32_16x16x64_i8 v[14:17], v[166:169], v[226:229], v[14:17]
	v_mfma_i32_16x16x64_i8 v[6:9], v[194:197], v[226:229], v[6:9]
	v_mfma_i32_16x16x64_i8 v[54:57], v[190:193], v[206:209], v[54:57]
	v_mfma_i32_16x16x64_i8 v[50:53], v[198:201], v[206:209], v[50:53]
	v_mfma_i32_16x16x64_i8 v[38:41], v[190:193], v[214:217], v[38:41]
	v_mfma_i32_16x16x64_i8 v[34:37], v[198:201], v[214:217], v[34:37]
	v_mfma_i32_16x16x64_i8 v[22:25], v[190:193], v[222:225], v[22:25]
	v_mfma_i32_16x16x64_i8 v[18:21], v[198:201], v[222:225], v[18:21]
	v_mfma_i32_16x16x64_i8 v[14:17], v[190:193], v[234:237], v[14:17]
	v_mfma_i32_16x16x64_i8 v[6:9], v[198:201], v[234:237], v[6:9]
	s_setprio 0
	s_barrier
	s_add_i32 s83, 0, 0x18000
	s_add_i32 s84, 0, 0x1c000
	v_add_u32_e32 v150, s83, v182
	v_add_u32_e32 v189, s84, v182
	ds_read_b128 v[138:141], v150
	ds_read_b128 v[142:145], v150 offset:1024
	ds_read_b128 v[146:149], v150 offset:2048
	ds_read_b128 v[150:153], v150 offset:3072
	ds_read_b128 v[166:169], v189
	ds_read_b128 v[190:193], v189 offset:1024
	ds_read_b128 v[194:197], v189 offset:2048
	ds_read_b128 v[198:201], v189 offset:3072
	s_add_u32 s60, s60, 0x20000
	s_addc_u32 s61, s61, 0
	s_mov_b32 m0, s70
	ds_read_b128 v[202:205], v185 offset:32768
	ds_read_b128 v[206:209], v185 offset:33792
	ds_read_b128 v[210:213], v185 offset:34816
	ds_read_b128 v[214:217], v185 offset:35840
	ds_read_b128 v[218:221], v185 offset:36864
	ds_read_b128 v[222:225], v185 offset:37888
	ds_read_b128 v[226:229], v185 offset:38912
	ds_read_b128 v[234:237], v185 offset:39936
	global_load_lds_dwordx4 v160, s[60:61]
	s_mov_b32 m0, s71
	s_nop 0
	global_load_lds_dwordx4 v162, s[60:61]
	s_waitcnt vmcnt(8)
	s_waitcnt lgkmcnt(0)
	s_barrier
	s_setprio 1
	s_waitcnt lgkmcnt(0)
	v_mfma_i32_16x16x64_i8 v[126:129], v[138:141], v[202:205], v[126:129]
	v_mfma_i32_16x16x64_i8 v[122:125], v[146:149], v[202:205], v[122:125]
	v_mfma_i32_16x16x64_i8 v[110:113], v[138:141], v[210:213], v[110:113]
	v_mfma_i32_16x16x64_i8 v[106:109], v[146:149], v[210:213], v[106:109]
	v_mfma_i32_16x16x64_i8 v[94:97], v[138:141], v[218:221], v[94:97]
	v_mfma_i32_16x16x64_i8 v[90:93], v[146:149], v[218:221], v[90:93]
	v_mfma_i32_16x16x64_i8 v[78:81], v[138:141], v[226:229], v[78:81]
	v_mfma_i32_16x16x64_i8 v[74:77], v[146:149], v[226:229], v[74:77]
	v_mfma_i32_16x16x64_i8 v[126:129], v[142:145], v[206:209], v[126:129]
	v_mfma_i32_16x16x64_i8 v[122:125], v[150:153], v[206:209], v[122:125]
	v_mfma_i32_16x16x64_i8 v[110:113], v[142:145], v[214:217], v[110:113]
	v_mfma_i32_16x16x64_i8 v[106:109], v[150:153], v[214:217], v[106:109]
	v_mfma_i32_16x16x64_i8 v[94:97], v[142:145], v[222:225], v[94:97]
	v_mfma_i32_16x16x64_i8 v[90:93], v[150:153], v[222:225], v[90:93]
	v_mfma_i32_16x16x64_i8 v[78:81], v[142:145], v[234:237], v[78:81]
	v_mfma_i32_16x16x64_i8 v[74:77], v[150:153], v[234:237], v[74:77]
	v_mfma_i32_16x16x64_i8 v[118:121], v[166:169], v[202:205], v[118:121]
	v_mfma_i32_16x16x64_i8 v[114:117], v[194:197], v[202:205], v[114:117]
	v_mfma_i32_16x16x64_i8 v[102:105], v[166:169], v[210:213], v[102:105]
	v_mfma_i32_16x16x64_i8 v[98:101], v[194:197], v[210:213], v[98:101]
	v_mfma_i32_16x16x64_i8 v[86:89], v[166:169], v[218:221], v[86:89]
	v_mfma_i32_16x16x64_i8 v[82:85], v[194:197], v[218:221], v[82:85]
	v_mfma_i32_16x16x64_i8 v[70:73], v[166:169], v[226:229], v[70:73]
	v_mfma_i32_16x16x64_i8 v[66:69], v[194:197], v[226:229], v[66:69]
	v_mfma_i32_16x16x64_i8 v[118:121], v[190:193], v[206:209], v[118:121]
	v_mfma_i32_16x16x64_i8 v[114:117], v[198:201], v[206:209], v[114:117]
	v_mfma_i32_16x16x64_i8 v[102:105], v[190:193], v[214:217], v[102:105]
	v_mfma_i32_16x16x64_i8 v[98:101], v[198:201], v[214:217], v[98:101]
	v_mfma_i32_16x16x64_i8 v[86:89], v[190:193], v[222:225], v[86:89]
	v_mfma_i32_16x16x64_i8 v[82:85], v[198:201], v[222:225], v[82:85]
	v_mfma_i32_16x16x64_i8 v[70:73], v[190:193], v[234:237], v[70:73]
	v_mfma_i32_16x16x64_i8 v[66:69], v[198:201], v[234:237], v[66:69]
	s_setprio 0
	s_barrier
	s_add_i32 s60, s83, s69
	s_add_u32 s98, s98, s14
	s_addc_u32 s99, s99, s15
	s_mov_b32 m0, s60
	ds_read_b128 v[202:205], v185 offset:49152
	ds_read_b128 v[206:209], v185 offset:50176
	ds_read_b128 v[210:213], v185 offset:51200
	ds_read_b128 v[214:217], v185 offset:52224
	ds_read_b128 v[218:221], v185 offset:53248
	ds_read_b128 v[222:225], v185 offset:54272
	ds_read_b128 v[226:229], v185 offset:55296
	ds_read_b128 v[234:237], v185 offset:56320
	global_load_lds_dwordx4 v0, s[98:99]
	s_add_i32 m0, s60, 0x2000
	s_add_u32 s58, s58, 0x20080
	s_addc_u32 s59, s59, 0
	s_add_i32 s60, s84, s69
	global_load_lds_dwordx4 v164, s[98:99]
	s_mov_b32 m0, s60
	s_nop 0
	global_load_lds_dwordx4 v0, s[58:59]
	s_add_i32 m0, s60, 0x2000
	s_nop 0
	global_load_lds_dwordx4 v164, s[58:59]
	s_add_u32 s100, s100, s14
	s_addc_u32 s101, s101, s15
	s_mov_b32 m0, s72
	s_nop 0
	global_load_lds_dwordx4 v160, s[100:101]
	s_mov_b32 m0, s73
	s_nop 0
	global_load_lds_dwordx4 v162, s[100:101]
	s_waitcnt vmcnt(8)
	s_waitcnt lgkmcnt(0)
	s_barrier
	s_setprio 1
	s_waitcnt lgkmcnt(0)
	v_mfma_i32_16x16x64_i8 v[62:65], v[138:141], v[202:205], v[62:65]
	v_mfma_i32_16x16x64_i8 v[58:61], v[146:149], v[202:205], v[58:61]
	v_mfma_i32_16x16x64_i8 v[46:49], v[138:141], v[210:213], v[46:49]
	v_mfma_i32_16x16x64_i8 v[42:45], v[146:149], v[210:213], v[42:45]
	v_mfma_i32_16x16x64_i8 v[30:33], v[138:141], v[218:221], v[30:33]
	v_mfma_i32_16x16x64_i8 v[26:29], v[146:149], v[218:221], v[26:29]
	v_mfma_i32_16x16x64_i8 v[10:13], v[138:141], v[226:229], v[10:13]
	v_mfma_i32_16x16x64_i8 v[2:5], v[146:149], v[226:229], v[2:5]
	v_mfma_i32_16x16x64_i8 v[62:65], v[142:145], v[206:209], v[62:65]
	v_mfma_i32_16x16x64_i8 v[58:61], v[150:153], v[206:209], v[58:61]
	v_mfma_i32_16x16x64_i8 v[46:49], v[142:145], v[214:217], v[46:49]
	v_mfma_i32_16x16x64_i8 v[42:45], v[150:153], v[214:217], v[42:45]
	v_mfma_i32_16x16x64_i8 v[30:33], v[142:145], v[222:225], v[30:33]
	v_mfma_i32_16x16x64_i8 v[26:29], v[150:153], v[222:225], v[26:29]
	v_mfma_i32_16x16x64_i8 v[10:13], v[142:145], v[234:237], v[10:13]
	v_mfma_i32_16x16x64_i8 v[2:5], v[150:153], v[234:237], v[2:5]
	v_mfma_i32_16x16x64_i8 v[54:57], v[166:169], v[202:205], v[54:57]
	v_mfma_i32_16x16x64_i8 v[50:53], v[194:197], v[202:205], v[50:53]
	v_mfma_i32_16x16x64_i8 v[38:41], v[166:169], v[210:213], v[38:41]
	v_mfma_i32_16x16x64_i8 v[34:37], v[194:197], v[210:213], v[34:37]
	v_mfma_i32_16x16x64_i8 v[22:25], v[166:169], v[218:221], v[22:25]
	v_mfma_i32_16x16x64_i8 v[18:21], v[194:197], v[218:221], v[18:21]
	v_mfma_i32_16x16x64_i8 v[14:17], v[166:169], v[226:229], v[14:17]
	v_mfma_i32_16x16x64_i8 v[6:9], v[194:197], v[226:229], v[6:9]
	v_mfma_i32_16x16x64_i8 v[54:57], v[190:193], v[206:209], v[54:57]
	v_mfma_i32_16x16x64_i8 v[50:53], v[198:201], v[206:209], v[50:53]
	v_mfma_i32_16x16x64_i8 v[38:41], v[190:193], v[214:217], v[38:41]
	v_mfma_i32_16x16x64_i8 v[34:37], v[198:201], v[214:217], v[34:37]
	v_mfma_i32_16x16x64_i8 v[22:25], v[190:193], v[222:225], v[22:25]
	v_mfma_i32_16x16x64_i8 v[18:21], v[198:201], v[222:225], v[18:21]
	v_mfma_i32_16x16x64_i8 v[14:17], v[190:193], v[234:237], v[14:17]
	v_mfma_i32_16x16x64_i8 v[6:9], v[198:201], v[234:237], v[6:9]
	s_setprio 0
	s_barrier
	s_add_i32 s82, s82, 2
	s_add_u32 s56, s56, 0x100
	s_addc_u32 s57, s57, 0
	s_add_u32 s80, s80, 0x100
	s_addc_u32 s81, s81, 0
	s_cmp_gt_u32 s82, 5
	s_cbranch_scc0 .LBB0_925
	s_and_b64 vcc, exec, s[40:41]
	s_cbranch_vccz .LBB0_928
	s_barrier

.LBB0_955:
	s_add_u32 s8, s6, 0xfffe0080
	s_addc_u32 s9, s7, -1
	s_add_i32 s70, 0, 0x10000
	s_cmp_eq_u32 s69, 4
	s_cselect_b32 s55, s43, s9
	s_cselect_b32 s54, s49, s8
	v_add_u32_e32 v0, s70, v188
	s_cselect_b32 s9, s39, s68
	s_cselect_b32 s8, s41, s67
	s_add_i32 s72, 0, 0x14000
	ds_read_b128 v[132:135], v0
	ds_read_b128 v[136:139], v0 offset:1024
	ds_read_b128 v[140:143], v0 offset:2048
	ds_read_b128 v[144:147], v0 offset:3072
	v_add_u32_e32 v0, s72, v188
	ds_read_b128 v[148:151], v0
	ds_read_b128 v[152:155], v0 offset:1024
	ds_read_b128 v[176:179], v0 offset:2048
	ds_read_b128 v[180:183], v0 offset:3072
	s_add_i32 m0, s45, 0xc000
	ds_read_b128 v[198:201], v196
	ds_read_b128 v[202:205], v196 offset:1024
	ds_read_b128 v[206:209], v196 offset:2048
	ds_read_b128 v[210:213], v196 offset:3072
	ds_read_b128 v[214:217], v196 offset:4096
	ds_read_b128 v[218:221], v196 offset:5120
	ds_read_b128 v[222:225], v196 offset:6144
	ds_read_b128 v[226:229], v196 offset:7168
	global_load_lds_dwordx4 v172, s[6:7]
	s_add_i32 m0, s45, 0xe000
	s_nop 0
	global_load_lds_dwordx4 v174, s[6:7]
	s_waitcnt vmcnt(8)
	s_waitcnt lgkmcnt(0)
	s_barrier
	s_setprio 1
	s_waitcnt lgkmcnt(0)
	v_mfma_f32_16x16x32_bf16 v[128:131], v[132:135], v[198:201], v[128:131]
	v_mfma_f32_16x16x32_bf16 v[124:127], v[140:143], v[198:201], v[124:127]
	v_mfma_f32_16x16x32_bf16 v[120:123], v[132:135], v[206:209], v[120:123]
	v_mfma_f32_16x16x32_bf16 v[116:119], v[140:143], v[206:209], v[116:119]
	v_mfma_f32_16x16x32_bf16 v[112:115], v[132:135], v[214:217], v[112:115]
	v_mfma_f32_16x16x32_bf16 v[108:111], v[140:143], v[214:217], v[108:111]
	v_mfma_f32_16x16x32_bf16 v[104:107], v[132:135], v[222:225], v[104:107]
	v_mfma_f32_16x16x32_bf16 v[100:103], v[140:143], v[222:225], v[100:103]
	v_mfma_f32_16x16x32_bf16 v[128:131], v[136:139], v[202:205], v[128:131]
	v_mfma_f32_16x16x32_bf16 v[124:127], v[144:147], v[202:205], v[124:127]
	v_mfma_f32_16x16x32_bf16 v[120:123], v[136:139], v[210:213], v[120:123]
	v_mfma_f32_16x16x32_bf16 v[116:119], v[144:147], v[210:213], v[116:119]
	v_mfma_f32_16x16x32_bf16 v[112:115], v[136:139], v[218:221], v[112:115]
	v_mfma_f32_16x16x32_bf16 v[108:111], v[144:147], v[218:221], v[108:111]
	v_mfma_f32_16x16x32_bf16 v[104:107], v[136:139], v[226:229], v[104:107]
	v_mfma_f32_16x16x32_bf16 v[100:103], v[144:147], v[226:229], v[100:103]
	v_mfma_f32_16x16x32_bf16 v[96:99], v[148:151], v[198:201], v[96:99]
	v_mfma_f32_16x16x32_bf16 v[92:95], v[176:179], v[198:201], v[92:95]
	v_mfma_f32_16x16x32_bf16 v[88:91], v[148:151], v[206:209], v[88:91]
	v_mfma_f32_16x16x32_bf16 v[84:87], v[176:179], v[206:209], v[84:87]
	v_mfma_f32_16x16x32_bf16 v[80:83], v[148:151], v[214:217], v[80:83]
	v_mfma_f32_16x16x32_bf16 v[76:79], v[176:179], v[214:217], v[76:79]
	v_mfma_f32_16x16x32_bf16 v[72:75], v[148:151], v[222:225], v[72:75]
	v_mfma_f32_16x16x32_bf16 v[68:71], v[176:179], v[222:225], v[68:71]
	v_mfma_f32_16x16x32_bf16 v[96:99], v[152:155], v[202:205], v[96:99]
	v_mfma_f32_16x16x32_bf16 v[92:95], v[180:183], v[202:205], v[92:95]
	v_mfma_f32_16x16x32_bf16 v[88:91], v[152:155], v[210:213], v[88:91]
	v_mfma_f32_16x16x32_bf16 v[84:87], v[180:183], v[210:213], v[84:87]
	v_mfma_f32_16x16x32_bf16 v[80:83], v[152:155], v[218:221], v[80:83]
	v_mfma_f32_16x16x32_bf16 v[76:79], v[180:183], v[218:221], v[76:79]
	v_mfma_f32_16x16x32_bf16 v[72:75], v[152:155], v[226:229], v[72:75]
	v_mfma_f32_16x16x32_bf16 v[68:71], v[180:183], v[226:229], v[68:71]
	s_setprio 0
	s_barrier
	s_add_i32 s70, s70, s58
	s_mov_b64 s[98:99], s[8:9]
	s_mov_b32 m0, s70
	ds_read_b128 v[198:201], v196 offset:16384
	ds_read_b128 v[202:205], v196 offset:17408
	ds_read_b128 v[206:209], v196 offset:18432
	ds_read_b128 v[210:213], v196 offset:19456
	ds_read_b128 v[214:217], v196 offset:20480
	ds_read_b128 v[218:221], v196 offset:21504
	ds_read_b128 v[222:225], v196 offset:22528
	ds_read_b128 v[226:229], v196 offset:23552
	global_load_lds_dwordx4 v166, s[8:9]
	s_add_i32 m0, s70, 0x2000
	s_add_u32 s70, s8, 0x20000
	s_addc_u32 s71, s9, 0
	s_add_i32 s72, s72, s58
	global_load_lds_dwordx4 v164, s[8:9]
	s_mov_b32 m0, s72
	s_mov_b64 s[100:101], s[54:55]
	global_load_lds_dwordx4 v166, s[70:71]
	s_add_i32 m0, s72, 0x2000
	s_nop 0
	global_load_lds_dwordx4 v164, s[70:71]
	s_mov_b32 m0, s45
	s_nop 0
	global_load_lds_dwordx4 v160, s[54:55]
	s_mov_b32 m0, s59
	s_nop 0
	global_load_lds_dwordx4 v162, s[54:55]
	s_waitcnt vmcnt(8)
	s_waitcnt lgkmcnt(0)
	s_barrier
	s_setprio 1
	s_waitcnt lgkmcnt(0)
	v_mfma_f32_16x16x32_bf16 v[64:67], v[132:135], v[198:201], v[64:67]
	v_mfma_f32_16x16x32_bf16 v[60:63], v[140:143], v[198:201], v[60:63]
	v_mfma_f32_16x16x32_bf16 v[56:59], v[132:135], v[206:209], v[56:59]
	v_mfma_f32_16x16x32_bf16 v[52:55], v[140:143], v[206:209], v[52:55]
	v_mfma_f32_16x16x32_bf16 v[48:51], v[132:135], v[214:217], v[48:51]
	v_mfma_f32_16x16x32_bf16 v[44:47], v[140:143], v[214:217], v[44:47]
	v_mfma_f32_16x16x32_bf16 v[40:43], v[132:135], v[222:225], v[40:43]
	v_mfma_f32_16x16x32_bf16 v[36:39], v[140:143], v[222:225], v[36:39]
	v_mfma_f32_16x16x32_bf16 v[64:67], v[136:139], v[202:205], v[64:67]
	v_mfma_f32_16x16x32_bf16 v[60:63], v[144:147], v[202:205], v[60:63]
	v_mfma_f32_16x16x32_bf16 v[56:59], v[136:139], v[210:213], v[56:59]
	v_mfma_f32_16x16x32_bf16 v[52:55], v[144:147], v[210:213], v[52:55]
	v_mfma_f32_16x16x32_bf16 v[48:51], v[136:139], v[218:221], v[48:51]
	v_mfma_f32_16x16x32_bf16 v[44:47], v[144:147], v[218:221], v[44:47]
	v_mfma_f32_16x16x32_bf16 v[40:43], v[136:139], v[226:229], v[40:43]
	v_mfma_f32_16x16x32_bf16 v[36:39], v[144:147], v[226:229], v[36:39]
	v_mfma_f32_16x16x32_bf16 v[32:35], v[148:151], v[198:201], v[32:35]
	v_mfma_f32_16x16x32_bf16 v[28:31], v[176:179], v[198:201], v[28:31]
	v_mfma_f32_16x16x32_bf16 v[24:27], v[148:151], v[206:209], v[24:27]
	v_mfma_f32_16x16x32_bf16 v[20:23], v[176:179], v[206:209], v[20:23]
	v_mfma_f32_16x16x32_bf16 v[16:19], v[148:151], v[214:217], v[16:19]
	v_mfma_f32_16x16x32_bf16 v[12:15], v[176:179], v[214:217], v[12:15]
	v_mfma_f32_16x16x32_bf16 v[8:11], v[148:151], v[222:225], v[8:11]
	v_mfma_f32_16x16x32_bf16 v[2:5], v[176:179], v[222:225], v[4:7]
	v_mfma_f32_16x16x32_bf16 v[32:35], v[152:155], v[202:205], v[32:35]
	v_mfma_f32_16x16x32_bf16 v[28:31], v[180:183], v[202:205], v[28:31]
	v_mfma_f32_16x16x32_bf16 v[24:27], v[152:155], v[210:213], v[24:27]
	v_mfma_f32_16x16x32_bf16 v[20:23], v[180:183], v[210:213], v[20:23]
	v_mfma_f32_16x16x32_bf16 v[16:19], v[152:155], v[218:221], v[16:19]
	v_mfma_f32_16x16x32_bf16 v[12:15], v[180:183], v[218:221], v[12:15]
	v_mfma_f32_16x16x32_bf16 v[8:11], v[152:155], v[226:229], v[8:11]
	v_mfma_f32_16x16x32_bf16 v[2:5], v[180:183], v[226:229], v[2:5]
	s_setprio 0
	s_barrier
	s_add_i32 s70, 0, 0x18000
	v_add_u32_e32 v0, s70, v188
	s_add_i32 s71, 0, 0x1c000
	ds_read_b128 v[132:135], v0
	ds_read_b128 v[136:139], v0 offset:1024
	ds_read_b128 v[140:143], v0 offset:2048
	ds_read_b128 v[144:147], v0 offset:3072
	v_add_u32_e32 v0, s71, v188
	ds_read_b128 v[148:151], v0
	ds_read_b128 v[152:155], v0 offset:1024
	ds_read_b128 v[176:179], v0 offset:2048
	ds_read_b128 v[180:183], v0 offset:3072
	s_add_u32 s54, s54, 0x20000
	s_addc_u32 s55, s55, 0
	s_mov_b32 m0, s60
	ds_read_b128 v[198:201], v196 offset:32768
	ds_read_b128 v[202:205], v196 offset:33792
	ds_read_b128 v[206:209], v196 offset:34816
	ds_read_b128 v[210:213], v196 offset:35840
	ds_read_b128 v[214:217], v196 offset:36864
	ds_read_b128 v[218:221], v196 offset:37888
	ds_read_b128 v[222:225], v196 offset:38912
	ds_read_b128 v[226:229], v196 offset:39936
	global_load_lds_dwordx4 v160, s[54:55]
	s_mov_b32 m0, s61
	s_nop 0
	global_load_lds_dwordx4 v162, s[54:55]
	s_waitcnt vmcnt(8)
	s_waitcnt lgkmcnt(0)
	s_barrier
	s_setprio 1
	s_waitcnt lgkmcnt(0)
	v_mfma_f32_16x16x32_bf16 v[128:131], v[132:135], v[198:201], v[128:131]
	v_mfma_f32_16x16x32_bf16 v[124:127], v[140:143], v[198:201], v[124:127]
	v_mfma_f32_16x16x32_bf16 v[120:123], v[132:135], v[206:209], v[120:123]
	v_mfma_f32_16x16x32_bf16 v[116:119], v[140:143], v[206:209], v[116:119]
	v_mfma_f32_16x16x32_bf16 v[112:115], v[132:135], v[214:217], v[112:115]
	v_mfma_f32_16x16x32_bf16 v[108:111], v[140:143], v[214:217], v[108:111]
	v_mfma_f32_16x16x32_bf16 v[104:107], v[132:135], v[222:225], v[104:107]
	v_mfma_f32_16x16x32_bf16 v[100:103], v[140:143], v[222:225], v[100:103]
	v_mfma_f32_16x16x32_bf16 v[128:131], v[136:139], v[202:205], v[128:131]
	v_mfma_f32_16x16x32_bf16 v[124:127], v[144:147], v[202:205], v[124:127]
	v_mfma_f32_16x16x32_bf16 v[120:123], v[136:139], v[210:213], v[120:123]
	v_mfma_f32_16x16x32_bf16 v[116:119], v[144:147], v[210:213], v[116:119]
	v_mfma_f32_16x16x32_bf16 v[112:115], v[136:139], v[218:221], v[112:115]
	v_mfma_f32_16x16x32_bf16 v[108:111], v[144:147], v[218:221], v[108:111]
	v_mfma_f32_16x16x32_bf16 v[104:107], v[136:139], v[226:229], v[104:107]
	v_mfma_f32_16x16x32_bf16 v[100:103], v[144:147], v[226:229], v[100:103]
	v_mfma_f32_16x16x32_bf16 v[96:99], v[148:151], v[198:201], v[96:99]
	v_mfma_f32_16x16x32_bf16 v[92:95], v[176:179], v[198:201], v[92:95]
	v_mfma_f32_16x16x32_bf16 v[88:91], v[148:151], v[206:209], v[88:91]
	v_mfma_f32_16x16x32_bf16 v[84:87], v[176:179], v[206:209], v[84:87]
	v_mfma_f32_16x16x32_bf16 v[80:83], v[148:151], v[214:217], v[80:83]
	v_mfma_f32_16x16x32_bf16 v[76:79], v[176:179], v[214:217], v[76:79]
	v_mfma_f32_16x16x32_bf16 v[72:75], v[148:151], v[222:225], v[72:75]
	v_mfma_f32_16x16x32_bf16 v[68:71], v[176:179], v[222:225], v[68:71]
	v_mfma_f32_16x16x32_bf16 v[96:99], v[152:155], v[202:205], v[96:99]
	v_mfma_f32_16x16x32_bf16 v[92:95], v[180:183], v[202:205], v[92:95]
	v_mfma_f32_16x16x32_bf16 v[88:91], v[152:155], v[210:213], v[88:91]
	v_mfma_f32_16x16x32_bf16 v[84:87], v[180:183], v[210:213], v[84:87]
	v_mfma_f32_16x16x32_bf16 v[80:83], v[152:155], v[218:221], v[80:83]
	v_mfma_f32_16x16x32_bf16 v[76:79], v[180:183], v[218:221], v[76:79]
	v_mfma_f32_16x16x32_bf16 v[72:75], v[152:155], v[226:229], v[72:75]
	v_mfma_f32_16x16x32_bf16 v[68:71], v[180:183], v[226:229], v[68:71]
	s_setprio 0
	s_barrier
	s_add_i32 s54, s70, s58
	s_add_u32 s98, s98, s14
	s_addc_u32 s99, s99, s15
	s_mov_b32 m0, s54
	ds_read_b128 v[198:201], v196 offset:49152
	ds_read_b128 v[202:205], v196 offset:50176
	ds_read_b128 v[206:209], v196 offset:51200
	ds_read_b128 v[210:213], v196 offset:52224
	ds_read_b128 v[214:217], v196 offset:53248
	ds_read_b128 v[218:221], v196 offset:54272
	ds_read_b128 v[222:225], v196 offset:55296
	ds_read_b128 v[226:229], v196 offset:56320
	global_load_lds_dwordx4 v166, s[98:99]
	s_add_i32 m0, s54, 0x2000
	s_add_u32 s8, s8, 0x20080
	s_addc_u32 s9, s9, 0
	s_add_i32 s54, s71, s58
	global_load_lds_dwordx4 v164, s[98:99]
	s_mov_b32 m0, s54
	s_nop 0
	global_load_lds_dwordx4 v166, s[8:9]
	s_add_i32 m0, s54, 0x2000
	s_nop 0
	global_load_lds_dwordx4 v164, s[8:9]
	s_add_u32 s100, s100, s14
	s_addc_u32 s101, s101, s15
	s_mov_b32 m0, s63
	s_nop 0
	global_load_lds_dwordx4 v160, s[100:101]
	s_mov_b32 m0, s64
	s_nop 0
	global_load_lds_dwordx4 v162, s[100:101]
	s_waitcnt vmcnt(8)
	s_waitcnt lgkmcnt(0)
	s_barrier
	s_setprio 1
	s_waitcnt lgkmcnt(0)
	v_mfma_f32_16x16x32_bf16 v[64:67], v[132:135], v[198:201], v[64:67]
	v_mfma_f32_16x16x32_bf16 v[60:63], v[140:143], v[198:201], v[60:63]
	v_mfma_f32_16x16x32_bf16 v[56:59], v[132:135], v[206:209], v[56:59]
	v_mfma_f32_16x16x32_bf16 v[52:55], v[140:143], v[206:209], v[52:55]
	v_mfma_f32_16x16x32_bf16 v[48:51], v[132:135], v[214:217], v[48:51]
	v_mfma_f32_16x16x32_bf16 v[44:47], v[140:143], v[214:217], v[44:47]
	v_mfma_f32_16x16x32_bf16 v[40:43], v[132:135], v[222:225], v[40:43]
	v_mfma_f32_16x16x32_bf16 v[36:39], v[140:143], v[222:225], v[36:39]
	v_mfma_f32_16x16x32_bf16 v[64:67], v[136:139], v[202:205], v[64:67]
	v_mfma_f32_16x16x32_bf16 v[60:63], v[144:147], v[202:205], v[60:63]
	v_mfma_f32_16x16x32_bf16 v[56:59], v[136:139], v[210:213], v[56:59]
	v_mfma_f32_16x16x32_bf16 v[52:55], v[144:147], v[210:213], v[52:55]
	v_mfma_f32_16x16x32_bf16 v[48:51], v[136:139], v[218:221], v[48:51]
	v_mfma_f32_16x16x32_bf16 v[44:47], v[144:147], v[218:221], v[44:47]
	v_mfma_f32_16x16x32_bf16 v[40:43], v[136:139], v[226:229], v[40:43]
	v_mfma_f32_16x16x32_bf16 v[36:39], v[144:147], v[226:229], v[36:39]
	v_mfma_f32_16x16x32_bf16 v[32:35], v[148:151], v[198:201], v[32:35]
	v_mfma_f32_16x16x32_bf16 v[28:31], v[176:179], v[198:201], v[28:31]
	v_mfma_f32_16x16x32_bf16 v[24:27], v[148:151], v[206:209], v[24:27]
	v_mfma_f32_16x16x32_bf16 v[20:23], v[176:179], v[206:209], v[20:23]
	v_mfma_f32_16x16x32_bf16 v[16:19], v[148:151], v[214:217], v[16:19]
	v_mfma_f32_16x16x32_bf16 v[12:15], v[176:179], v[214:217], v[12:15]
	v_mfma_f32_16x16x32_bf16 v[6:9], v[148:151], v[222:225], v[8:11]
	v_mfma_f32_16x16x32_bf16 v[2:5], v[176:179], v[222:225], v[2:5]
	v_mfma_f32_16x16x32_bf16 v[32:35], v[152:155], v[202:205], v[32:35]
	v_mfma_f32_16x16x32_bf16 v[28:31], v[180:183], v[202:205], v[28:31]
	v_mfma_f32_16x16x32_bf16 v[24:27], v[152:155], v[210:213], v[24:27]
	v_mfma_f32_16x16x32_bf16 v[20:23], v[180:183], v[210:213], v[20:23]
	v_mfma_f32_16x16x32_bf16 v[16:19], v[152:155], v[218:221], v[16:19]
	v_mfma_f32_16x16x32_bf16 v[12:15], v[180:183], v[218:221], v[12:15]
	v_mfma_f32_16x16x32_bf16 v[8:11], v[152:155], v[226:229], v[6:9]
	v_mfma_f32_16x16x32_bf16 v[4:7], v[180:183], v[226:229], v[2:5]
	s_setprio 0
	s_barrier
	s_add_i32 s69, s69, 2
	s_add_u32 s6, s6, 0x100
	s_addc_u32 s7, s7, 0
	s_add_u32 s67, s67, 0x100
	s_addc_u32 s68, s68, 0
	s_cmp_gt_u32 s69, 5
	s_cbranch_scc0 .LBB0_955
	s_and_b64 vcc, exec, s[34:35]
	s_cbranch_vccz .LBB0_958
	s_barrier

.LBB0_1167:
	s_add_u32 s60, s48, 0xfffc0080
	s_addc_u32 s61, s49, -1
	s_add_i32 s66, 0, 0x10000
	s_cmp_eq_u32 s65, 12
	s_cselect_b32 s63, s14, s61
	s_cselect_b32 s62, s51, s60
	v_add_u32_e32 v0, s66, v169
	s_cselect_b32 s61, s45, s64
	s_cselect_b32 s60, s57, s59
	s_add_i32 s68, 0, 0x14000
	ds_read_b128 v[148:151], v0
	ds_read_b128 v[152:155], v0 offset:1024
	ds_read_b128 v[156:159], v0 offset:2048
	ds_read_b128 v[190:193], v0 offset:3072
	v_add_u32_e32 v0, s68, v169
	ds_read_b128 v[194:197], v0
	ds_read_b128 v[198:201], v0 offset:1024
	ds_read_b128 v[202:205], v0 offset:2048
	ds_read_b128 v[206:209], v0 offset:3072
	s_add_i32 m0, s79, 0xc000
	ds_read_b128 v[210:213], v188
	ds_read_b128 v[214:217], v188 offset:1024
	ds_read_b128 v[218:221], v188 offset:2048
	ds_read_b128 v[222:225], v188 offset:3072
	ds_read_b128 v[226:229], v188 offset:4096
	ds_read_b128 v[234:237], v188 offset:5120
	ds_read_b128 v[238:241], v188 offset:6144
	ds_read_b128 v[242:245], v188 offset:7168
	global_load_lds_dwordx4 v144, s[48:49]
	s_add_i32 m0, s79, 0xe000
	s_nop 0
	global_load_lds_dwordx4 v146, s[48:49]
	s_waitcnt vmcnt(8)
	s_waitcnt lgkmcnt(0)
	s_barrier
	s_setprio 1
	s_waitcnt lgkmcnt(0)
	v_mfma_f32_16x16x32_bf16 v[126:129], v[148:151], v[210:213], v[126:129]
	v_mfma_f32_16x16x32_bf16 v[122:125], v[156:159], v[210:213], v[122:125]
	v_mfma_f32_16x16x32_bf16 v[110:113], v[148:151], v[218:221], v[110:113]
	v_mfma_f32_16x16x32_bf16 v[106:109], v[156:159], v[218:221], v[106:109]
	v_mfma_f32_16x16x32_bf16 v[94:97], v[148:151], v[226:229], v[94:97]
	v_mfma_f32_16x16x32_bf16 v[90:93], v[156:159], v[226:229], v[90:93]
	v_mfma_f32_16x16x32_bf16 v[78:81], v[148:151], v[238:241], v[78:81]
	v_mfma_f32_16x16x32_bf16 v[74:77], v[156:159], v[238:241], v[74:77]
	v_mfma_f32_16x16x32_bf16 v[126:129], v[152:155], v[214:217], v[126:129]
	v_mfma_f32_16x16x32_bf16 v[122:125], v[190:193], v[214:217], v[122:125]
	v_mfma_f32_16x16x32_bf16 v[110:113], v[152:155], v[222:225], v[110:113]
	v_mfma_f32_16x16x32_bf16 v[106:109], v[190:193], v[222:225], v[106:109]
	v_mfma_f32_16x16x32_bf16 v[94:97], v[152:155], v[234:237], v[94:97]
	v_mfma_f32_16x16x32_bf16 v[90:93], v[190:193], v[234:237], v[90:93]
	v_mfma_f32_16x16x32_bf16 v[78:81], v[152:155], v[242:245], v[78:81]
	v_mfma_f32_16x16x32_bf16 v[74:77], v[190:193], v[242:245], v[74:77]
	v_mfma_f32_16x16x32_bf16 v[118:121], v[194:197], v[210:213], v[118:121]
	v_mfma_f32_16x16x32_bf16 v[114:117], v[202:205], v[210:213], v[114:117]
	v_mfma_f32_16x16x32_bf16 v[102:105], v[194:197], v[218:221], v[102:105]
	v_mfma_f32_16x16x32_bf16 v[98:101], v[202:205], v[218:221], v[98:101]
	v_mfma_f32_16x16x32_bf16 v[86:89], v[194:197], v[226:229], v[86:89]
	v_mfma_f32_16x16x32_bf16 v[82:85], v[202:205], v[226:229], v[82:85]
	v_mfma_f32_16x16x32_bf16 v[70:73], v[194:197], v[238:241], v[70:73]
	v_mfma_f32_16x16x32_bf16 v[66:69], v[202:205], v[238:241], v[66:69]
	v_mfma_f32_16x16x32_bf16 v[118:121], v[198:201], v[214:217], v[118:121]
	v_mfma_f32_16x16x32_bf16 v[114:117], v[206:209], v[214:217], v[114:117]
	v_mfma_f32_16x16x32_bf16 v[102:105], v[198:201], v[222:225], v[102:105]
	v_mfma_f32_16x16x32_bf16 v[98:101], v[206:209], v[222:225], v[98:101]
	v_mfma_f32_16x16x32_bf16 v[86:89], v[198:201], v[234:237], v[86:89]
	v_mfma_f32_16x16x32_bf16 v[82:85], v[206:209], v[234:237], v[82:85]
	v_mfma_f32_16x16x32_bf16 v[70:73], v[198:201], v[242:245], v[70:73]
	v_mfma_f32_16x16x32_bf16 v[66:69], v[206:209], v[242:245], v[66:69]
	s_setprio 0
	s_barrier
	s_add_i32 s66, s66, s78
	s_mov_b64 s[98:99], s[60:61]
	s_mov_b32 m0, s66
	ds_read_b128 v[210:213], v188 offset:16384
	ds_read_b128 v[214:217], v188 offset:17408
	ds_read_b128 v[218:221], v188 offset:18432
	ds_read_b128 v[222:225], v188 offset:19456
	ds_read_b128 v[226:229], v188 offset:20480
	ds_read_b128 v[234:237], v188 offset:21504
	ds_read_b128 v[238:241], v188 offset:22528
	ds_read_b128 v[242:245], v188 offset:23552
	global_load_lds_dwordx4 v136, s[60:61]
	s_add_i32 m0, s66, 0x2000
	s_add_u32 s66, s60, 0x40000
	s_addc_u32 s67, s61, 0
	s_add_i32 s68, s68, s78
	global_load_lds_dwordx4 v140, s[60:61]
	s_mov_b32 m0, s68
	s_mov_b64 s[100:101], s[62:63]
	global_load_lds_dwordx4 v136, s[66:67]
	s_add_i32 m0, s68, 0x2000
	s_nop 0
	global_load_lds_dwordx4 v140, s[66:67]
	s_mov_b32 m0, s79
	s_nop 0
	global_load_lds_dwordx4 v134, s[62:63]
	s_mov_b32 m0, s80
	s_nop 0
	global_load_lds_dwordx4 v138, s[62:63]
	s_waitcnt vmcnt(8)
	s_waitcnt lgkmcnt(0)
	s_barrier
	s_setprio 1
	s_waitcnt lgkmcnt(0)
	v_mfma_f32_16x16x32_bf16 v[62:65], v[148:151], v[210:213], v[62:65]
	v_mfma_f32_16x16x32_bf16 v[58:61], v[156:159], v[210:213], v[58:61]
	v_mfma_f32_16x16x32_bf16 v[46:49], v[148:151], v[218:221], v[46:49]
	v_mfma_f32_16x16x32_bf16 v[42:45], v[156:159], v[218:221], v[42:45]
	v_mfma_f32_16x16x32_bf16 v[30:33], v[148:151], v[226:229], v[30:33]
	v_mfma_f32_16x16x32_bf16 v[26:29], v[156:159], v[226:229], v[26:29]
	v_mfma_f32_16x16x32_bf16 v[14:17], v[148:151], v[238:241], v[14:17]
	v_mfma_f32_16x16x32_bf16 v[10:13], v[156:159], v[238:241], v[10:13]
	v_mfma_f32_16x16x32_bf16 v[62:65], v[152:155], v[214:217], v[62:65]
	v_mfma_f32_16x16x32_bf16 v[58:61], v[190:193], v[214:217], v[58:61]
	v_mfma_f32_16x16x32_bf16 v[46:49], v[152:155], v[222:225], v[46:49]
	v_mfma_f32_16x16x32_bf16 v[42:45], v[190:193], v[222:225], v[42:45]
	v_mfma_f32_16x16x32_bf16 v[30:33], v[152:155], v[234:237], v[30:33]
	v_mfma_f32_16x16x32_bf16 v[26:29], v[190:193], v[234:237], v[26:29]
	v_mfma_f32_16x16x32_bf16 v[14:17], v[152:155], v[242:245], v[14:17]
	v_mfma_f32_16x16x32_bf16 v[10:13], v[190:193], v[242:245], v[10:13]
	v_mfma_f32_16x16x32_bf16 v[54:57], v[194:197], v[210:213], v[54:57]
	v_mfma_f32_16x16x32_bf16 v[50:53], v[202:205], v[210:213], v[50:53]
	v_mfma_f32_16x16x32_bf16 v[38:41], v[194:197], v[218:221], v[38:41]
	v_mfma_f32_16x16x32_bf16 v[34:37], v[202:205], v[218:221], v[34:37]
	v_mfma_f32_16x16x32_bf16 v[22:25], v[194:197], v[226:229], v[22:25]
	v_mfma_f32_16x16x32_bf16 v[18:21], v[202:205], v[226:229], v[18:21]
	v_mfma_f32_16x16x32_bf16 v[6:9], v[194:197], v[238:241], v[6:9]
	v_mfma_f32_16x16x32_bf16 v[2:5], v[202:205], v[238:241], v[2:5]
	v_mfma_f32_16x16x32_bf16 v[54:57], v[198:201], v[214:217], v[54:57]
	v_mfma_f32_16x16x32_bf16 v[50:53], v[206:209], v[214:217], v[50:53]
	v_mfma_f32_16x16x32_bf16 v[38:41], v[198:201], v[222:225], v[38:41]
	v_mfma_f32_16x16x32_bf16 v[34:37], v[206:209], v[222:225], v[34:37]
	v_mfma_f32_16x16x32_bf16 v[22:25], v[198:201], v[234:237], v[22:25]
	v_mfma_f32_16x16x32_bf16 v[18:21], v[206:209], v[234:237], v[18:21]
	v_mfma_f32_16x16x32_bf16 v[6:9], v[198:201], v[242:245], v[6:9]
	v_mfma_f32_16x16x32_bf16 v[2:5], v[206:209], v[242:245], v[2:5]
	s_setprio 0
	s_barrier
	s_add_i32 s66, 0, 0x18000
	v_add_u32_e32 v0, s66, v169
	s_add_i32 s67, 0, 0x1c000
	ds_read_b128 v[148:151], v0
	ds_read_b128 v[152:155], v0 offset:1024
	ds_read_b128 v[156:159], v0 offset:2048
	ds_read_b128 v[190:193], v0 offset:3072
	v_add_u32_e32 v0, s67, v169
	ds_read_b128 v[194:197], v0
	ds_read_b128 v[198:201], v0 offset:1024
	ds_read_b128 v[202:205], v0 offset:2048
	ds_read_b128 v[206:209], v0 offset:3072
	s_add_u32 s62, s62, 0x40000
	s_addc_u32 s63, s63, 0
	s_mov_b32 m0, s81
	ds_read_b128 v[210:213], v188 offset:32768
	ds_read_b128 v[214:217], v188 offset:33792
	ds_read_b128 v[218:221], v188 offset:34816
	ds_read_b128 v[222:225], v188 offset:35840
	ds_read_b128 v[226:229], v188 offset:36864
	ds_read_b128 v[234:237], v188 offset:37888
	ds_read_b128 v[238:241], v188 offset:38912
	ds_read_b128 v[242:245], v188 offset:39936
	global_load_lds_dwordx4 v134, s[62:63]
	s_mov_b32 m0, s82
	s_nop 0
	global_load_lds_dwordx4 v138, s[62:63]
	s_waitcnt vmcnt(8)
	s_waitcnt lgkmcnt(0)
	s_barrier
	s_setprio 1
	s_waitcnt lgkmcnt(0)
	v_mfma_f32_16x16x32_bf16 v[126:129], v[148:151], v[210:213], v[126:129]
	v_mfma_f32_16x16x32_bf16 v[122:125], v[156:159], v[210:213], v[122:125]
	v_mfma_f32_16x16x32_bf16 v[110:113], v[148:151], v[218:221], v[110:113]
	v_mfma_f32_16x16x32_bf16 v[106:109], v[156:159], v[218:221], v[106:109]
	v_mfma_f32_16x16x32_bf16 v[94:97], v[148:151], v[226:229], v[94:97]
	v_mfma_f32_16x16x32_bf16 v[90:93], v[156:159], v[226:229], v[90:93]
	v_mfma_f32_16x16x32_bf16 v[78:81], v[148:151], v[238:241], v[78:81]
	v_mfma_f32_16x16x32_bf16 v[74:77], v[156:159], v[238:241], v[74:77]
	v_mfma_f32_16x16x32_bf16 v[126:129], v[152:155], v[214:217], v[126:129]
	v_mfma_f32_16x16x32_bf16 v[122:125], v[190:193], v[214:217], v[122:125]
	v_mfma_f32_16x16x32_bf16 v[110:113], v[152:155], v[222:225], v[110:113]
	v_mfma_f32_16x16x32_bf16 v[106:109], v[190:193], v[222:225], v[106:109]
	v_mfma_f32_16x16x32_bf16 v[94:97], v[152:155], v[234:237], v[94:97]
	v_mfma_f32_16x16x32_bf16 v[90:93], v[190:193], v[234:237], v[90:93]
	v_mfma_f32_16x16x32_bf16 v[78:81], v[152:155], v[242:245], v[78:81]
	v_mfma_f32_16x16x32_bf16 v[74:77], v[190:193], v[242:245], v[74:77]
	v_mfma_f32_16x16x32_bf16 v[118:121], v[194:197], v[210:213], v[118:121]
	v_mfma_f32_16x16x32_bf16 v[114:117], v[202:205], v[210:213], v[114:117]
	v_mfma_f32_16x16x32_bf16 v[102:105], v[194:197], v[218:221], v[102:105]
	v_mfma_f32_16x16x32_bf16 v[98:101], v[202:205], v[218:221], v[98:101]
	v_mfma_f32_16x16x32_bf16 v[86:89], v[194:197], v[226:229], v[86:89]
	v_mfma_f32_16x16x32_bf16 v[82:85], v[202:205], v[226:229], v[82:85]
	v_mfma_f32_16x16x32_bf16 v[70:73], v[194:197], v[238:241], v[70:73]
	v_mfma_f32_16x16x32_bf16 v[66:69], v[202:205], v[238:241], v[66:69]
	v_mfma_f32_16x16x32_bf16 v[118:121], v[198:201], v[214:217], v[118:121]
	v_mfma_f32_16x16x32_bf16 v[114:117], v[206:209], v[214:217], v[114:117]
	v_mfma_f32_16x16x32_bf16 v[102:105], v[198:201], v[222:225], v[102:105]
	v_mfma_f32_16x16x32_bf16 v[98:101], v[206:209], v[222:225], v[98:101]
	v_mfma_f32_16x16x32_bf16 v[86:89], v[198:201], v[234:237], v[86:89]
	v_mfma_f32_16x16x32_bf16 v[82:85], v[206:209], v[234:237], v[82:85]
	v_mfma_f32_16x16x32_bf16 v[70:73], v[198:201], v[242:245], v[70:73]
	v_mfma_f32_16x16x32_bf16 v[66:69], v[206:209], v[242:245], v[66:69]
	s_setprio 0
	s_barrier
	s_add_i32 s62, s66, s78
	s_add_u32 s98, s98, s16
	s_addc_u32 s99, s99, s17
	s_mov_b32 m0, s62
	ds_read_b128 v[210:213], v188 offset:49152
	ds_read_b128 v[214:217], v188 offset:50176
	ds_read_b128 v[218:221], v188 offset:51200
	ds_read_b128 v[222:225], v188 offset:52224
	ds_read_b128 v[226:229], v188 offset:53248
	ds_read_b128 v[234:237], v188 offset:54272
	ds_read_b128 v[238:241], v188 offset:55296
	ds_read_b128 v[242:245], v188 offset:56320
	global_load_lds_dwordx4 v136, s[98:99]
	s_add_i32 m0, s62, 0x2000
	s_add_u32 s60, s60, 0x40080
	s_addc_u32 s61, s61, 0
	s_add_i32 s62, s67, s78
	global_load_lds_dwordx4 v140, s[98:99]
	s_mov_b32 m0, s62
	s_nop 0
	global_load_lds_dwordx4 v136, s[60:61]
	s_add_i32 m0, s62, 0x2000
	s_nop 0
	global_load_lds_dwordx4 v140, s[60:61]
	s_add_u32 s100, s100, s16
	s_addc_u32 s101, s101, s17
	s_mov_b32 m0, s85
	s_nop 0
	global_load_lds_dwordx4 v134, s[100:101]
	s_mov_b32 m0, s86
	s_nop 0
	global_load_lds_dwordx4 v138, s[100:101]
	s_waitcnt vmcnt(8)
	s_waitcnt lgkmcnt(0)
	s_barrier
	s_setprio 1
	s_waitcnt lgkmcnt(0)
	v_mfma_f32_16x16x32_bf16 v[62:65], v[148:151], v[210:213], v[62:65]
	v_mfma_f32_16x16x32_bf16 v[58:61], v[156:159], v[210:213], v[58:61]
	v_mfma_f32_16x16x32_bf16 v[46:49], v[148:151], v[218:221], v[46:49]
	v_mfma_f32_16x16x32_bf16 v[42:45], v[156:159], v[218:221], v[42:45]
	v_mfma_f32_16x16x32_bf16 v[30:33], v[148:151], v[226:229], v[30:33]
	v_mfma_f32_16x16x32_bf16 v[26:29], v[156:159], v[226:229], v[26:29]
	v_mfma_f32_16x16x32_bf16 v[14:17], v[148:151], v[238:241], v[14:17]
	v_mfma_f32_16x16x32_bf16 v[10:13], v[156:159], v[238:241], v[10:13]
	v_mfma_f32_16x16x32_bf16 v[62:65], v[152:155], v[214:217], v[62:65]
	v_mfma_f32_16x16x32_bf16 v[58:61], v[190:193], v[214:217], v[58:61]
	v_mfma_f32_16x16x32_bf16 v[46:49], v[152:155], v[222:225], v[46:49]
	v_mfma_f32_16x16x32_bf16 v[42:45], v[190:193], v[222:225], v[42:45]
	v_mfma_f32_16x16x32_bf16 v[30:33], v[152:155], v[234:237], v[30:33]
	v_mfma_f32_16x16x32_bf16 v[26:29], v[190:193], v[234:237], v[26:29]
	v_mfma_f32_16x16x32_bf16 v[14:17], v[152:155], v[242:245], v[14:17]
	v_mfma_f32_16x16x32_bf16 v[10:13], v[190:193], v[242:245], v[10:13]
	v_mfma_f32_16x16x32_bf16 v[54:57], v[194:197], v[210:213], v[54:57]
	v_mfma_f32_16x16x32_bf16 v[50:53], v[202:205], v[210:213], v[50:53]
	v_mfma_f32_16x16x32_bf16 v[38:41], v[194:197], v[218:221], v[38:41]
	v_mfma_f32_16x16x32_bf16 v[34:37], v[202:205], v[218:221], v[34:37]
	v_mfma_f32_16x16x32_bf16 v[22:25], v[194:197], v[226:229], v[22:25]
	v_mfma_f32_16x16x32_bf16 v[18:21], v[202:205], v[226:229], v[18:21]
	v_mfma_f32_16x16x32_bf16 v[6:9], v[194:197], v[238:241], v[6:9]
	v_mfma_f32_16x16x32_bf16 v[2:5], v[202:205], v[238:241], v[2:5]
	v_mfma_f32_16x16x32_bf16 v[54:57], v[198:201], v[214:217], v[54:57]
	v_mfma_f32_16x16x32_bf16 v[50:53], v[206:209], v[214:217], v[50:53]
	v_mfma_f32_16x16x32_bf16 v[38:41], v[198:201], v[222:225], v[38:41]
	v_mfma_f32_16x16x32_bf16 v[34:37], v[206:209], v[222:225], v[34:37]
	v_mfma_f32_16x16x32_bf16 v[22:25], v[198:201], v[234:237], v[22:25]
	v_mfma_f32_16x16x32_bf16 v[18:21], v[206:209], v[234:237], v[18:21]
	v_mfma_f32_16x16x32_bf16 v[6:9], v[198:201], v[242:245], v[6:9]
	v_mfma_f32_16x16x32_bf16 v[2:5], v[206:209], v[242:245], v[2:5]
	s_setprio 0
	s_barrier
	s_add_i32 s65, s65, 2
	s_add_u32 s48, s48, 0x100
	s_addc_u32 s49, s49, 0
	s_add_u32 s59, s59, 0x100
	s_addc_u32 s64, s64, 0
	s_cmp_gt_u32 s65, 13
	s_cbranch_scc0 .LBB0_1167
	s_and_b64 vcc, exec, s[38:39]
	s_cbranch_vccz .LBB0_1171
	s_barrier
	s_andn2_b64 vcc, exec, s[20:21]
	s_cbranch_vccz .LBB0_1172

.LBB0_1478:
	s_add_i32 m0, s55, 0xc000
	s_and_b64 vcc, exec, s[8:9]
	global_load_lds_dwordx4 v210, s[60:61]
	s_add_i32 m0, s55, 0xe000
	s_nop 0
	global_load_lds_dwordx4 v212, s[60:61]
	s_waitcnt vmcnt(8)
	s_waitcnt lgkmcnt(0)
	s_barrier
	s_cbranch_vccnz .LBB0_1480
	s_setprio 1
	s_waitcnt lgkmcnt(0)
	v_mfma_i32_16x16x64_i8 v[176:179], v[180:183], v[4:7], v[176:179]
	v_mfma_i32_16x16x64_i8 v[168:171], v[188:191], v[4:7], v[168:171]
	v_mfma_i32_16x16x64_i8 v[160:163], v[180:183], v[12:15], v[160:163]
	v_mfma_i32_16x16x64_i8 v[152:155], v[188:191], v[12:15], v[152:155]
	v_mfma_i32_16x16x64_i8 v[144:147], v[180:183], v[20:23], v[144:147]
	v_mfma_i32_16x16x64_i8 v[136:139], v[188:191], v[20:23], v[136:139]
	v_mfma_i32_16x16x64_i8 v[120:123], v[180:183], v[28:31], v[120:123]
	v_mfma_i32_16x16x64_i8 v[104:107], v[188:191], v[28:31], v[104:107]
	v_mfma_i32_16x16x64_i8 v[176:179], v[184:187], v[8:11], v[176:179]
	v_mfma_i32_16x16x64_i8 v[168:171], v[192:195], v[8:11], v[168:171]
	v_mfma_i32_16x16x64_i8 v[160:163], v[184:187], v[16:19], v[160:163]
	v_mfma_i32_16x16x64_i8 v[152:155], v[192:195], v[16:19], v[152:155]
	v_mfma_i32_16x16x64_i8 v[144:147], v[184:187], v[24:27], v[144:147]
	v_mfma_i32_16x16x64_i8 v[136:139], v[192:195], v[24:27], v[136:139]
	v_mfma_i32_16x16x64_i8 v[120:123], v[184:187], v[32:35], v[120:123]
	v_mfma_i32_16x16x64_i8 v[104:107], v[192:195], v[32:35], v[104:107]
	v_mfma_i32_16x16x64_i8 v[172:175], v[108:111], v[4:7], v[172:175]
	v_mfma_i32_16x16x64_i8 v[164:167], v[124:127], v[4:7], v[164:167]
	v_mfma_i32_16x16x64_i8 v[156:159], v[108:111], v[12:15], v[156:159]
	v_mfma_i32_16x16x64_i8 v[148:151], v[124:127], v[12:15], v[148:151]
	v_mfma_i32_16x16x64_i8 v[140:143], v[108:111], v[20:23], v[140:143]
	v_mfma_i32_16x16x64_i8 v[132:135], v[124:127], v[20:23], v[132:135]
	v_mfma_i32_16x16x64_i8 v[116:119], v[108:111], v[28:31], v[116:119]
	v_mfma_i32_16x16x64_i8 v[100:103], v[124:127], v[28:31], v[100:103]
	v_mfma_i32_16x16x64_i8 v[172:175], v[112:115], v[8:11], v[172:175]
	v_mfma_i32_16x16x64_i8 v[164:167], v[128:131], v[8:11], v[164:167]
	v_mfma_i32_16x16x64_i8 v[156:159], v[112:115], v[16:19], v[156:159]
	v_mfma_i32_16x16x64_i8 v[148:151], v[128:131], v[16:19], v[148:151]
	v_mfma_i32_16x16x64_i8 v[140:143], v[112:115], v[24:27], v[140:143]
	v_mfma_i32_16x16x64_i8 v[132:135], v[128:131], v[24:27], v[132:135]
	v_mfma_i32_16x16x64_i8 v[116:119], v[112:115], v[32:35], v[116:119]
	v_mfma_i32_16x16x64_i8 v[100:103], v[128:131], v[32:35], v[100:103]
	s_setprio 0

.LBB0_1482:
	s_add_u32 s62, s60, 0xfffe0080
	s_addc_u32 s63, s61, -1
	s_cmp_eq_u32 s97, 4
	s_cselect_b32 s65, s43, s63
	s_cselect_b32 s64, s93, s62
	s_cselect_b32 s63, s41, s96
	s_cselect_b32 s62, s94, s95
	s_mov_b32 m0, s57
	s_mov_b64 s[98:99], s[62:63]
	s_add_u32 vcc_lo, s62, 0x20000
	global_load_lds_dwordx4 v200, s[62:63]
	s_mov_b32 m0, s73
	s_addc_u32 vcc_hi, s63, 0
	global_load_lds_dwordx4 v204, s[62:63]
	v_lshl_add_u64 v[216:217], vcc, 0, v[200:201]
	s_mov_b32 m0, s74
	s_mov_b64 s[100:101], s[64:65]
	global_load_lds_dwordx4 v[216:217], off
	v_lshl_add_u64 v[216:217], vcc, 0, v[204:205]
	s_mov_b32 m0, s75
	s_and_b64 vcc, exec, s[6:7]
	global_load_lds_dwordx4 v[216:217], off
	s_mov_b32 m0, s55
	s_nop 0
	global_load_lds_dwordx4 v198, s[64:65]
	s_mov_b32 m0, s76
	s_nop 0
	global_load_lds_dwordx4 v202, s[64:65]
	s_waitcnt vmcnt(8)
	s_waitcnt lgkmcnt(0)
	s_barrier
	s_cbranch_vccnz .LBB0_1484
	s_setprio 1
	s_waitcnt lgkmcnt(0)
	v_mfma_i32_16x16x64_i8 v[96:99], v[180:183], v[4:7], v[96:99]
	v_mfma_i32_16x16x64_i8 v[88:91], v[188:191], v[4:7], v[88:91]
	v_mfma_i32_16x16x64_i8 v[80:83], v[180:183], v[12:15], v[80:83]
	v_mfma_i32_16x16x64_i8 v[72:75], v[188:191], v[12:15], v[72:75]
	v_mfma_i32_16x16x64_i8 v[64:67], v[180:183], v[20:23], v[64:67]
	v_mfma_i32_16x16x64_i8 v[56:59], v[188:191], v[20:23], v[56:59]
	v_mfma_i32_16x16x64_i8 v[48:51], v[180:183], v[28:31], v[48:51]
	v_mfma_i32_16x16x64_i8 v[40:43], v[188:191], v[28:31], v[40:43]
	v_mfma_i32_16x16x64_i8 v[96:99], v[184:187], v[8:11], v[96:99]
	v_mfma_i32_16x16x64_i8 v[88:91], v[192:195], v[8:11], v[88:91]
	v_mfma_i32_16x16x64_i8 v[80:83], v[184:187], v[16:19], v[80:83]
	v_mfma_i32_16x16x64_i8 v[72:75], v[192:195], v[16:19], v[72:75]
	v_mfma_i32_16x16x64_i8 v[64:67], v[184:187], v[24:27], v[64:67]
	v_mfma_i32_16x16x64_i8 v[56:59], v[192:195], v[24:27], v[56:59]
	v_mfma_i32_16x16x64_i8 v[48:51], v[184:187], v[32:35], v[48:51]
	v_mfma_i32_16x16x64_i8 v[40:43], v[192:195], v[32:35], v[40:43]
	v_mfma_i32_16x16x64_i8 v[92:95], v[108:111], v[4:7], v[92:95]
	v_mfma_i32_16x16x64_i8 v[84:87], v[124:127], v[4:7], v[84:87]
	v_mfma_i32_16x16x64_i8 v[76:79], v[108:111], v[12:15], v[76:79]
	v_mfma_i32_16x16x64_i8 v[68:71], v[124:127], v[12:15], v[68:71]
	v_mfma_i32_16x16x64_i8 v[60:63], v[108:111], v[20:23], v[60:63]
	v_mfma_i32_16x16x64_i8 v[52:55], v[124:127], v[20:23], v[52:55]
	v_mfma_i32_16x16x64_i8 v[44:47], v[108:111], v[28:31], v[44:47]
	v_mfma_i32_16x16x64_i8 v[36:39], v[124:127], v[28:31], v[36:39]
	v_mfma_i32_16x16x64_i8 v[92:95], v[112:115], v[8:11], v[92:95]
	v_mfma_i32_16x16x64_i8 v[84:87], v[128:131], v[8:11], v[84:87]
	v_mfma_i32_16x16x64_i8 v[76:79], v[112:115], v[16:19], v[76:79]
	v_mfma_i32_16x16x64_i8 v[68:71], v[128:131], v[16:19], v[68:71]
	v_mfma_i32_16x16x64_i8 v[60:63], v[112:115], v[24:27], v[60:63]
	v_mfma_i32_16x16x64_i8 v[52:55], v[128:131], v[24:27], v[52:55]
	v_mfma_i32_16x16x64_i8 v[44:47], v[112:115], v[32:35], v[44:47]
	v_mfma_i32_16x16x64_i8 v[36:39], v[128:131], v[32:35], v[36:39]
	s_setprio 0

.LBB0_1486:
	s_add_u32 s64, s64, 0x20000
	s_addc_u32 s65, s65, 0
	s_mov_b32 m0, s77
	s_nop 0
	global_load_lds_dwordx4 v198, s[64:65]
	s_mov_b32 m0, s78
	s_and_b64 vcc, exec, s[8:9]
	global_load_lds_dwordx4 v202, s[64:65]
	s_waitcnt vmcnt(8)
	s_waitcnt lgkmcnt(0)
	s_barrier
	s_cbranch_vccnz .LBB0_1488
	s_setprio 1
	s_waitcnt lgkmcnt(0)
	v_mfma_i32_16x16x64_i8 v[176:179], v[180:183], v[4:7], v[176:179]
	v_mfma_i32_16x16x64_i8 v[168:171], v[188:191], v[4:7], v[168:171]
	v_mfma_i32_16x16x64_i8 v[160:163], v[180:183], v[12:15], v[160:163]
	v_mfma_i32_16x16x64_i8 v[152:155], v[188:191], v[12:15], v[152:155]
	v_mfma_i32_16x16x64_i8 v[144:147], v[180:183], v[20:23], v[144:147]
	v_mfma_i32_16x16x64_i8 v[136:139], v[188:191], v[20:23], v[136:139]
	v_mfma_i32_16x16x64_i8 v[120:123], v[180:183], v[28:31], v[120:123]
	v_mfma_i32_16x16x64_i8 v[104:107], v[188:191], v[28:31], v[104:107]
	v_mfma_i32_16x16x64_i8 v[176:179], v[184:187], v[8:11], v[176:179]
	v_mfma_i32_16x16x64_i8 v[168:171], v[192:195], v[8:11], v[168:171]
	v_mfma_i32_16x16x64_i8 v[160:163], v[184:187], v[16:19], v[160:163]
	v_mfma_i32_16x16x64_i8 v[152:155], v[192:195], v[16:19], v[152:155]
	v_mfma_i32_16x16x64_i8 v[144:147], v[184:187], v[24:27], v[144:147]
	v_mfma_i32_16x16x64_i8 v[136:139], v[192:195], v[24:27], v[136:139]
	v_mfma_i32_16x16x64_i8 v[120:123], v[184:187], v[32:35], v[120:123]
	v_mfma_i32_16x16x64_i8 v[104:107], v[192:195], v[32:35], v[104:107]
	v_mfma_i32_16x16x64_i8 v[172:175], v[108:111], v[4:7], v[172:175]
	v_mfma_i32_16x16x64_i8 v[164:167], v[124:127], v[4:7], v[164:167]
	v_mfma_i32_16x16x64_i8 v[156:159], v[108:111], v[12:15], v[156:159]
	v_mfma_i32_16x16x64_i8 v[148:151], v[124:127], v[12:15], v[148:151]
	v_mfma_i32_16x16x64_i8 v[140:143], v[108:111], v[20:23], v[140:143]
	v_mfma_i32_16x16x64_i8 v[132:135], v[124:127], v[20:23], v[132:135]
	v_mfma_i32_16x16x64_i8 v[116:119], v[108:111], v[28:31], v[116:119]
	v_mfma_i32_16x16x64_i8 v[100:103], v[124:127], v[28:31], v[100:103]
	v_mfma_i32_16x16x64_i8 v[172:175], v[112:115], v[8:11], v[172:175]
	v_mfma_i32_16x16x64_i8 v[164:167], v[128:131], v[8:11], v[164:167]
	v_mfma_i32_16x16x64_i8 v[156:159], v[112:115], v[16:19], v[156:159]
	v_mfma_i32_16x16x64_i8 v[148:151], v[128:131], v[16:19], v[148:151]
	v_mfma_i32_16x16x64_i8 v[140:143], v[112:115], v[24:27], v[140:143]
	v_mfma_i32_16x16x64_i8 v[132:135], v[128:131], v[24:27], v[132:135]
	v_mfma_i32_16x16x64_i8 v[116:119], v[112:115], v[32:35], v[116:119]
	v_mfma_i32_16x16x64_i8 v[100:103], v[128:131], v[32:35], v[100:103]
	s_setprio 0

.LBB0_1490:
	s_mov_b32 m0, s80
	s_add_u32 s98, s98, s20
	s_addc_u32 s99, s99, s21
	s_add_u32 s8, s62, 0x20080
	global_load_lds_dwordx4 v200, s[98:99]
	s_mov_b32 m0, s81
	s_addc_u32 s9, s63, 0
	global_load_lds_dwordx4 v204, s[98:99]
	s_mov_b32 m0, s84
	s_and_b64 vcc, exec, s[6:7]
	global_load_lds_dwordx4 v200, s[8:9]
	s_mov_b32 m0, s85
	s_nop 0
	global_load_lds_dwordx4 v204, s[8:9]
	s_add_u32 s100, s100, s20
	s_addc_u32 s101, s101, s21
	s_mov_b32 m0, s82
	s_nop 0
	global_load_lds_dwordx4 v198, s[100:101]
	s_mov_b32 m0, s83
	s_nop 0
	global_load_lds_dwordx4 v202, s[100:101]
	s_waitcnt vmcnt(8)
	s_waitcnt lgkmcnt(0)
	s_barrier
	s_cbranch_vccnz .LBB0_1475
	s_setprio 1
	s_waitcnt lgkmcnt(0)
	v_mfma_i32_16x16x64_i8 v[96:99], v[180:183], v[4:7], v[96:99]
	v_mfma_i32_16x16x64_i8 v[88:91], v[188:191], v[4:7], v[88:91]
	v_mfma_i32_16x16x64_i8 v[80:83], v[180:183], v[12:15], v[80:83]
	v_mfma_i32_16x16x64_i8 v[72:75], v[188:191], v[12:15], v[72:75]
	v_mfma_i32_16x16x64_i8 v[64:67], v[180:183], v[20:23], v[64:67]
	v_mfma_i32_16x16x64_i8 v[56:59], v[188:191], v[20:23], v[56:59]
	v_mfma_i32_16x16x64_i8 v[48:51], v[180:183], v[28:31], v[48:51]
	v_mfma_i32_16x16x64_i8 v[40:43], v[188:191], v[28:31], v[40:43]
	v_mfma_i32_16x16x64_i8 v[96:99], v[184:187], v[8:11], v[96:99]
	v_mfma_i32_16x16x64_i8 v[88:91], v[192:195], v[8:11], v[88:91]
	v_mfma_i32_16x16x64_i8 v[80:83], v[184:187], v[16:19], v[80:83]
	v_mfma_i32_16x16x64_i8 v[72:75], v[192:195], v[16:19], v[72:75]
	v_mfma_i32_16x16x64_i8 v[64:67], v[184:187], v[24:27], v[64:67]
	v_mfma_i32_16x16x64_i8 v[56:59], v[192:195], v[24:27], v[56:59]
	v_mfma_i32_16x16x64_i8 v[48:51], v[184:187], v[32:35], v[48:51]
	v_mfma_i32_16x16x64_i8 v[40:43], v[192:195], v[32:35], v[40:43]
	v_mfma_i32_16x16x64_i8 v[92:95], v[108:111], v[4:7], v[92:95]
	v_mfma_i32_16x16x64_i8 v[84:87], v[124:127], v[4:7], v[84:87]
	v_mfma_i32_16x16x64_i8 v[76:79], v[108:111], v[12:15], v[76:79]
	v_mfma_i32_16x16x64_i8 v[68:71], v[124:127], v[12:15], v[68:71]
	v_mfma_i32_16x16x64_i8 v[60:63], v[108:111], v[20:23], v[60:63]
	v_mfma_i32_16x16x64_i8 v[52:55], v[124:127], v[20:23], v[52:55]
	v_mfma_i32_16x16x64_i8 v[44:47], v[108:111], v[28:31], v[44:47]
	v_mfma_i32_16x16x64_i8 v[36:39], v[124:127], v[28:31], v[36:39]
	v_mfma_i32_16x16x64_i8 v[92:95], v[112:115], v[8:11], v[92:95]
	v_mfma_i32_16x16x64_i8 v[84:87], v[128:131], v[8:11], v[84:87]
	v_mfma_i32_16x16x64_i8 v[76:79], v[112:115], v[16:19], v[76:79]
	v_mfma_i32_16x16x64_i8 v[68:71], v[128:131], v[16:19], v[68:71]
	v_mfma_i32_16x16x64_i8 v[60:63], v[112:115], v[24:27], v[60:63]
	v_mfma_i32_16x16x64_i8 v[52:55], v[128:131], v[24:27], v[52:55]
	v_mfma_i32_16x16x64_i8 v[44:47], v[112:115], v[32:35], v[44:47]
	v_mfma_i32_16x16x64_i8 v[36:39], v[128:131], v[32:35], v[36:39]
	s_setprio 0
	s_branch .LBB0_1475

.LBB0_1636:
	s_add_u32 s56, s48, 0x100
	s_addc_u32 s57, s49, 0
	s_add_i32 s64, 0, 0x10000
	s_cmp_eq_u32 s63, 40
	s_cselect_b32 s61, s13, s57
	s_cselect_b32 s60, s12, s56
	v_add_u32_e32 v0, s64, v169
	s_cselect_b32 s59, s53, s55
	s_cselect_b32 s58, s52, s16
	s_add_i32 s65, 0, 0x14000
	ds_read_b128 v[148:151], v0
	ds_read_b128 v[152:155], v0 offset:1024
	ds_read_b128 v[156:159], v0 offset:2048
	ds_read_b128 v[190:193], v0 offset:3072
	v_add_u32_e32 v0, s65, v169
	ds_read_b128 v[194:197], v0
	ds_read_b128 v[198:201], v0 offset:1024
	ds_read_b128 v[202:205], v0 offset:2048
	ds_read_b128 v[206:209], v0 offset:3072
	v_lshl_add_u64 v[230:231], s[48:49], 0, v[144:145]
	s_add_i32 m0, s79, 0xc000
	ds_read_b128 v[210:213], v188
	ds_read_b128 v[214:217], v188 offset:1024
	ds_read_b128 v[218:221], v188 offset:2048
	ds_read_b128 v[222:225], v188 offset:3072
	ds_read_b128 v[226:229], v188 offset:4096
	ds_read_b128 v[234:237], v188 offset:5120
	ds_read_b128 v[238:241], v188 offset:6144
	ds_read_b128 v[242:245], v188 offset:7168
	global_load_lds_dwordx4 v[230:231], off
	v_lshl_add_u64 v[230:231], s[48:49], 0, v[146:147]
	s_add_i32 m0, s79, 0xe000
	s_nop 0
	global_load_lds_dwordx4 v[230:231], off
	s_waitcnt vmcnt(8)
	s_waitcnt lgkmcnt(0)
	s_barrier
	s_setprio 1
	s_waitcnt lgkmcnt(0)
	v_mfma_f32_16x16x32_bf16 v[126:129], v[148:151], v[210:213], v[126:129]
	v_mfma_f32_16x16x32_bf16 v[122:125], v[156:159], v[210:213], v[122:125]
	v_mfma_f32_16x16x32_bf16 v[110:113], v[148:151], v[218:221], v[110:113]
	v_mfma_f32_16x16x32_bf16 v[106:109], v[156:159], v[218:221], v[106:109]
	v_mfma_f32_16x16x32_bf16 v[94:97], v[148:151], v[226:229], v[94:97]
	v_mfma_f32_16x16x32_bf16 v[90:93], v[156:159], v[226:229], v[90:93]
	v_mfma_f32_16x16x32_bf16 v[78:81], v[148:151], v[238:241], v[78:81]
	v_mfma_f32_16x16x32_bf16 v[74:77], v[156:159], v[238:241], v[74:77]
	v_mfma_f32_16x16x32_bf16 v[126:129], v[152:155], v[214:217], v[126:129]
	v_mfma_f32_16x16x32_bf16 v[122:125], v[190:193], v[214:217], v[122:125]
	v_mfma_f32_16x16x32_bf16 v[110:113], v[152:155], v[222:225], v[110:113]
	v_mfma_f32_16x16x32_bf16 v[106:109], v[190:193], v[222:225], v[106:109]
	v_mfma_f32_16x16x32_bf16 v[94:97], v[152:155], v[234:237], v[94:97]
	v_mfma_f32_16x16x32_bf16 v[90:93], v[190:193], v[234:237], v[90:93]
	v_mfma_f32_16x16x32_bf16 v[78:81], v[152:155], v[242:245], v[78:81]
	v_mfma_f32_16x16x32_bf16 v[74:77], v[190:193], v[242:245], v[74:77]
	v_mfma_f32_16x16x32_bf16 v[118:121], v[194:197], v[210:213], v[118:121]
	v_mfma_f32_16x16x32_bf16 v[114:117], v[202:205], v[210:213], v[114:117]
	v_mfma_f32_16x16x32_bf16 v[102:105], v[194:197], v[218:221], v[102:105]
	v_mfma_f32_16x16x32_bf16 v[98:101], v[202:205], v[218:221], v[98:101]
	v_mfma_f32_16x16x32_bf16 v[86:89], v[194:197], v[226:229], v[86:89]
	v_mfma_f32_16x16x32_bf16 v[82:85], v[202:205], v[226:229], v[82:85]
	v_mfma_f32_16x16x32_bf16 v[70:73], v[194:197], v[238:241], v[70:73]
	v_mfma_f32_16x16x32_bf16 v[66:69], v[202:205], v[238:241], v[66:69]
	v_mfma_f32_16x16x32_bf16 v[118:121], v[198:201], v[214:217], v[118:121]
	v_mfma_f32_16x16x32_bf16 v[114:117], v[206:209], v[214:217], v[114:117]
	v_mfma_f32_16x16x32_bf16 v[102:105], v[198:201], v[222:225], v[102:105]
	v_mfma_f32_16x16x32_bf16 v[98:101], v[206:209], v[222:225], v[98:101]
	v_mfma_f32_16x16x32_bf16 v[86:89], v[198:201], v[234:237], v[86:89]
	v_mfma_f32_16x16x32_bf16 v[82:85], v[206:209], v[234:237], v[82:85]
	v_mfma_f32_16x16x32_bf16 v[70:73], v[198:201], v[242:245], v[70:73]
	v_mfma_f32_16x16x32_bf16 v[66:69], v[206:209], v[242:245], v[66:69]
	s_setprio 0
	s_barrier
	s_add_i32 s48, s64, s78
	s_mov_b64 s[98:99], s[58:59]
	s_mov_b32 m0, s48
	ds_read_b128 v[210:213], v188 offset:16384
	ds_read_b128 v[214:217], v188 offset:17408
	ds_read_b128 v[218:221], v188 offset:18432
	ds_read_b128 v[222:225], v188 offset:19456
	ds_read_b128 v[226:229], v188 offset:20480
	ds_read_b128 v[234:237], v188 offset:21504
	ds_read_b128 v[238:241], v188 offset:22528
	ds_read_b128 v[242:245], v188 offset:23552
	global_load_lds_dwordx4 v136, s[58:59]
	s_add_i32 m0, s48, 0x2000
	s_add_u32 s48, s58, 0xb0000
	s_addc_u32 s49, s59, 0
	s_add_i32 s64, s65, s78
	global_load_lds_dwordx4 v140, s[58:59]
	s_mov_b32 m0, s64
	s_mov_b64 s[100:101], s[60:61]
	global_load_lds_dwordx4 v136, s[48:49]
	s_add_i32 m0, s64, 0x2000
	s_nop 0
	global_load_lds_dwordx4 v140, s[48:49]
	s_mov_b32 m0, s79
	s_nop 0
	global_load_lds_dwordx4 v134, s[60:61]
	s_mov_b32 m0, s80
	s_nop 0
	global_load_lds_dwordx4 v138, s[60:61]
	s_waitcnt vmcnt(8)
	s_waitcnt lgkmcnt(0)
	s_barrier
	s_setprio 1
	s_waitcnt lgkmcnt(0)
	v_mfma_f32_16x16x32_bf16 v[62:65], v[148:151], v[210:213], v[62:65]
	v_mfma_f32_16x16x32_bf16 v[58:61], v[156:159], v[210:213], v[58:61]
	v_mfma_f32_16x16x32_bf16 v[46:49], v[148:151], v[218:221], v[46:49]
	v_mfma_f32_16x16x32_bf16 v[42:45], v[156:159], v[218:221], v[42:45]
	v_mfma_f32_16x16x32_bf16 v[30:33], v[148:151], v[226:229], v[30:33]
	v_mfma_f32_16x16x32_bf16 v[26:29], v[156:159], v[226:229], v[26:29]
	v_mfma_f32_16x16x32_bf16 v[14:17], v[148:151], v[238:241], v[14:17]
	v_mfma_f32_16x16x32_bf16 v[10:13], v[156:159], v[238:241], v[10:13]
	v_mfma_f32_16x16x32_bf16 v[62:65], v[152:155], v[214:217], v[62:65]
	v_mfma_f32_16x16x32_bf16 v[58:61], v[190:193], v[214:217], v[58:61]
	v_mfma_f32_16x16x32_bf16 v[46:49], v[152:155], v[222:225], v[46:49]
	v_mfma_f32_16x16x32_bf16 v[42:45], v[190:193], v[222:225], v[42:45]
	v_mfma_f32_16x16x32_bf16 v[30:33], v[152:155], v[234:237], v[30:33]
	v_mfma_f32_16x16x32_bf16 v[26:29], v[190:193], v[234:237], v[26:29]
	v_mfma_f32_16x16x32_bf16 v[14:17], v[152:155], v[242:245], v[14:17]
	v_mfma_f32_16x16x32_bf16 v[10:13], v[190:193], v[242:245], v[10:13]
	v_mfma_f32_16x16x32_bf16 v[54:57], v[194:197], v[210:213], v[54:57]
	v_mfma_f32_16x16x32_bf16 v[50:53], v[202:205], v[210:213], v[50:53]
	v_mfma_f32_16x16x32_bf16 v[38:41], v[194:197], v[218:221], v[38:41]
	v_mfma_f32_16x16x32_bf16 v[34:37], v[202:205], v[218:221], v[34:37]
	v_mfma_f32_16x16x32_bf16 v[22:25], v[194:197], v[226:229], v[22:25]
	v_mfma_f32_16x16x32_bf16 v[18:21], v[202:205], v[226:229], v[18:21]
	v_mfma_f32_16x16x32_bf16 v[6:9], v[194:197], v[238:241], v[6:9]
	v_mfma_f32_16x16x32_bf16 v[2:5], v[202:205], v[238:241], v[2:5]
	v_mfma_f32_16x16x32_bf16 v[54:57], v[198:201], v[214:217], v[54:57]
	v_mfma_f32_16x16x32_bf16 v[50:53], v[206:209], v[214:217], v[50:53]
	v_mfma_f32_16x16x32_bf16 v[38:41], v[198:201], v[222:225], v[38:41]
	v_mfma_f32_16x16x32_bf16 v[34:37], v[206:209], v[222:225], v[34:37]
	v_mfma_f32_16x16x32_bf16 v[22:25], v[198:201], v[234:237], v[22:25]
	v_mfma_f32_16x16x32_bf16 v[18:21], v[206:209], v[234:237], v[18:21]
	v_mfma_f32_16x16x32_bf16 v[6:9], v[198:201], v[242:245], v[6:9]
	v_mfma_f32_16x16x32_bf16 v[2:5], v[206:209], v[242:245], v[2:5]
	s_setprio 0
	s_barrier
	s_add_i32 s64, 0, 0x18000
	v_add_u32_e32 v0, s64, v169
	s_add_i32 s65, 0, 0x1c000
	ds_read_b128 v[148:151], v0
	ds_read_b128 v[152:155], v0 offset:1024
	ds_read_b128 v[156:159], v0 offset:2048
	ds_read_b128 v[190:193], v0 offset:3072
	v_add_u32_e32 v0, s65, v169
	ds_read_b128 v[194:197], v0
	ds_read_b128 v[198:201], v0 offset:1024
	ds_read_b128 v[202:205], v0 offset:2048
	ds_read_b128 v[206:209], v0 offset:3072
	s_add_u32 s48, s60, 0xb0000
	s_addc_u32 s49, s61, 0
	s_mov_b32 m0, s81
	ds_read_b128 v[210:213], v188 offset:32768
	ds_read_b128 v[214:217], v188 offset:33792
	ds_read_b128 v[218:221], v188 offset:34816
	ds_read_b128 v[222:225], v188 offset:35840
	ds_read_b128 v[226:229], v188 offset:36864
	ds_read_b128 v[234:237], v188 offset:37888
	ds_read_b128 v[238:241], v188 offset:38912
	ds_read_b128 v[242:245], v188 offset:39936
	global_load_lds_dwordx4 v134, s[48:49]
	s_mov_b32 m0, s82
	s_nop 0
	global_load_lds_dwordx4 v138, s[48:49]
	s_waitcnt vmcnt(8)
	s_waitcnt lgkmcnt(0)
	s_barrier
	s_setprio 1
	s_waitcnt lgkmcnt(0)
	v_mfma_f32_16x16x32_bf16 v[126:129], v[148:151], v[210:213], v[126:129]
	v_mfma_f32_16x16x32_bf16 v[122:125], v[156:159], v[210:213], v[122:125]
	v_mfma_f32_16x16x32_bf16 v[110:113], v[148:151], v[218:221], v[110:113]
	v_mfma_f32_16x16x32_bf16 v[106:109], v[156:159], v[218:221], v[106:109]
	v_mfma_f32_16x16x32_bf16 v[94:97], v[148:151], v[226:229], v[94:97]
	v_mfma_f32_16x16x32_bf16 v[90:93], v[156:159], v[226:229], v[90:93]
	v_mfma_f32_16x16x32_bf16 v[78:81], v[148:151], v[238:241], v[78:81]
	v_mfma_f32_16x16x32_bf16 v[74:77], v[156:159], v[238:241], v[74:77]
	v_mfma_f32_16x16x32_bf16 v[126:129], v[152:155], v[214:217], v[126:129]
	v_mfma_f32_16x16x32_bf16 v[122:125], v[190:193], v[214:217], v[122:125]
	v_mfma_f32_16x16x32_bf16 v[110:113], v[152:155], v[222:225], v[110:113]
	v_mfma_f32_16x16x32_bf16 v[106:109], v[190:193], v[222:225], v[106:109]
	v_mfma_f32_16x16x32_bf16 v[94:97], v[152:155], v[234:237], v[94:97]
	v_mfma_f32_16x16x32_bf16 v[90:93], v[190:193], v[234:237], v[90:93]
	v_mfma_f32_16x16x32_bf16 v[78:81], v[152:155], v[242:245], v[78:81]
	v_mfma_f32_16x16x32_bf16 v[74:77], v[190:193], v[242:245], v[74:77]
	v_mfma_f32_16x16x32_bf16 v[118:121], v[194:197], v[210:213], v[118:121]
	v_mfma_f32_16x16x32_bf16 v[114:117], v[202:205], v[210:213], v[114:117]
	v_mfma_f32_16x16x32_bf16 v[102:105], v[194:197], v[218:221], v[102:105]
	v_mfma_f32_16x16x32_bf16 v[98:101], v[202:205], v[218:221], v[98:101]
	v_mfma_f32_16x16x32_bf16 v[86:89], v[194:197], v[226:229], v[86:89]
	v_mfma_f32_16x16x32_bf16 v[82:85], v[202:205], v[226:229], v[82:85]
	v_mfma_f32_16x16x32_bf16 v[70:73], v[194:197], v[238:241], v[70:73]
	v_mfma_f32_16x16x32_bf16 v[66:69], v[202:205], v[238:241], v[66:69]
	v_mfma_f32_16x16x32_bf16 v[118:121], v[198:201], v[214:217], v[118:121]
	v_mfma_f32_16x16x32_bf16 v[114:117], v[206:209], v[214:217], v[114:117]
	v_mfma_f32_16x16x32_bf16 v[102:105], v[198:201], v[222:225], v[102:105]
	v_mfma_f32_16x16x32_bf16 v[98:101], v[206:209], v[222:225], v[98:101]
	v_mfma_f32_16x16x32_bf16 v[86:89], v[198:201], v[234:237], v[86:89]
	v_mfma_f32_16x16x32_bf16 v[82:85], v[206:209], v[234:237], v[82:85]
	v_mfma_f32_16x16x32_bf16 v[70:73], v[198:201], v[242:245], v[70:73]
	v_mfma_f32_16x16x32_bf16 v[66:69], v[206:209], v[242:245], v[66:69]
	s_setprio 0
	s_barrier
	s_add_i32 s48, s64, s78
	s_add_u32 s98, s98, s18
	s_addc_u32 s99, s99, s19
	s_mov_b32 m0, s48
	ds_read_b128 v[210:213], v188 offset:49152
	ds_read_b128 v[214:217], v188 offset:50176
	ds_read_b128 v[218:221], v188 offset:51200
	ds_read_b128 v[222:225], v188 offset:52224
	ds_read_b128 v[226:229], v188 offset:53248
	ds_read_b128 v[234:237], v188 offset:54272
	ds_read_b128 v[238:241], v188 offset:55296
	ds_read_b128 v[242:245], v188 offset:56320
	global_load_lds_dwordx4 v136, s[98:99]
	s_add_i32 m0, s48, 0x2000
	s_add_u32 s48, s58, 0xb0080
	s_addc_u32 s49, s59, 0
	s_add_i32 s58, s65, s78
	global_load_lds_dwordx4 v140, s[98:99]
	s_mov_b32 m0, s58
	s_nop 0
	global_load_lds_dwordx4 v136, s[48:49]
	s_add_i32 m0, s58, 0x2000
	s_nop 0
	global_load_lds_dwordx4 v140, s[48:49]
	s_add_u32 s100, s100, s18
	s_addc_u32 s101, s101, s19
	s_mov_b32 m0, s85
	s_nop 0
	global_load_lds_dwordx4 v134, s[100:101]
	s_mov_b32 m0, s86
	s_nop 0
	global_load_lds_dwordx4 v138, s[100:101]
	s_waitcnt vmcnt(8)
	s_waitcnt lgkmcnt(0)
	s_barrier
	s_setprio 1
	s_waitcnt lgkmcnt(0)
	v_mfma_f32_16x16x32_bf16 v[62:65], v[148:151], v[210:213], v[62:65]
	v_mfma_f32_16x16x32_bf16 v[58:61], v[156:159], v[210:213], v[58:61]
	v_mfma_f32_16x16x32_bf16 v[46:49], v[148:151], v[218:221], v[46:49]
	v_mfma_f32_16x16x32_bf16 v[42:45], v[156:159], v[218:221], v[42:45]
	v_mfma_f32_16x16x32_bf16 v[30:33], v[148:151], v[226:229], v[30:33]
	v_mfma_f32_16x16x32_bf16 v[26:29], v[156:159], v[226:229], v[26:29]
	v_mfma_f32_16x16x32_bf16 v[14:17], v[148:151], v[238:241], v[14:17]
	v_mfma_f32_16x16x32_bf16 v[10:13], v[156:159], v[238:241], v[10:13]
	v_mfma_f32_16x16x32_bf16 v[62:65], v[152:155], v[214:217], v[62:65]
	v_mfma_f32_16x16x32_bf16 v[58:61], v[190:193], v[214:217], v[58:61]
	v_mfma_f32_16x16x32_bf16 v[46:49], v[152:155], v[222:225], v[46:49]
	v_mfma_f32_16x16x32_bf16 v[42:45], v[190:193], v[222:225], v[42:45]
	v_mfma_f32_16x16x32_bf16 v[30:33], v[152:155], v[234:237], v[30:33]
	v_mfma_f32_16x16x32_bf16 v[26:29], v[190:193], v[234:237], v[26:29]
	v_mfma_f32_16x16x32_bf16 v[14:17], v[152:155], v[242:245], v[14:17]
	v_mfma_f32_16x16x32_bf16 v[10:13], v[190:193], v[242:245], v[10:13]
	v_mfma_f32_16x16x32_bf16 v[54:57], v[194:197], v[210:213], v[54:57]
	v_mfma_f32_16x16x32_bf16 v[50:53], v[202:205], v[210:213], v[50:53]
	v_mfma_f32_16x16x32_bf16 v[38:41], v[194:197], v[218:221], v[38:41]
	v_mfma_f32_16x16x32_bf16 v[34:37], v[202:205], v[218:221], v[34:37]
	v_mfma_f32_16x16x32_bf16 v[22:25], v[194:197], v[226:229], v[22:25]
	v_mfma_f32_16x16x32_bf16 v[18:21], v[202:205], v[226:229], v[18:21]
	v_mfma_f32_16x16x32_bf16 v[6:9], v[194:197], v[238:241], v[6:9]
	v_mfma_f32_16x16x32_bf16 v[2:5], v[202:205], v[238:241], v[2:5]
	v_mfma_f32_16x16x32_bf16 v[54:57], v[198:201], v[214:217], v[54:57]
	v_mfma_f32_16x16x32_bf16 v[50:53], v[206:209], v[214:217], v[50:53]
	v_mfma_f32_16x16x32_bf16 v[38:41], v[198:201], v[222:225], v[38:41]
	v_mfma_f32_16x16x32_bf16 v[34:37], v[206:209], v[222:225], v[34:37]
	v_mfma_f32_16x16x32_bf16 v[22:25], v[198:201], v[234:237], v[22:25]
	v_mfma_f32_16x16x32_bf16 v[18:21], v[206:209], v[234:237], v[18:21]
	v_mfma_f32_16x16x32_bf16 v[6:9], v[198:201], v[242:245], v[6:9]
	v_mfma_f32_16x16x32_bf16 v[2:5], v[206:209], v[242:245], v[2:5]
	s_setprio 0
	s_barrier
	s_add_i32 s63, s63, 2
	s_add_u32 s16, s16, 0x100
	s_addc_u32 s55, s55, 0
	s_cmp_gt_u32 s63, 41
	s_mov_b64 s[48:49], s[56:57]
	s_cbranch_scc0 .LBB0_1636
	s_and_b64 vcc, exec, s[42:43]
	s_cbranch_vccz .LBB0_1640
	s_barrier
	s_andn2_b64 vcc, exec, s[24:25]
	s_cbranch_vccz .LBB0_1641

.LBB0_2108:
	s_add_u32 s48, s8, 0xfffc0080
	s_addc_u32 s49, s9, -1
	s_add_i32 s85, 0, 0x10000
	s_cmp_eq_u32 s71, 12
	s_cselect_b32 s65, s7, s49
	s_cselect_b32 s64, s57, s48
	v_add_u32_e32 v128, s85, v173
	s_cselect_b32 s49, s59, s70
	s_cselect_b32 s48, s68, s69
	s_add_i32 s87, 0, 0x14000
	ds_read_b128 v[174:177], v128
	ds_read_b128 v[180:183], v128 offset:1024
	ds_read_b128 v[184:187], v128 offset:2048
	ds_read_b128 v[188:191], v128 offset:3072
	v_add_u32_e32 v128, s87, v173
	ds_read_b128 v[192:195], v128
	ds_read_b128 v[196:199], v128 offset:1024
	ds_read_b128 v[202:205], v128 offset:2048
	ds_read_b128 v[206:209], v128 offset:3072
	s_add_i32 m0, s67, 0xc000
	ds_read_b128 v[216:219], v200
	ds_read_b128 v[220:223], v200 offset:1024
	ds_read_b128 v[224:227], v200 offset:2048
	ds_read_b128 v[228:231], v200 offset:3072
	ds_read_b128 v[234:237], v200 offset:4096
	ds_read_b128 v[238:241], v200 offset:5120
	ds_read_b128 v[242:245], v200 offset:6144
	ds_read_b128 v[246:249], v200 offset:7168
	global_load_lds_dwordx4 v148, s[8:9]
	s_add_i32 m0, s67, 0xe000
	s_nop 0
	global_load_lds_dwordx4 v150, s[8:9]
	s_waitcnt vmcnt(8)
	s_waitcnt lgkmcnt(0)
	s_barrier
	s_setprio 1
	s_waitcnt lgkmcnt(0)
	v_mfma_f32_16x16x32_bf16 v[124:127], v[174:177], v[216:219], v[124:127]
	v_mfma_f32_16x16x32_bf16 v[120:123], v[184:187], v[216:219], v[120:123]
	v_mfma_f32_16x16x32_bf16 v[108:111], v[174:177], v[224:227], v[108:111]
	v_mfma_f32_16x16x32_bf16 v[104:107], v[184:187], v[224:227], v[104:107]
	v_mfma_f32_16x16x32_bf16 v[92:95], v[174:177], v[234:237], v[92:95]
	v_mfma_f32_16x16x32_bf16 v[88:91], v[184:187], v[234:237], v[88:91]
	v_mfma_f32_16x16x32_bf16 v[76:79], v[174:177], v[242:245], v[76:79]
	v_mfma_f32_16x16x32_bf16 v[72:75], v[184:187], v[242:245], v[72:75]
	v_mfma_f32_16x16x32_bf16 v[124:127], v[180:183], v[220:223], v[124:127]
	v_mfma_f32_16x16x32_bf16 v[120:123], v[188:191], v[220:223], v[120:123]
	v_mfma_f32_16x16x32_bf16 v[108:111], v[180:183], v[228:231], v[108:111]
	v_mfma_f32_16x16x32_bf16 v[104:107], v[188:191], v[228:231], v[104:107]
	v_mfma_f32_16x16x32_bf16 v[92:95], v[180:183], v[238:241], v[92:95]
	v_mfma_f32_16x16x32_bf16 v[88:91], v[188:191], v[238:241], v[88:91]
	v_mfma_f32_16x16x32_bf16 v[76:79], v[180:183], v[246:249], v[76:79]
	v_mfma_f32_16x16x32_bf16 v[72:75], v[188:191], v[246:249], v[72:75]
	v_mfma_f32_16x16x32_bf16 v[116:119], v[192:195], v[216:219], v[116:119]
	v_mfma_f32_16x16x32_bf16 v[112:115], v[202:205], v[216:219], v[112:115]
	v_mfma_f32_16x16x32_bf16 v[100:103], v[192:195], v[224:227], v[100:103]
	v_mfma_f32_16x16x32_bf16 v[96:99], v[202:205], v[224:227], v[96:99]
	v_mfma_f32_16x16x32_bf16 v[84:87], v[192:195], v[234:237], v[84:87]
	v_mfma_f32_16x16x32_bf16 v[80:83], v[202:205], v[234:237], v[80:83]
	v_mfma_f32_16x16x32_bf16 v[68:71], v[192:195], v[242:245], v[68:71]
	v_mfma_f32_16x16x32_bf16 v[64:67], v[202:205], v[242:245], v[64:67]
	v_mfma_f32_16x16x32_bf16 v[116:119], v[196:199], v[220:223], v[116:119]
	v_mfma_f32_16x16x32_bf16 v[112:115], v[206:209], v[220:223], v[112:115]
	v_mfma_f32_16x16x32_bf16 v[100:103], v[196:199], v[228:231], v[100:103]
	v_mfma_f32_16x16x32_bf16 v[96:99], v[206:209], v[228:231], v[96:99]
	v_mfma_f32_16x16x32_bf16 v[84:87], v[196:199], v[238:241], v[84:87]
	v_mfma_f32_16x16x32_bf16 v[80:83], v[206:209], v[238:241], v[80:83]
	v_mfma_f32_16x16x32_bf16 v[68:71], v[196:199], v[246:249], v[68:71]
	v_mfma_f32_16x16x32_bf16 v[64:67], v[206:209], v[246:249], v[64:67]
	s_setprio 0
	s_barrier
	s_add_i32 s85, s85, s77
	s_mov_b64 s[98:99], s[48:49]
	s_mov_b32 m0, s85
	ds_read_b128 v[216:219], v200 offset:16384
	ds_read_b128 v[220:223], v200 offset:17408
	ds_read_b128 v[224:227], v200 offset:18432
	ds_read_b128 v[228:231], v200 offset:19456
	ds_read_b128 v[234:237], v200 offset:20480
	ds_read_b128 v[238:241], v200 offset:21504
	ds_read_b128 v[242:245], v200 offset:22528
	ds_read_b128 v[246:249], v200 offset:23552
	global_load_lds_dwordx4 v136, s[48:49]
	s_add_i32 m0, s85, 0x2000
	s_add_u32 s88, s48, 0x40000
	s_addc_u32 s89, s49, 0
	s_add_i32 s85, s87, s77
	global_load_lds_dwordx4 v140, s[48:49]
	s_mov_b32 m0, s85
	s_mov_b64 s[100:101], s[64:65]
	global_load_lds_dwordx4 v136, s[88:89]
	s_add_i32 m0, s85, 0x2000
	s_nop 0
	global_load_lds_dwordx4 v140, s[88:89]
	s_mov_b32 m0, s67
	s_nop 0
	global_load_lds_dwordx4 v134, s[64:65]
	s_mov_b32 m0, s78
	s_nop 0
	global_load_lds_dwordx4 v138, s[64:65]
	s_waitcnt vmcnt(8)
	s_waitcnt lgkmcnt(0)
	s_barrier
	s_setprio 1
	s_waitcnt lgkmcnt(0)
	v_mfma_f32_16x16x32_bf16 v[60:63], v[174:177], v[216:219], v[60:63]
	v_mfma_f32_16x16x32_bf16 v[56:59], v[184:187], v[216:219], v[56:59]
	v_mfma_f32_16x16x32_bf16 v[44:47], v[174:177], v[224:227], v[44:47]
	v_mfma_f32_16x16x32_bf16 v[40:43], v[184:187], v[224:227], v[40:43]
	v_mfma_f32_16x16x32_bf16 v[28:31], v[174:177], v[234:237], v[28:31]
	v_mfma_f32_16x16x32_bf16 v[24:27], v[184:187], v[234:237], v[24:27]
	v_mfma_f32_16x16x32_bf16 v[12:15], v[174:177], v[242:245], v[12:15]
	v_mfma_f32_16x16x32_bf16 v[8:11], v[184:187], v[242:245], v[8:11]
	v_mfma_f32_16x16x32_bf16 v[60:63], v[180:183], v[220:223], v[60:63]
	v_mfma_f32_16x16x32_bf16 v[56:59], v[188:191], v[220:223], v[56:59]
	v_mfma_f32_16x16x32_bf16 v[44:47], v[180:183], v[228:231], v[44:47]
	v_mfma_f32_16x16x32_bf16 v[40:43], v[188:191], v[228:231], v[40:43]
	v_mfma_f32_16x16x32_bf16 v[28:31], v[180:183], v[238:241], v[28:31]
	v_mfma_f32_16x16x32_bf16 v[24:27], v[188:191], v[238:241], v[24:27]
	v_mfma_f32_16x16x32_bf16 v[12:15], v[180:183], v[246:249], v[12:15]
	v_mfma_f32_16x16x32_bf16 v[8:11], v[188:191], v[246:249], v[8:11]
	v_mfma_f32_16x16x32_bf16 v[52:55], v[192:195], v[216:219], v[52:55]
	v_mfma_f32_16x16x32_bf16 v[48:51], v[202:205], v[216:219], v[48:51]
	v_mfma_f32_16x16x32_bf16 v[36:39], v[192:195], v[224:227], v[36:39]
	v_mfma_f32_16x16x32_bf16 v[32:35], v[202:205], v[224:227], v[32:35]
	v_mfma_f32_16x16x32_bf16 v[20:23], v[192:195], v[234:237], v[20:23]
	v_mfma_f32_16x16x32_bf16 v[16:19], v[202:205], v[234:237], v[16:19]
	v_mfma_f32_16x16x32_bf16 v[4:7], v[192:195], v[242:245], v[4:7]
	v_mfma_f32_16x16x32_bf16 v[0:3], v[202:205], v[242:245], v[0:3]
	v_mfma_f32_16x16x32_bf16 v[52:55], v[196:199], v[220:223], v[52:55]
	v_mfma_f32_16x16x32_bf16 v[48:51], v[206:209], v[220:223], v[48:51]
	v_mfma_f32_16x16x32_bf16 v[36:39], v[196:199], v[228:231], v[36:39]
	v_mfma_f32_16x16x32_bf16 v[32:35], v[206:209], v[228:231], v[32:35]
	v_mfma_f32_16x16x32_bf16 v[20:23], v[196:199], v[238:241], v[20:23]
	v_mfma_f32_16x16x32_bf16 v[16:19], v[206:209], v[238:241], v[16:19]
	v_mfma_f32_16x16x32_bf16 v[4:7], v[196:199], v[246:249], v[4:7]
	v_mfma_f32_16x16x32_bf16 v[0:3], v[206:209], v[246:249], v[0:3]
	s_setprio 0
	s_barrier
	v_add_u32_e32 v128, s0, v173
	s_add_i32 s85, 0, 0x1c000
	ds_read_b128 v[174:177], v128
	ds_read_b128 v[180:183], v128 offset:1024
	ds_read_b128 v[184:187], v128 offset:2048
	ds_read_b128 v[188:191], v128 offset:3072
	v_add_u32_e32 v128, s85, v173
	ds_read_b128 v[192:195], v128
	ds_read_b128 v[196:199], v128 offset:1024
	ds_read_b128 v[202:205], v128 offset:2048
	ds_read_b128 v[206:209], v128 offset:3072
	s_add_u32 s64, s64, 0x40000
	s_addc_u32 s65, s65, 0
	s_mov_b32 m0, s79
	ds_read_b128 v[216:219], v200 offset:32768
	ds_read_b128 v[220:223], v200 offset:33792
	ds_read_b128 v[224:227], v200 offset:34816
	ds_read_b128 v[228:231], v200 offset:35840
	ds_read_b128 v[234:237], v200 offset:36864
	ds_read_b128 v[238:241], v200 offset:37888
	ds_read_b128 v[242:245], v200 offset:38912
	ds_read_b128 v[246:249], v200 offset:39936
	global_load_lds_dwordx4 v134, s[64:65]
	s_mov_b32 m0, s80
	s_nop 0
	global_load_lds_dwordx4 v138, s[64:65]
	s_waitcnt vmcnt(8)
	s_waitcnt lgkmcnt(0)
	s_barrier
	s_setprio 1
	s_waitcnt lgkmcnt(0)
	v_mfma_f32_16x16x32_bf16 v[124:127], v[174:177], v[216:219], v[124:127]
	v_mfma_f32_16x16x32_bf16 v[120:123], v[184:187], v[216:219], v[120:123]
	v_mfma_f32_16x16x32_bf16 v[108:111], v[174:177], v[224:227], v[108:111]
	v_mfma_f32_16x16x32_bf16 v[104:107], v[184:187], v[224:227], v[104:107]
	v_mfma_f32_16x16x32_bf16 v[92:95], v[174:177], v[234:237], v[92:95]
	v_mfma_f32_16x16x32_bf16 v[88:91], v[184:187], v[234:237], v[88:91]
	v_mfma_f32_16x16x32_bf16 v[76:79], v[174:177], v[242:245], v[76:79]
	v_mfma_f32_16x16x32_bf16 v[72:75], v[184:187], v[242:245], v[72:75]
	v_mfma_f32_16x16x32_bf16 v[124:127], v[180:183], v[220:223], v[124:127]
	v_mfma_f32_16x16x32_bf16 v[120:123], v[188:191], v[220:223], v[120:123]
	v_mfma_f32_16x16x32_bf16 v[108:111], v[180:183], v[228:231], v[108:111]
	v_mfma_f32_16x16x32_bf16 v[104:107], v[188:191], v[228:231], v[104:107]
	v_mfma_f32_16x16x32_bf16 v[92:95], v[180:183], v[238:241], v[92:95]
	v_mfma_f32_16x16x32_bf16 v[88:91], v[188:191], v[238:241], v[88:91]
	v_mfma_f32_16x16x32_bf16 v[76:79], v[180:183], v[246:249], v[76:79]
	v_mfma_f32_16x16x32_bf16 v[72:75], v[188:191], v[246:249], v[72:75]
	v_mfma_f32_16x16x32_bf16 v[116:119], v[192:195], v[216:219], v[116:119]
	v_mfma_f32_16x16x32_bf16 v[112:115], v[202:205], v[216:219], v[112:115]
	v_mfma_f32_16x16x32_bf16 v[100:103], v[192:195], v[224:227], v[100:103]
	v_mfma_f32_16x16x32_bf16 v[96:99], v[202:205], v[224:227], v[96:99]
	v_mfma_f32_16x16x32_bf16 v[84:87], v[192:195], v[234:237], v[84:87]
	v_mfma_f32_16x16x32_bf16 v[80:83], v[202:205], v[234:237], v[80:83]
	v_mfma_f32_16x16x32_bf16 v[68:71], v[192:195], v[242:245], v[68:71]
	v_mfma_f32_16x16x32_bf16 v[64:67], v[202:205], v[242:245], v[64:67]
	v_mfma_f32_16x16x32_bf16 v[116:119], v[196:199], v[220:223], v[116:119]
	v_mfma_f32_16x16x32_bf16 v[112:115], v[206:209], v[220:223], v[112:115]
	v_mfma_f32_16x16x32_bf16 v[100:103], v[196:199], v[228:231], v[100:103]
	v_mfma_f32_16x16x32_bf16 v[96:99], v[206:209], v[228:231], v[96:99]
	v_mfma_f32_16x16x32_bf16 v[84:87], v[196:199], v[238:241], v[84:87]
	v_mfma_f32_16x16x32_bf16 v[80:83], v[206:209], v[238:241], v[80:83]
	v_mfma_f32_16x16x32_bf16 v[68:71], v[196:199], v[246:249], v[68:71]
	v_mfma_f32_16x16x32_bf16 v[64:67], v[206:209], v[246:249], v[64:67]
	s_setprio 0
	s_barrier
	s_add_i32 s64, s0, s77
	s_add_u32 s98, s98, s14
	s_addc_u32 s99, s99, s15
	s_mov_b32 m0, s64
	ds_read_b128 v[216:219], v200 offset:49152
	ds_read_b128 v[220:223], v200 offset:50176
	ds_read_b128 v[224:227], v200 offset:51200
	ds_read_b128 v[228:231], v200 offset:52224
	ds_read_b128 v[234:237], v200 offset:53248
	ds_read_b128 v[238:241], v200 offset:54272
	ds_read_b128 v[242:245], v200 offset:55296
	ds_read_b128 v[246:249], v200 offset:56320
	global_load_lds_dwordx4 v136, s[98:99]
	s_add_i32 m0, s64, 0x2000
	s_add_u32 s48, s48, 0x40080
	s_addc_u32 s49, s49, 0
	s_add_i32 s64, s85, s77
	global_load_lds_dwordx4 v140, s[98:99]
	s_mov_b32 m0, s64
	s_nop 0
	global_load_lds_dwordx4 v136, s[48:49]
	s_add_i32 m0, s64, 0x2000
	s_nop 0
	global_load_lds_dwordx4 v140, s[48:49]
	s_add_u32 s100, s100, s14
	s_addc_u32 s101, s101, s15
	s_mov_b32 m0, s81
	s_nop 0
	global_load_lds_dwordx4 v134, s[100:101]
	s_mov_b32 m0, s82
	s_nop 0
	global_load_lds_dwordx4 v138, s[100:101]
	s_waitcnt vmcnt(8)
	s_waitcnt lgkmcnt(0)
	s_barrier
	s_setprio 1
	s_waitcnt lgkmcnt(0)
	v_mfma_f32_16x16x32_bf16 v[60:63], v[174:177], v[216:219], v[60:63]
	v_mfma_f32_16x16x32_bf16 v[56:59], v[184:187], v[216:219], v[56:59]
	v_mfma_f32_16x16x32_bf16 v[44:47], v[174:177], v[224:227], v[44:47]
	v_mfma_f32_16x16x32_bf16 v[40:43], v[184:187], v[224:227], v[40:43]
	v_mfma_f32_16x16x32_bf16 v[28:31], v[174:177], v[234:237], v[28:31]
	v_mfma_f32_16x16x32_bf16 v[24:27], v[184:187], v[234:237], v[24:27]
	v_mfma_f32_16x16x32_bf16 v[12:15], v[174:177], v[242:245], v[12:15]
	v_mfma_f32_16x16x32_bf16 v[8:11], v[184:187], v[242:245], v[8:11]
	v_mfma_f32_16x16x32_bf16 v[60:63], v[180:183], v[220:223], v[60:63]
	v_mfma_f32_16x16x32_bf16 v[56:59], v[188:191], v[220:223], v[56:59]
	v_mfma_f32_16x16x32_bf16 v[44:47], v[180:183], v[228:231], v[44:47]
	v_mfma_f32_16x16x32_bf16 v[40:43], v[188:191], v[228:231], v[40:43]
	v_mfma_f32_16x16x32_bf16 v[28:31], v[180:183], v[238:241], v[28:31]
	v_mfma_f32_16x16x32_bf16 v[24:27], v[188:191], v[238:241], v[24:27]
	v_mfma_f32_16x16x32_bf16 v[12:15], v[180:183], v[246:249], v[12:15]
	v_mfma_f32_16x16x32_bf16 v[8:11], v[188:191], v[246:249], v[8:11]
	v_mfma_f32_16x16x32_bf16 v[52:55], v[192:195], v[216:219], v[52:55]
	v_mfma_f32_16x16x32_bf16 v[48:51], v[202:205], v[216:219], v[48:51]
	v_mfma_f32_16x16x32_bf16 v[36:39], v[192:195], v[224:227], v[36:39]
	v_mfma_f32_16x16x32_bf16 v[32:35], v[202:205], v[224:227], v[32:35]
	v_mfma_f32_16x16x32_bf16 v[20:23], v[192:195], v[234:237], v[20:23]
	v_mfma_f32_16x16x32_bf16 v[16:19], v[202:205], v[234:237], v[16:19]
	v_mfma_f32_16x16x32_bf16 v[4:7], v[192:195], v[242:245], v[4:7]
	v_mfma_f32_16x16x32_bf16 v[0:3], v[202:205], v[242:245], v[0:3]
	v_mfma_f32_16x16x32_bf16 v[52:55], v[196:199], v[220:223], v[52:55]
	v_mfma_f32_16x16x32_bf16 v[48:51], v[206:209], v[220:223], v[48:51]
	v_mfma_f32_16x16x32_bf16 v[36:39], v[196:199], v[228:231], v[36:39]
	v_mfma_f32_16x16x32_bf16 v[32:35], v[206:209], v[228:231], v[32:35]
	v_mfma_f32_16x16x32_bf16 v[20:23], v[196:199], v[238:241], v[20:23]
	v_mfma_f32_16x16x32_bf16 v[16:19], v[206:209], v[238:241], v[16:19]
	v_mfma_f32_16x16x32_bf16 v[4:7], v[196:199], v[246:249], v[4:7]
	v_mfma_f32_16x16x32_bf16 v[0:3], v[206:209], v[246:249], v[0:3]
	s_setprio 0
	s_barrier
	s_add_i32 s71, s71, 2
	s_add_u32 s8, s8, 0x100
	s_addc_u32 s9, s9, 0
	s_add_u32 s69, s69, 0x100
	s_addc_u32 s70, s70, 0
	s_cmp_gt_u32 s71, 13
	s_cbranch_scc0 .LBB0_2108
	s_and_b64 vcc, exec, s[54:55]
	s_cbranch_vccz .LBB0_2111
	s_barrier

.LBB0_2189:
	s_add_u32 s68, s48, 0xfffe0080
	s_addc_u32 s69, s49, -1
	s_add_i32 s78, 0, 0x10000
	s_cmp_eq_u32 vcc_lo, 4
	s_cselect_b32 s73, s1, s69
	s_cselect_b32 s72, s7, s68
	s_cselect_b32 s69, s61, s75
	s_cselect_b32 s68, s63, s74
	s_add_i32 vcc_hi, 0, 0x14000
	v_add_u32_e32 v140, s78, v225
	v_add_u32_e32 v144, vcc_hi, v225
	ds_read_b128 v[128:131], v140
	ds_read_b128 v[132:135], v140 offset:1024
	ds_read_b128 v[136:139], v140 offset:2048
	ds_read_b128 v[140:143], v140 offset:3072
	ds_read_b128 v[172:175], v144
	ds_read_b128 v[176:179], v144 offset:1024
	ds_read_b128 v[180:183], v144 offset:2048
	ds_read_b128 v[184:187], v144 offset:3072
	s_add_i32 m0, s18, 0xc000
	ds_read_b128 v[188:191], v228
	ds_read_b128 v[192:195], v228 offset:1024
	ds_read_b128 v[196:199], v228 offset:2048
	ds_read_b128 v[200:203], v228 offset:3072
	ds_read_b128 v[204:207], v228 offset:4096
	ds_read_b128 v[208:211], v228 offset:5120
	ds_read_b128 v[234:237], v228 offset:6144
	ds_read_b128 v[238:241], v228 offset:7168
	global_load_lds_dwordx4 v166, s[48:49]
	s_add_i32 m0, s18, 0xe000
	s_nop 0
	global_load_lds_dwordx4 v168, s[48:49]
	s_waitcnt vmcnt(8)
	s_waitcnt lgkmcnt(0)
	s_barrier
	s_setprio 1
	s_waitcnt lgkmcnt(0)
	v_mfma_i32_16x16x64_i8 v[124:127], v[128:131], v[188:191], v[124:127]
	v_mfma_i32_16x16x64_i8 v[120:123], v[136:139], v[188:191], v[120:123]
	v_mfma_i32_16x16x64_i8 v[116:119], v[128:131], v[196:199], v[116:119]
	v_mfma_i32_16x16x64_i8 v[112:115], v[136:139], v[196:199], v[112:115]
	v_mfma_i32_16x16x64_i8 v[108:111], v[128:131], v[204:207], v[108:111]
	v_mfma_i32_16x16x64_i8 v[104:107], v[136:139], v[204:207], v[104:107]
	v_mfma_i32_16x16x64_i8 v[100:103], v[128:131], v[234:237], v[100:103]
	v_mfma_i32_16x16x64_i8 v[96:99], v[136:139], v[234:237], v[96:99]
	v_mfma_i32_16x16x64_i8 v[124:127], v[132:135], v[192:195], v[124:127]
	v_mfma_i32_16x16x64_i8 v[120:123], v[140:143], v[192:195], v[120:123]
	v_mfma_i32_16x16x64_i8 v[116:119], v[132:135], v[200:203], v[116:119]
	v_mfma_i32_16x16x64_i8 v[112:115], v[140:143], v[200:203], v[112:115]
	v_mfma_i32_16x16x64_i8 v[108:111], v[132:135], v[208:211], v[108:111]
	v_mfma_i32_16x16x64_i8 v[104:107], v[140:143], v[208:211], v[104:107]
	v_mfma_i32_16x16x64_i8 v[100:103], v[132:135], v[238:241], v[100:103]
	v_mfma_i32_16x16x64_i8 v[96:99], v[140:143], v[238:241], v[96:99]
	v_mfma_i32_16x16x64_i8 v[92:95], v[172:175], v[188:191], v[92:95]
	v_mfma_i32_16x16x64_i8 v[88:91], v[180:183], v[188:191], v[88:91]
	v_mfma_i32_16x16x64_i8 v[84:87], v[172:175], v[196:199], v[84:87]
	v_mfma_i32_16x16x64_i8 v[80:83], v[180:183], v[196:199], v[80:83]
	v_mfma_i32_16x16x64_i8 v[76:79], v[172:175], v[204:207], v[76:79]
	v_mfma_i32_16x16x64_i8 v[72:75], v[180:183], v[204:207], v[72:75]
	v_mfma_i32_16x16x64_i8 v[68:71], v[172:175], v[234:237], v[68:71]
	v_mfma_i32_16x16x64_i8 v[64:67], v[180:183], v[234:237], v[64:67]
	v_mfma_i32_16x16x64_i8 v[92:95], v[176:179], v[192:195], v[92:95]
	v_mfma_i32_16x16x64_i8 v[88:91], v[184:187], v[192:195], v[88:91]
	v_mfma_i32_16x16x64_i8 v[84:87], v[176:179], v[200:203], v[84:87]
	v_mfma_i32_16x16x64_i8 v[80:83], v[184:187], v[200:203], v[80:83]
	v_mfma_i32_16x16x64_i8 v[76:79], v[176:179], v[208:211], v[76:79]
	v_mfma_i32_16x16x64_i8 v[72:75], v[184:187], v[208:211], v[72:75]
	v_mfma_i32_16x16x64_i8 v[68:71], v[176:179], v[238:241], v[68:71]
	v_mfma_i32_16x16x64_i8 v[64:67], v[184:187], v[238:241], v[64:67]
	s_setprio 0
	s_barrier
	s_add_i32 s78, s78, s11
	s_mov_b64 s[98:99], s[68:69]
	s_mov_b32 m0, s78
	ds_read_b128 v[188:191], v228 offset:16384
	ds_read_b128 v[192:195], v228 offset:17408
	ds_read_b128 v[196:199], v228 offset:18432
	ds_read_b128 v[200:203], v228 offset:19456
	ds_read_b128 v[204:207], v228 offset:20480
	ds_read_b128 v[208:211], v228 offset:21504
	ds_read_b128 v[234:237], v228 offset:22528
	ds_read_b128 v[238:241], v228 offset:23552
	global_load_lds_dwordx4 v152, s[68:69]
	s_add_i32 m0, s78, 0x2000
	s_add_u32 s78, s68, 0x20000
	s_addc_u32 s79, s69, 0
	s_add_i32 vcc_hi, vcc_hi, s11
	global_load_lds_dwordx4 v156, s[68:69]
	s_mov_b32 m0, vcc_hi
	s_mov_b64 s[100:101], s[72:73]
	global_load_lds_dwordx4 v152, s[78:79]
	s_add_i32 m0, vcc_hi, 0x2000
	s_nop 0
	global_load_lds_dwordx4 v156, s[78:79]
	s_mov_b32 m0, s18
	s_nop 0
	global_load_lds_dwordx4 v150, s[72:73]
	s_mov_b32 m0, s19
	s_nop 0
	global_load_lds_dwordx4 v154, s[72:73]
	s_waitcnt vmcnt(8)
	s_waitcnt lgkmcnt(0)
	s_barrier
	s_setprio 1
	s_waitcnt lgkmcnt(0)
	v_mfma_i32_16x16x64_i8 v[60:63], v[128:131], v[188:191], v[60:63]
	v_mfma_i32_16x16x64_i8 v[56:59], v[136:139], v[188:191], v[56:59]
	v_mfma_i32_16x16x64_i8 v[52:55], v[128:131], v[196:199], v[52:55]
	v_mfma_i32_16x16x64_i8 v[48:51], v[136:139], v[196:199], v[48:51]
	v_mfma_i32_16x16x64_i8 v[44:47], v[128:131], v[204:207], v[44:47]
	v_mfma_i32_16x16x64_i8 v[40:43], v[136:139], v[204:207], v[40:43]
	v_mfma_i32_16x16x64_i8 v[36:39], v[128:131], v[234:237], v[36:39]
	v_mfma_i32_16x16x64_i8 v[32:35], v[136:139], v[234:237], v[32:35]
	v_mfma_i32_16x16x64_i8 v[60:63], v[132:135], v[192:195], v[60:63]
	v_mfma_i32_16x16x64_i8 v[56:59], v[140:143], v[192:195], v[56:59]
	v_mfma_i32_16x16x64_i8 v[52:55], v[132:135], v[200:203], v[52:55]
	v_mfma_i32_16x16x64_i8 v[48:51], v[140:143], v[200:203], v[48:51]
	v_mfma_i32_16x16x64_i8 v[44:47], v[132:135], v[208:211], v[44:47]
	v_mfma_i32_16x16x64_i8 v[40:43], v[140:143], v[208:211], v[40:43]
	v_mfma_i32_16x16x64_i8 v[36:39], v[132:135], v[238:241], v[36:39]
	v_mfma_i32_16x16x64_i8 v[32:35], v[140:143], v[238:241], v[32:35]
	v_mfma_i32_16x16x64_i8 v[28:31], v[172:175], v[188:191], v[28:31]
	v_mfma_i32_16x16x64_i8 v[24:27], v[180:183], v[188:191], v[24:27]
	v_mfma_i32_16x16x64_i8 v[20:23], v[172:175], v[196:199], v[20:23]
	v_mfma_i32_16x16x64_i8 v[16:19], v[180:183], v[196:199], v[16:19]
	v_mfma_i32_16x16x64_i8 v[12:15], v[172:175], v[204:207], v[12:15]
	v_mfma_i32_16x16x64_i8 v[8:11], v[180:183], v[204:207], v[8:11]
	v_mfma_i32_16x16x64_i8 v[4:7], v[172:175], v[234:237], v[4:7]
	v_mfma_i32_16x16x64_i8 v[0:3], v[180:183], v[234:237], v[0:3]
	v_mfma_i32_16x16x64_i8 v[28:31], v[176:179], v[192:195], v[28:31]
	v_mfma_i32_16x16x64_i8 v[24:27], v[184:187], v[192:195], v[24:27]
	v_mfma_i32_16x16x64_i8 v[20:23], v[176:179], v[200:203], v[20:23]
	v_mfma_i32_16x16x64_i8 v[16:19], v[184:187], v[200:203], v[16:19]
	v_mfma_i32_16x16x64_i8 v[12:15], v[176:179], v[208:211], v[12:15]
	v_mfma_i32_16x16x64_i8 v[8:11], v[184:187], v[208:211], v[8:11]
	v_mfma_i32_16x16x64_i8 v[4:7], v[176:179], v[238:241], v[4:7]
	v_mfma_i32_16x16x64_i8 v[0:3], v[184:187], v[238:241], v[0:3]
	s_setprio 0
	s_barrier
	s_add_i32 s78, 0, 0x1c000
	v_add_u32_e32 v140, s0, v225
	v_add_u32_e32 v144, s78, v225
	ds_read_b128 v[128:131], v140
	ds_read_b128 v[132:135], v140 offset:1024
	ds_read_b128 v[136:139], v140 offset:2048
	ds_read_b128 v[140:143], v140 offset:3072
	ds_read_b128 v[172:175], v144
	ds_read_b128 v[176:179], v144 offset:1024
	ds_read_b128 v[180:183], v144 offset:2048
	ds_read_b128 v[184:187], v144 offset:3072
	s_add_u32 s72, s72, 0x20000
	s_addc_u32 s73, s73, 0
	s_mov_b32 m0, s20
	ds_read_b128 v[188:191], v228 offset:32768
	ds_read_b128 v[192:195], v228 offset:33792
	ds_read_b128 v[196:199], v228 offset:34816
	ds_read_b128 v[200:203], v228 offset:35840
	ds_read_b128 v[204:207], v228 offset:36864
	ds_read_b128 v[208:211], v228 offset:37888
	ds_read_b128 v[234:237], v228 offset:38912
	ds_read_b128 v[238:241], v228 offset:39936
	global_load_lds_dwordx4 v150, s[72:73]
	s_mov_b32 m0, s21
	s_nop 0
	global_load_lds_dwordx4 v154, s[72:73]
	s_waitcnt vmcnt(8)
	s_waitcnt lgkmcnt(0)
	s_barrier
	s_setprio 1
	s_waitcnt lgkmcnt(0)
	v_mfma_i32_16x16x64_i8 v[124:127], v[128:131], v[188:191], v[124:127]
	v_mfma_i32_16x16x64_i8 v[120:123], v[136:139], v[188:191], v[120:123]
	v_mfma_i32_16x16x64_i8 v[116:119], v[128:131], v[196:199], v[116:119]
	v_mfma_i32_16x16x64_i8 v[112:115], v[136:139], v[196:199], v[112:115]
	v_mfma_i32_16x16x64_i8 v[108:111], v[128:131], v[204:207], v[108:111]
	v_mfma_i32_16x16x64_i8 v[104:107], v[136:139], v[204:207], v[104:107]
	v_mfma_i32_16x16x64_i8 v[100:103], v[128:131], v[234:237], v[100:103]
	v_mfma_i32_16x16x64_i8 v[96:99], v[136:139], v[234:237], v[96:99]
	v_mfma_i32_16x16x64_i8 v[124:127], v[132:135], v[192:195], v[124:127]
	v_mfma_i32_16x16x64_i8 v[120:123], v[140:143], v[192:195], v[120:123]
	v_mfma_i32_16x16x64_i8 v[116:119], v[132:135], v[200:203], v[116:119]
	v_mfma_i32_16x16x64_i8 v[112:115], v[140:143], v[200:203], v[112:115]
	v_mfma_i32_16x16x64_i8 v[108:111], v[132:135], v[208:211], v[108:111]
	v_mfma_i32_16x16x64_i8 v[104:107], v[140:143], v[208:211], v[104:107]
	v_mfma_i32_16x16x64_i8 v[100:103], v[132:135], v[238:241], v[100:103]
	v_mfma_i32_16x16x64_i8 v[96:99], v[140:143], v[238:241], v[96:99]
	v_mfma_i32_16x16x64_i8 v[92:95], v[172:175], v[188:191], v[92:95]
	v_mfma_i32_16x16x64_i8 v[88:91], v[180:183], v[188:191], v[88:91]
	v_mfma_i32_16x16x64_i8 v[84:87], v[172:175], v[196:199], v[84:87]
	v_mfma_i32_16x16x64_i8 v[80:83], v[180:183], v[196:199], v[80:83]
	v_mfma_i32_16x16x64_i8 v[76:79], v[172:175], v[204:207], v[76:79]
	v_mfma_i32_16x16x64_i8 v[72:75], v[180:183], v[204:207], v[72:75]
	v_mfma_i32_16x16x64_i8 v[68:71], v[172:175], v[234:237], v[68:71]
	v_mfma_i32_16x16x64_i8 v[64:67], v[180:183], v[234:237], v[64:67]
	v_mfma_i32_16x16x64_i8 v[92:95], v[176:179], v[192:195], v[92:95]
	v_mfma_i32_16x16x64_i8 v[88:91], v[184:187], v[192:195], v[88:91]
	v_mfma_i32_16x16x64_i8 v[84:87], v[176:179], v[200:203], v[84:87]
	v_mfma_i32_16x16x64_i8 v[80:83], v[184:187], v[200:203], v[80:83]
	v_mfma_i32_16x16x64_i8 v[76:79], v[176:179], v[208:211], v[76:79]
	v_mfma_i32_16x16x64_i8 v[72:75], v[184:187], v[208:211], v[72:75]
	v_mfma_i32_16x16x64_i8 v[68:71], v[176:179], v[238:241], v[68:71]
	v_mfma_i32_16x16x64_i8 v[64:67], v[184:187], v[238:241], v[64:67]
	s_setprio 0
	s_barrier
	s_add_i32 s72, s0, s11
	s_add_u32 s98, s98, s24
	s_addc_u32 s99, s99, s25
	s_mov_b32 m0, s72
	ds_read_b128 v[188:191], v228 offset:49152
	ds_read_b128 v[192:195], v228 offset:50176
	ds_read_b128 v[196:199], v228 offset:51200
	ds_read_b128 v[200:203], v228 offset:52224
	ds_read_b128 v[204:207], v228 offset:53248
	ds_read_b128 v[208:211], v228 offset:54272
	ds_read_b128 v[234:237], v228 offset:55296
	ds_read_b128 v[238:241], v228 offset:56320
	global_load_lds_dwordx4 v152, s[98:99]
	s_add_i32 m0, s72, 0x2000
	s_add_u32 s68, s68, 0x20080
	s_addc_u32 s69, s69, 0
	s_add_i32 s72, s78, s11
	global_load_lds_dwordx4 v156, s[98:99]
	s_mov_b32 m0, s72
	s_nop 0
	global_load_lds_dwordx4 v152, s[68:69]
	s_add_i32 m0, s72, 0x2000
	s_nop 0
	global_load_lds_dwordx4 v156, s[68:69]
	s_add_u32 s100, s100, s24
	s_addc_u32 s101, s101, s25
	s_mov_b32 m0, s77
	s_nop 0
	global_load_lds_dwordx4 v150, s[100:101]
	s_mov_b32 m0, s84
	s_nop 0
	global_load_lds_dwordx4 v154, s[100:101]
	s_waitcnt vmcnt(8)
	s_waitcnt lgkmcnt(0)
	s_barrier
	s_setprio 1
	s_waitcnt lgkmcnt(0)
	v_mfma_i32_16x16x64_i8 v[60:63], v[128:131], v[188:191], v[60:63]
	v_mfma_i32_16x16x64_i8 v[56:59], v[136:139], v[188:191], v[56:59]
	v_mfma_i32_16x16x64_i8 v[52:55], v[128:131], v[196:199], v[52:55]
	v_mfma_i32_16x16x64_i8 v[48:51], v[136:139], v[196:199], v[48:51]
	v_mfma_i32_16x16x64_i8 v[44:47], v[128:131], v[204:207], v[44:47]
	v_mfma_i32_16x16x64_i8 v[40:43], v[136:139], v[204:207], v[40:43]
	v_mfma_i32_16x16x64_i8 v[36:39], v[128:131], v[234:237], v[36:39]
	v_mfma_i32_16x16x64_i8 v[32:35], v[136:139], v[234:237], v[32:35]
	v_mfma_i32_16x16x64_i8 v[60:63], v[132:135], v[192:195], v[60:63]
	v_mfma_i32_16x16x64_i8 v[56:59], v[140:143], v[192:195], v[56:59]
	v_mfma_i32_16x16x64_i8 v[52:55], v[132:135], v[200:203], v[52:55]
	v_mfma_i32_16x16x64_i8 v[48:51], v[140:143], v[200:203], v[48:51]
	v_mfma_i32_16x16x64_i8 v[44:47], v[132:135], v[208:211], v[44:47]
	v_mfma_i32_16x16x64_i8 v[40:43], v[140:143], v[208:211], v[40:43]
	v_mfma_i32_16x16x64_i8 v[36:39], v[132:135], v[238:241], v[36:39]
	v_mfma_i32_16x16x64_i8 v[32:35], v[140:143], v[238:241], v[32:35]
	v_mfma_i32_16x16x64_i8 v[28:31], v[172:175], v[188:191], v[28:31]
	v_mfma_i32_16x16x64_i8 v[24:27], v[180:183], v[188:191], v[24:27]
	v_mfma_i32_16x16x64_i8 v[20:23], v[172:175], v[196:199], v[20:23]
	v_mfma_i32_16x16x64_i8 v[16:19], v[180:183], v[196:199], v[16:19]
	v_mfma_i32_16x16x64_i8 v[12:15], v[172:175], v[204:207], v[12:15]
	v_mfma_i32_16x16x64_i8 v[8:11], v[180:183], v[204:207], v[8:11]
	v_mfma_i32_16x16x64_i8 v[4:7], v[172:175], v[234:237], v[4:7]
	v_mfma_i32_16x16x64_i8 v[0:3], v[180:183], v[234:237], v[0:3]
	v_mfma_i32_16x16x64_i8 v[28:31], v[176:179], v[192:195], v[28:31]
	v_mfma_i32_16x16x64_i8 v[24:27], v[184:187], v[192:195], v[24:27]
	v_mfma_i32_16x16x64_i8 v[20:23], v[176:179], v[200:203], v[20:23]
	v_mfma_i32_16x16x64_i8 v[16:19], v[184:187], v[200:203], v[16:19]
	v_mfma_i32_16x16x64_i8 v[12:15], v[176:179], v[208:211], v[12:15]
	v_mfma_i32_16x16x64_i8 v[8:11], v[184:187], v[208:211], v[8:11]
	v_mfma_i32_16x16x64_i8 v[4:7], v[176:179], v[238:241], v[4:7]
	v_mfma_i32_16x16x64_i8 v[0:3], v[184:187], v[238:241], v[0:3]
	s_setprio 0
	s_barrier
	s_add_i32 vcc_lo, vcc_lo, 2
	s_add_u32 s48, s48, 0x100
	s_addc_u32 s49, s49, 0
	s_add_u32 s74, s74, 0x100
	s_addc_u32 s75, s75, 0
	s_cmp_gt_u32 vcc_lo, 5
	s_cbranch_scc0 .LBB0_2189
	s_and_b64 vcc, exec, s[58:59]
	s_cbranch_vccz .LBB0_2192
	s_barrier

.LBB0_2520:
	s_add_u32 s48, s8, 0xfffc0080
	s_addc_u32 s49, s9, -1
	s_add_i32 s84, 0, 0x10000
	s_cmp_eq_u32 s67, 12
	s_cselect_b32 s61, s7, s49
	s_cselect_b32 s60, s55, s48
	v_add_u32_e32 v128, s84, v173
	s_cselect_b32 s49, s53, s66
	s_cselect_b32 s48, s64, s65
	s_add_i32 s88, 0, 0x14000
	ds_read_b128 v[174:177], v128
	ds_read_b128 v[180:183], v128 offset:1024
	ds_read_b128 v[184:187], v128 offset:2048
	ds_read_b128 v[188:191], v128 offset:3072
	v_add_u32_e32 v128, s88, v173
	ds_read_b128 v[192:195], v128
	ds_read_b128 v[196:199], v128 offset:1024
	ds_read_b128 v[204:207], v128 offset:2048
	ds_read_b128 v[208:211], v128 offset:3072
	s_add_i32 m0, s63, 0xc000
	ds_read_b128 v[212:215], v203
	ds_read_b128 v[216:219], v203 offset:1024
	ds_read_b128 v[220:223], v203 offset:2048
	ds_read_b128 v[224:227], v203 offset:3072
	ds_read_b128 v[228:231], v203 offset:4096
	ds_read_b128 v[234:237], v203 offset:5120
	ds_read_b128 v[238:241], v203 offset:6144
	ds_read_b128 v[242:245], v203 offset:7168
	global_load_lds_dwordx4 v148, s[8:9]
	s_add_i32 m0, s63, 0xe000
	s_nop 0
	global_load_lds_dwordx4 v150, s[8:9]
	s_waitcnt vmcnt(8)
	s_waitcnt lgkmcnt(0)
	s_barrier
	s_setprio 1
	s_waitcnt lgkmcnt(0)
	v_mfma_f32_16x16x32_bf16 v[124:127], v[174:177], v[212:215], v[124:127]
	v_mfma_f32_16x16x32_bf16 v[120:123], v[184:187], v[212:215], v[120:123]
	v_mfma_f32_16x16x32_bf16 v[108:111], v[174:177], v[220:223], v[108:111]
	v_mfma_f32_16x16x32_bf16 v[104:107], v[184:187], v[220:223], v[104:107]
	v_mfma_f32_16x16x32_bf16 v[92:95], v[174:177], v[228:231], v[92:95]
	v_mfma_f32_16x16x32_bf16 v[88:91], v[184:187], v[228:231], v[88:91]
	v_mfma_f32_16x16x32_bf16 v[76:79], v[174:177], v[238:241], v[76:79]
	v_mfma_f32_16x16x32_bf16 v[72:75], v[184:187], v[238:241], v[72:75]
	v_mfma_f32_16x16x32_bf16 v[124:127], v[180:183], v[216:219], v[124:127]
	v_mfma_f32_16x16x32_bf16 v[120:123], v[188:191], v[216:219], v[120:123]
	v_mfma_f32_16x16x32_bf16 v[108:111], v[180:183], v[224:227], v[108:111]
	v_mfma_f32_16x16x32_bf16 v[104:107], v[188:191], v[224:227], v[104:107]
	v_mfma_f32_16x16x32_bf16 v[92:95], v[180:183], v[234:237], v[92:95]
	v_mfma_f32_16x16x32_bf16 v[88:91], v[188:191], v[234:237], v[88:91]
	v_mfma_f32_16x16x32_bf16 v[76:79], v[180:183], v[242:245], v[76:79]
	v_mfma_f32_16x16x32_bf16 v[72:75], v[188:191], v[242:245], v[72:75]
	v_mfma_f32_16x16x32_bf16 v[116:119], v[192:195], v[212:215], v[116:119]
	v_mfma_f32_16x16x32_bf16 v[112:115], v[204:207], v[212:215], v[112:115]
	v_mfma_f32_16x16x32_bf16 v[100:103], v[192:195], v[220:223], v[100:103]
	v_mfma_f32_16x16x32_bf16 v[96:99], v[204:207], v[220:223], v[96:99]
	v_mfma_f32_16x16x32_bf16 v[84:87], v[192:195], v[228:231], v[84:87]
	v_mfma_f32_16x16x32_bf16 v[80:83], v[204:207], v[228:231], v[80:83]
	v_mfma_f32_16x16x32_bf16 v[68:71], v[192:195], v[238:241], v[68:71]
	v_mfma_f32_16x16x32_bf16 v[64:67], v[204:207], v[238:241], v[64:67]
	v_mfma_f32_16x16x32_bf16 v[116:119], v[196:199], v[216:219], v[116:119]
	v_mfma_f32_16x16x32_bf16 v[112:115], v[208:211], v[216:219], v[112:115]
	v_mfma_f32_16x16x32_bf16 v[100:103], v[196:199], v[224:227], v[100:103]
	v_mfma_f32_16x16x32_bf16 v[96:99], v[208:211], v[224:227], v[96:99]
	v_mfma_f32_16x16x32_bf16 v[84:87], v[196:199], v[234:237], v[84:87]
	v_mfma_f32_16x16x32_bf16 v[80:83], v[208:211], v[234:237], v[80:83]
	v_mfma_f32_16x16x32_bf16 v[68:71], v[196:199], v[242:245], v[68:71]
	v_mfma_f32_16x16x32_bf16 v[64:67], v[208:211], v[242:245], v[64:67]
	s_setprio 0
	s_barrier
	s_add_i32 s84, s84, s75
	s_mov_b64 s[98:99], s[48:49]
	s_mov_b32 m0, s84
	ds_read_b128 v[212:215], v203 offset:16384
	ds_read_b128 v[216:219], v203 offset:17408
	ds_read_b128 v[220:223], v203 offset:18432
	ds_read_b128 v[224:227], v203 offset:19456
	ds_read_b128 v[228:231], v203 offset:20480
	ds_read_b128 v[234:237], v203 offset:21504
	ds_read_b128 v[238:241], v203 offset:22528
	ds_read_b128 v[242:245], v203 offset:23552
	global_load_lds_dwordx4 v136, s[48:49]
	s_add_i32 m0, s84, 0x2000
	s_add_u32 s86, s48, 0x40000
	s_addc_u32 s87, s49, 0
	s_add_i32 s84, s88, s75
	global_load_lds_dwordx4 v140, s[48:49]
	s_mov_b32 m0, s84
	s_mov_b64 s[100:101], s[60:61]
	global_load_lds_dwordx4 v136, s[86:87]
	s_add_i32 m0, s84, 0x2000
	s_nop 0
	global_load_lds_dwordx4 v140, s[86:87]
	s_mov_b32 m0, s63
	s_nop 0
	global_load_lds_dwordx4 v134, s[60:61]
	s_mov_b32 m0, s76
	s_nop 0
	global_load_lds_dwordx4 v138, s[60:61]
	s_waitcnt vmcnt(8)
	s_waitcnt lgkmcnt(0)
	s_barrier
	s_setprio 1
	s_waitcnt lgkmcnt(0)
	v_mfma_f32_16x16x32_bf16 v[60:63], v[174:177], v[212:215], v[60:63]
	v_mfma_f32_16x16x32_bf16 v[56:59], v[184:187], v[212:215], v[56:59]
	v_mfma_f32_16x16x32_bf16 v[44:47], v[174:177], v[220:223], v[44:47]
	v_mfma_f32_16x16x32_bf16 v[40:43], v[184:187], v[220:223], v[40:43]
	v_mfma_f32_16x16x32_bf16 v[28:31], v[174:177], v[228:231], v[28:31]
	v_mfma_f32_16x16x32_bf16 v[24:27], v[184:187], v[228:231], v[24:27]
	v_mfma_f32_16x16x32_bf16 v[12:15], v[174:177], v[238:241], v[12:15]
	v_mfma_f32_16x16x32_bf16 v[8:11], v[184:187], v[238:241], v[8:11]
	v_mfma_f32_16x16x32_bf16 v[60:63], v[180:183], v[216:219], v[60:63]
	v_mfma_f32_16x16x32_bf16 v[56:59], v[188:191], v[216:219], v[56:59]
	v_mfma_f32_16x16x32_bf16 v[44:47], v[180:183], v[224:227], v[44:47]
	v_mfma_f32_16x16x32_bf16 v[40:43], v[188:191], v[224:227], v[40:43]
	v_mfma_f32_16x16x32_bf16 v[28:31], v[180:183], v[234:237], v[28:31]
	v_mfma_f32_16x16x32_bf16 v[24:27], v[188:191], v[234:237], v[24:27]
	v_mfma_f32_16x16x32_bf16 v[12:15], v[180:183], v[242:245], v[12:15]
	v_mfma_f32_16x16x32_bf16 v[8:11], v[188:191], v[242:245], v[8:11]
	v_mfma_f32_16x16x32_bf16 v[52:55], v[192:195], v[212:215], v[52:55]
	v_mfma_f32_16x16x32_bf16 v[48:51], v[204:207], v[212:215], v[48:51]
	v_mfma_f32_16x16x32_bf16 v[36:39], v[192:195], v[220:223], v[36:39]
	v_mfma_f32_16x16x32_bf16 v[32:35], v[204:207], v[220:223], v[32:35]
	v_mfma_f32_16x16x32_bf16 v[20:23], v[192:195], v[228:231], v[20:23]
	v_mfma_f32_16x16x32_bf16 v[16:19], v[204:207], v[228:231], v[16:19]
	v_mfma_f32_16x16x32_bf16 v[4:7], v[192:195], v[238:241], v[4:7]
	v_mfma_f32_16x16x32_bf16 v[0:3], v[204:207], v[238:241], v[0:3]
	v_mfma_f32_16x16x32_bf16 v[52:55], v[196:199], v[216:219], v[52:55]
	v_mfma_f32_16x16x32_bf16 v[48:51], v[208:211], v[216:219], v[48:51]
	v_mfma_f32_16x16x32_bf16 v[36:39], v[196:199], v[224:227], v[36:39]
	v_mfma_f32_16x16x32_bf16 v[32:35], v[208:211], v[224:227], v[32:35]
	v_mfma_f32_16x16x32_bf16 v[20:23], v[196:199], v[234:237], v[20:23]
	v_mfma_f32_16x16x32_bf16 v[16:19], v[208:211], v[234:237], v[16:19]
	v_mfma_f32_16x16x32_bf16 v[4:7], v[196:199], v[242:245], v[4:7]
	v_mfma_f32_16x16x32_bf16 v[0:3], v[208:211], v[242:245], v[0:3]
	s_setprio 0
	s_barrier
	v_add_u32_e32 v128, s0, v173
	s_add_i32 s84, 0, 0x1c000
	ds_read_b128 v[174:177], v128
	ds_read_b128 v[180:183], v128 offset:1024
	ds_read_b128 v[184:187], v128 offset:2048
	ds_read_b128 v[188:191], v128 offset:3072
	v_add_u32_e32 v128, s84, v173
	ds_read_b128 v[192:195], v128
	ds_read_b128 v[196:199], v128 offset:1024
	ds_read_b128 v[204:207], v128 offset:2048
	ds_read_b128 v[208:211], v128 offset:3072
	s_add_u32 s60, s60, 0x40000
	s_addc_u32 s61, s61, 0
	s_mov_b32 m0, s77
	ds_read_b128 v[212:215], v203 offset:32768
	ds_read_b128 v[216:219], v203 offset:33792
	ds_read_b128 v[220:223], v203 offset:34816
	ds_read_b128 v[224:227], v203 offset:35840
	ds_read_b128 v[228:231], v203 offset:36864
	ds_read_b128 v[234:237], v203 offset:37888
	ds_read_b128 v[238:241], v203 offset:38912
	ds_read_b128 v[242:245], v203 offset:39936
	global_load_lds_dwordx4 v134, s[60:61]
	s_mov_b32 m0, s78
	s_nop 0
	global_load_lds_dwordx4 v138, s[60:61]
	s_waitcnt vmcnt(8)
	s_waitcnt lgkmcnt(0)
	s_barrier
	s_setprio 1
	s_waitcnt lgkmcnt(0)
	v_mfma_f32_16x16x32_bf16 v[124:127], v[174:177], v[212:215], v[124:127]
	v_mfma_f32_16x16x32_bf16 v[120:123], v[184:187], v[212:215], v[120:123]
	v_mfma_f32_16x16x32_bf16 v[108:111], v[174:177], v[220:223], v[108:111]
	v_mfma_f32_16x16x32_bf16 v[104:107], v[184:187], v[220:223], v[104:107]
	v_mfma_f32_16x16x32_bf16 v[92:95], v[174:177], v[228:231], v[92:95]
	v_mfma_f32_16x16x32_bf16 v[88:91], v[184:187], v[228:231], v[88:91]
	v_mfma_f32_16x16x32_bf16 v[76:79], v[174:177], v[238:241], v[76:79]
	v_mfma_f32_16x16x32_bf16 v[72:75], v[184:187], v[238:241], v[72:75]
	v_mfma_f32_16x16x32_bf16 v[124:127], v[180:183], v[216:219], v[124:127]
	v_mfma_f32_16x16x32_bf16 v[120:123], v[188:191], v[216:219], v[120:123]
	v_mfma_f32_16x16x32_bf16 v[108:111], v[180:183], v[224:227], v[108:111]
	v_mfma_f32_16x16x32_bf16 v[104:107], v[188:191], v[224:227], v[104:107]
	v_mfma_f32_16x16x32_bf16 v[92:95], v[180:183], v[234:237], v[92:95]
	v_mfma_f32_16x16x32_bf16 v[88:91], v[188:191], v[234:237], v[88:91]
	v_mfma_f32_16x16x32_bf16 v[76:79], v[180:183], v[242:245], v[76:79]
	v_mfma_f32_16x16x32_bf16 v[72:75], v[188:191], v[242:245], v[72:75]
	v_mfma_f32_16x16x32_bf16 v[116:119], v[192:195], v[212:215], v[116:119]
	v_mfma_f32_16x16x32_bf16 v[112:115], v[204:207], v[212:215], v[112:115]
	v_mfma_f32_16x16x32_bf16 v[100:103], v[192:195], v[220:223], v[100:103]
	v_mfma_f32_16x16x32_bf16 v[96:99], v[204:207], v[220:223], v[96:99]
	v_mfma_f32_16x16x32_bf16 v[84:87], v[192:195], v[228:231], v[84:87]
	v_mfma_f32_16x16x32_bf16 v[80:83], v[204:207], v[228:231], v[80:83]
	v_mfma_f32_16x16x32_bf16 v[68:71], v[192:195], v[238:241], v[68:71]
	v_mfma_f32_16x16x32_bf16 v[64:67], v[204:207], v[238:241], v[64:67]
	v_mfma_f32_16x16x32_bf16 v[116:119], v[196:199], v[216:219], v[116:119]
	v_mfma_f32_16x16x32_bf16 v[112:115], v[208:211], v[216:219], v[112:115]
	v_mfma_f32_16x16x32_bf16 v[100:103], v[196:199], v[224:227], v[100:103]
	v_mfma_f32_16x16x32_bf16 v[96:99], v[208:211], v[224:227], v[96:99]
	v_mfma_f32_16x16x32_bf16 v[84:87], v[196:199], v[234:237], v[84:87]
	v_mfma_f32_16x16x32_bf16 v[80:83], v[208:211], v[234:237], v[80:83]
	v_mfma_f32_16x16x32_bf16 v[68:71], v[196:199], v[242:245], v[68:71]
	v_mfma_f32_16x16x32_bf16 v[64:67], v[208:211], v[242:245], v[64:67]
	s_setprio 0
	s_barrier
	s_add_i32 s60, s0, s75
	s_add_u32 s98, s98, s12
	s_addc_u32 s99, s99, s13
	s_mov_b32 m0, s60
	ds_read_b128 v[212:215], v203 offset:49152
	ds_read_b128 v[216:219], v203 offset:50176
	ds_read_b128 v[220:223], v203 offset:51200
	ds_read_b128 v[224:227], v203 offset:52224
	ds_read_b128 v[228:231], v203 offset:53248
	ds_read_b128 v[234:237], v203 offset:54272
	ds_read_b128 v[238:241], v203 offset:55296
	ds_read_b128 v[242:245], v203 offset:56320
	global_load_lds_dwordx4 v136, s[98:99]
	s_add_i32 m0, s60, 0x2000
	s_add_u32 s48, s48, 0x40080
	s_addc_u32 s49, s49, 0
	s_add_i32 s60, s84, s75
	global_load_lds_dwordx4 v140, s[98:99]
	s_mov_b32 m0, s60
	s_nop 0
	global_load_lds_dwordx4 v136, s[48:49]
	s_add_i32 m0, s60, 0x2000
	s_nop 0
	global_load_lds_dwordx4 v140, s[48:49]
	s_add_u32 s100, s100, s12
	s_addc_u32 s101, s101, s13
	s_mov_b32 m0, s79
	s_nop 0
	global_load_lds_dwordx4 v134, s[100:101]
	s_mov_b32 m0, s80
	s_nop 0
	global_load_lds_dwordx4 v138, s[100:101]
	s_waitcnt vmcnt(8)
	s_waitcnt lgkmcnt(0)
	s_barrier
	s_setprio 1
	s_waitcnt lgkmcnt(0)
	v_mfma_f32_16x16x32_bf16 v[60:63], v[174:177], v[212:215], v[60:63]
	v_mfma_f32_16x16x32_bf16 v[56:59], v[184:187], v[212:215], v[56:59]
	v_mfma_f32_16x16x32_bf16 v[44:47], v[174:177], v[220:223], v[44:47]
	v_mfma_f32_16x16x32_bf16 v[40:43], v[184:187], v[220:223], v[40:43]
	v_mfma_f32_16x16x32_bf16 v[28:31], v[174:177], v[228:231], v[28:31]
	v_mfma_f32_16x16x32_bf16 v[24:27], v[184:187], v[228:231], v[24:27]
	v_mfma_f32_16x16x32_bf16 v[12:15], v[174:177], v[238:241], v[12:15]
	v_mfma_f32_16x16x32_bf16 v[8:11], v[184:187], v[238:241], v[8:11]
	v_mfma_f32_16x16x32_bf16 v[60:63], v[180:183], v[216:219], v[60:63]
	v_mfma_f32_16x16x32_bf16 v[56:59], v[188:191], v[216:219], v[56:59]
	v_mfma_f32_16x16x32_bf16 v[44:47], v[180:183], v[224:227], v[44:47]
	v_mfma_f32_16x16x32_bf16 v[40:43], v[188:191], v[224:227], v[40:43]
	v_mfma_f32_16x16x32_bf16 v[28:31], v[180:183], v[234:237], v[28:31]
	v_mfma_f32_16x16x32_bf16 v[24:27], v[188:191], v[234:237], v[24:27]
	v_mfma_f32_16x16x32_bf16 v[12:15], v[180:183], v[242:245], v[12:15]
	v_mfma_f32_16x16x32_bf16 v[8:11], v[188:191], v[242:245], v[8:11]
	v_mfma_f32_16x16x32_bf16 v[52:55], v[192:195], v[212:215], v[52:55]
	v_mfma_f32_16x16x32_bf16 v[48:51], v[204:207], v[212:215], v[48:51]
	v_mfma_f32_16x16x32_bf16 v[36:39], v[192:195], v[220:223], v[36:39]
	v_mfma_f32_16x16x32_bf16 v[32:35], v[204:207], v[220:223], v[32:35]
	v_mfma_f32_16x16x32_bf16 v[20:23], v[192:195], v[228:231], v[20:23]
	v_mfma_f32_16x16x32_bf16 v[16:19], v[204:207], v[228:231], v[16:19]
	v_mfma_f32_16x16x32_bf16 v[4:7], v[192:195], v[238:241], v[4:7]
	v_mfma_f32_16x16x32_bf16 v[0:3], v[204:207], v[238:241], v[0:3]
	v_mfma_f32_16x16x32_bf16 v[52:55], v[196:199], v[216:219], v[52:55]
	v_mfma_f32_16x16x32_bf16 v[48:51], v[208:211], v[216:219], v[48:51]
	v_mfma_f32_16x16x32_bf16 v[36:39], v[196:199], v[224:227], v[36:39]
	v_mfma_f32_16x16x32_bf16 v[32:35], v[208:211], v[224:227], v[32:35]
	v_mfma_f32_16x16x32_bf16 v[20:23], v[196:199], v[234:237], v[20:23]
	v_mfma_f32_16x16x32_bf16 v[16:19], v[208:211], v[234:237], v[16:19]
	v_mfma_f32_16x16x32_bf16 v[4:7], v[196:199], v[242:245], v[4:7]
	v_mfma_f32_16x16x32_bf16 v[0:3], v[208:211], v[242:245], v[0:3]
	s_setprio 0
	s_barrier
	s_add_i32 s67, s67, 2
	s_add_u32 s8, s8, 0x100
	s_addc_u32 s9, s9, 0
	s_add_u32 s65, s65, 0x100
	s_addc_u32 s66, s66, 0
	s_cmp_gt_u32 s67, 13
	s_cbranch_scc0 .LBB0_2520
	s_and_b64 vcc, exec, s[50:51]
	s_cbranch_vccz .LBB0_2523
	s_barrier

.LBB0_2602:
	s_add_u32 s56, s48, 0xfffe0080
	s_addc_u32 s57, s49, -1
	s_add_i32 s87, 0, 0x10000
	s_cmp_eq_u32 s86, 4
	s_cselect_b32 s61, s7, s57
	s_cselect_b32 s60, s51, s56
	s_cselect_b32 s57, s45, s85
	s_cselect_b32 s56, s62, s63
	s_add_i32 s90, 0, 0x14000
	v_add_u32_e32 v140, s87, v203
	v_add_u32_e32 v144, s90, v203
	ds_read_b128 v[128:131], v140
	ds_read_b128 v[132:135], v140 offset:1024
	ds_read_b128 v[136:139], v140 offset:2048
	ds_read_b128 v[140:143], v140 offset:3072
	ds_read_b128 v[172:175], v144
	ds_read_b128 v[176:179], v144 offset:1024
	ds_read_b128 v[180:183], v144 offset:2048
	ds_read_b128 v[184:187], v144 offset:3072
	s_add_i32 m0, s76, 0xc000
	ds_read_b128 v[188:191], v206
	ds_read_b128 v[208:211], v206 offset:1024
	ds_read_b128 v[212:215], v206 offset:2048
	ds_read_b128 v[216:219], v206 offset:3072
	ds_read_b128 v[220:223], v206 offset:4096
	ds_read_b128 v[224:227], v206 offset:5120
	ds_read_b128 v[228:231], v206 offset:6144
	ds_read_b128 v[234:237], v206 offset:7168
	global_load_lds_dwordx4 v166, s[48:49]
	s_add_i32 m0, s76, 0xe000
	s_nop 0
	global_load_lds_dwordx4 v168, s[48:49]
	s_waitcnt vmcnt(8)
	s_waitcnt lgkmcnt(0)
	s_barrier
	s_setprio 1
	s_waitcnt lgkmcnt(0)
	v_mfma_i32_16x16x64_i8 v[124:127], v[128:131], v[188:191], v[124:127]
	v_mfma_i32_16x16x64_i8 v[120:123], v[136:139], v[188:191], v[120:123]
	v_mfma_i32_16x16x64_i8 v[116:119], v[128:131], v[212:215], v[116:119]
	v_mfma_i32_16x16x64_i8 v[112:115], v[136:139], v[212:215], v[112:115]
	v_mfma_i32_16x16x64_i8 v[108:111], v[128:131], v[220:223], v[108:111]
	v_mfma_i32_16x16x64_i8 v[104:107], v[136:139], v[220:223], v[104:107]
	v_mfma_i32_16x16x64_i8 v[100:103], v[128:131], v[228:231], v[100:103]
	v_mfma_i32_16x16x64_i8 v[96:99], v[136:139], v[228:231], v[96:99]
	v_mfma_i32_16x16x64_i8 v[124:127], v[132:135], v[208:211], v[124:127]
	v_mfma_i32_16x16x64_i8 v[120:123], v[140:143], v[208:211], v[120:123]
	v_mfma_i32_16x16x64_i8 v[116:119], v[132:135], v[216:219], v[116:119]
	v_mfma_i32_16x16x64_i8 v[112:115], v[140:143], v[216:219], v[112:115]
	v_mfma_i32_16x16x64_i8 v[108:111], v[132:135], v[224:227], v[108:111]
	v_mfma_i32_16x16x64_i8 v[104:107], v[140:143], v[224:227], v[104:107]
	v_mfma_i32_16x16x64_i8 v[100:103], v[132:135], v[234:237], v[100:103]
	v_mfma_i32_16x16x64_i8 v[96:99], v[140:143], v[234:237], v[96:99]
	v_mfma_i32_16x16x64_i8 v[92:95], v[172:175], v[188:191], v[92:95]
	v_mfma_i32_16x16x64_i8 v[88:91], v[180:183], v[188:191], v[88:91]
	v_mfma_i32_16x16x64_i8 v[84:87], v[172:175], v[212:215], v[84:87]
	v_mfma_i32_16x16x64_i8 v[80:83], v[180:183], v[212:215], v[80:83]
	v_mfma_i32_16x16x64_i8 v[76:79], v[172:175], v[220:223], v[76:79]
	v_mfma_i32_16x16x64_i8 v[72:75], v[180:183], v[220:223], v[72:75]
	v_mfma_i32_16x16x64_i8 v[68:71], v[172:175], v[228:231], v[68:71]
	v_mfma_i32_16x16x64_i8 v[64:67], v[180:183], v[228:231], v[64:67]
	v_mfma_i32_16x16x64_i8 v[92:95], v[176:179], v[208:211], v[92:95]
	v_mfma_i32_16x16x64_i8 v[88:91], v[184:187], v[208:211], v[88:91]
	v_mfma_i32_16x16x64_i8 v[84:87], v[176:179], v[216:219], v[84:87]
	v_mfma_i32_16x16x64_i8 v[80:83], v[184:187], v[216:219], v[80:83]
	v_mfma_i32_16x16x64_i8 v[76:79], v[176:179], v[224:227], v[76:79]
	v_mfma_i32_16x16x64_i8 v[72:75], v[184:187], v[224:227], v[72:75]
	v_mfma_i32_16x16x64_i8 v[68:71], v[176:179], v[234:237], v[68:71]
	v_mfma_i32_16x16x64_i8 v[64:67], v[184:187], v[234:237], v[64:67]
	s_setprio 0
	s_barrier
	s_add_i32 s87, s87, s75
	s_mov_b64 s[98:99], s[56:57]
	s_mov_b32 m0, s87
	ds_read_b128 v[188:191], v206 offset:16384
	ds_read_b128 v[208:211], v206 offset:17408
	ds_read_b128 v[212:215], v206 offset:18432
	ds_read_b128 v[216:219], v206 offset:19456
	ds_read_b128 v[220:223], v206 offset:20480
	ds_read_b128 v[224:227], v206 offset:21504
	ds_read_b128 v[228:231], v206 offset:22528
	ds_read_b128 v[234:237], v206 offset:23552
	global_load_lds_dwordx4 v152, s[56:57]
	s_add_i32 m0, s87, 0x2000
	s_add_u32 s88, s56, 0x20000
	s_addc_u32 s89, s57, 0
	s_add_i32 s87, s90, s75
	global_load_lds_dwordx4 v156, s[56:57]
	s_mov_b32 m0, s87
	s_mov_b64 s[100:101], s[60:61]
	global_load_lds_dwordx4 v152, s[88:89]
	s_add_i32 m0, s87, 0x2000
	s_nop 0
	global_load_lds_dwordx4 v156, s[88:89]
	s_mov_b32 m0, s76
	s_nop 0
	global_load_lds_dwordx4 v150, s[60:61]
	s_mov_b32 m0, s77
	s_nop 0
	global_load_lds_dwordx4 v154, s[60:61]
	s_waitcnt vmcnt(8)
	s_waitcnt lgkmcnt(0)
	s_barrier
	s_setprio 1
	s_waitcnt lgkmcnt(0)
	v_mfma_i32_16x16x64_i8 v[60:63], v[128:131], v[188:191], v[60:63]
	v_mfma_i32_16x16x64_i8 v[56:59], v[136:139], v[188:191], v[56:59]
	v_mfma_i32_16x16x64_i8 v[52:55], v[128:131], v[212:215], v[52:55]
	v_mfma_i32_16x16x64_i8 v[48:51], v[136:139], v[212:215], v[48:51]
	v_mfma_i32_16x16x64_i8 v[44:47], v[128:131], v[220:223], v[44:47]
	v_mfma_i32_16x16x64_i8 v[40:43], v[136:139], v[220:223], v[40:43]
	v_mfma_i32_16x16x64_i8 v[36:39], v[128:131], v[228:231], v[36:39]
	v_mfma_i32_16x16x64_i8 v[32:35], v[136:139], v[228:231], v[32:35]
	v_mfma_i32_16x16x64_i8 v[60:63], v[132:135], v[208:211], v[60:63]
	v_mfma_i32_16x16x64_i8 v[56:59], v[140:143], v[208:211], v[56:59]
	v_mfma_i32_16x16x64_i8 v[52:55], v[132:135], v[216:219], v[52:55]
	v_mfma_i32_16x16x64_i8 v[48:51], v[140:143], v[216:219], v[48:51]
	v_mfma_i32_16x16x64_i8 v[44:47], v[132:135], v[224:227], v[44:47]
	v_mfma_i32_16x16x64_i8 v[40:43], v[140:143], v[224:227], v[40:43]
	v_mfma_i32_16x16x64_i8 v[36:39], v[132:135], v[234:237], v[36:39]
	v_mfma_i32_16x16x64_i8 v[32:35], v[140:143], v[234:237], v[32:35]
	v_mfma_i32_16x16x64_i8 v[28:31], v[172:175], v[188:191], v[28:31]
	v_mfma_i32_16x16x64_i8 v[24:27], v[180:183], v[188:191], v[24:27]
	v_mfma_i32_16x16x64_i8 v[20:23], v[172:175], v[212:215], v[20:23]
	v_mfma_i32_16x16x64_i8 v[16:19], v[180:183], v[212:215], v[16:19]
	v_mfma_i32_16x16x64_i8 v[12:15], v[172:175], v[220:223], v[12:15]
	v_mfma_i32_16x16x64_i8 v[8:11], v[180:183], v[220:223], v[8:11]
	v_mfma_i32_16x16x64_i8 v[4:7], v[172:175], v[228:231], v[4:7]
	v_mfma_i32_16x16x64_i8 v[0:3], v[180:183], v[228:231], v[0:3]
	v_mfma_i32_16x16x64_i8 v[28:31], v[176:179], v[208:211], v[28:31]
	v_mfma_i32_16x16x64_i8 v[24:27], v[184:187], v[208:211], v[24:27]
	v_mfma_i32_16x16x64_i8 v[20:23], v[176:179], v[216:219], v[20:23]
	v_mfma_i32_16x16x64_i8 v[16:19], v[184:187], v[216:219], v[16:19]
	v_mfma_i32_16x16x64_i8 v[12:15], v[176:179], v[224:227], v[12:15]
	v_mfma_i32_16x16x64_i8 v[8:11], v[184:187], v[224:227], v[8:11]
	v_mfma_i32_16x16x64_i8 v[4:7], v[176:179], v[234:237], v[4:7]
	v_mfma_i32_16x16x64_i8 v[0:3], v[184:187], v[234:237], v[0:3]
	s_setprio 0
	s_barrier
	s_add_i32 s87, 0, 0x1c000
	v_add_u32_e32 v140, s0, v203
	v_add_u32_e32 v144, s87, v203
	ds_read_b128 v[128:131], v140
	ds_read_b128 v[132:135], v140 offset:1024
	ds_read_b128 v[136:139], v140 offset:2048
	ds_read_b128 v[140:143], v140 offset:3072
	ds_read_b128 v[172:175], v144
	ds_read_b128 v[176:179], v144 offset:1024
	ds_read_b128 v[180:183], v144 offset:2048
	ds_read_b128 v[184:187], v144 offset:3072
	s_add_u32 s60, s60, 0x20000
	s_addc_u32 s61, s61, 0
	s_mov_b32 m0, s78
	ds_read_b128 v[188:191], v206 offset:32768
	ds_read_b128 v[208:211], v206 offset:33792
	ds_read_b128 v[212:215], v206 offset:34816
	ds_read_b128 v[216:219], v206 offset:35840
	ds_read_b128 v[220:223], v206 offset:36864
	ds_read_b128 v[224:227], v206 offset:37888
	ds_read_b128 v[228:231], v206 offset:38912
	ds_read_b128 v[234:237], v206 offset:39936
	global_load_lds_dwordx4 v150, s[60:61]
	s_mov_b32 m0, s79
	s_nop 0
	global_load_lds_dwordx4 v154, s[60:61]
	s_waitcnt vmcnt(8)
	s_waitcnt lgkmcnt(0)
	s_barrier
	s_setprio 1
	s_waitcnt lgkmcnt(0)
	v_mfma_i32_16x16x64_i8 v[124:127], v[128:131], v[188:191], v[124:127]
	v_mfma_i32_16x16x64_i8 v[120:123], v[136:139], v[188:191], v[120:123]
	v_mfma_i32_16x16x64_i8 v[116:119], v[128:131], v[212:215], v[116:119]
	v_mfma_i32_16x16x64_i8 v[112:115], v[136:139], v[212:215], v[112:115]
	v_mfma_i32_16x16x64_i8 v[108:111], v[128:131], v[220:223], v[108:111]
	v_mfma_i32_16x16x64_i8 v[104:107], v[136:139], v[220:223], v[104:107]
	v_mfma_i32_16x16x64_i8 v[100:103], v[128:131], v[228:231], v[100:103]
	v_mfma_i32_16x16x64_i8 v[96:99], v[136:139], v[228:231], v[96:99]
	v_mfma_i32_16x16x64_i8 v[124:127], v[132:135], v[208:211], v[124:127]
	v_mfma_i32_16x16x64_i8 v[120:123], v[140:143], v[208:211], v[120:123]
	v_mfma_i32_16x16x64_i8 v[116:119], v[132:135], v[216:219], v[116:119]
	v_mfma_i32_16x16x64_i8 v[112:115], v[140:143], v[216:219], v[112:115]
	v_mfma_i32_16x16x64_i8 v[108:111], v[132:135], v[224:227], v[108:111]
	v_mfma_i32_16x16x64_i8 v[104:107], v[140:143], v[224:227], v[104:107]
	v_mfma_i32_16x16x64_i8 v[100:103], v[132:135], v[234:237], v[100:103]
	v_mfma_i32_16x16x64_i8 v[96:99], v[140:143], v[234:237], v[96:99]
	v_mfma_i32_16x16x64_i8 v[92:95], v[172:175], v[188:191], v[92:95]
	v_mfma_i32_16x16x64_i8 v[88:91], v[180:183], v[188:191], v[88:91]
	v_mfma_i32_16x16x64_i8 v[84:87], v[172:175], v[212:215], v[84:87]
	v_mfma_i32_16x16x64_i8 v[80:83], v[180:183], v[212:215], v[80:83]
	v_mfma_i32_16x16x64_i8 v[76:79], v[172:175], v[220:223], v[76:79]
	v_mfma_i32_16x16x64_i8 v[72:75], v[180:183], v[220:223], v[72:75]
	v_mfma_i32_16x16x64_i8 v[68:71], v[172:175], v[228:231], v[68:71]
	v_mfma_i32_16x16x64_i8 v[64:67], v[180:183], v[228:231], v[64:67]
	v_mfma_i32_16x16x64_i8 v[92:95], v[176:179], v[208:211], v[92:95]
	v_mfma_i32_16x16x64_i8 v[88:91], v[184:187], v[208:211], v[88:91]
	v_mfma_i32_16x16x64_i8 v[84:87], v[176:179], v[216:219], v[84:87]
	v_mfma_i32_16x16x64_i8 v[80:83], v[184:187], v[216:219], v[80:83]
	v_mfma_i32_16x16x64_i8 v[76:79], v[176:179], v[224:227], v[76:79]
	v_mfma_i32_16x16x64_i8 v[72:75], v[184:187], v[224:227], v[72:75]
	v_mfma_i32_16x16x64_i8 v[68:71], v[176:179], v[234:237], v[68:71]
	v_mfma_i32_16x16x64_i8 v[64:67], v[184:187], v[234:237], v[64:67]
	s_setprio 0
	s_barrier
	s_add_i32 s60, s0, s75
	s_add_u32 s98, s98, s10
	s_addc_u32 s99, s99, s11
	s_mov_b32 m0, s60
	ds_read_b128 v[188:191], v206 offset:49152
	ds_read_b128 v[208:211], v206 offset:50176
	ds_read_b128 v[212:215], v206 offset:51200
	ds_read_b128 v[216:219], v206 offset:52224
	ds_read_b128 v[220:223], v206 offset:53248
	ds_read_b128 v[224:227], v206 offset:54272
	ds_read_b128 v[228:231], v206 offset:55296
	ds_read_b128 v[234:237], v206 offset:56320
	global_load_lds_dwordx4 v152, s[98:99]
	s_add_i32 m0, s60, 0x2000
	s_add_u32 s56, s56, 0x20080
	s_addc_u32 s57, s57, 0
	s_add_i32 s60, s87, s75
	global_load_lds_dwordx4 v156, s[98:99]
	s_mov_b32 m0, s60
	s_nop 0
	global_load_lds_dwordx4 v152, s[56:57]
	s_add_i32 m0, s60, 0x2000
	s_nop 0
	global_load_lds_dwordx4 v156, s[56:57]
	s_add_u32 s100, s100, s10
	s_addc_u32 s101, s101, s11
	s_mov_b32 m0, s80
	s_nop 0
	global_load_lds_dwordx4 v150, s[100:101]
	s_mov_b32 m0, s81
	s_nop 0
	global_load_lds_dwordx4 v154, s[100:101]
	s_waitcnt vmcnt(8)
	s_waitcnt lgkmcnt(0)
	s_barrier
	s_setprio 1
	s_waitcnt lgkmcnt(0)
	v_mfma_i32_16x16x64_i8 v[60:63], v[128:131], v[188:191], v[60:63]
	v_mfma_i32_16x16x64_i8 v[56:59], v[136:139], v[188:191], v[56:59]
	v_mfma_i32_16x16x64_i8 v[52:55], v[128:131], v[212:215], v[52:55]
	v_mfma_i32_16x16x64_i8 v[48:51], v[136:139], v[212:215], v[48:51]
	v_mfma_i32_16x16x64_i8 v[44:47], v[128:131], v[220:223], v[44:47]
	v_mfma_i32_16x16x64_i8 v[40:43], v[136:139], v[220:223], v[40:43]
	v_mfma_i32_16x16x64_i8 v[36:39], v[128:131], v[228:231], v[36:39]
	v_mfma_i32_16x16x64_i8 v[32:35], v[136:139], v[228:231], v[32:35]
	v_mfma_i32_16x16x64_i8 v[60:63], v[132:135], v[208:211], v[60:63]
	v_mfma_i32_16x16x64_i8 v[56:59], v[140:143], v[208:211], v[56:59]
	v_mfma_i32_16x16x64_i8 v[52:55], v[132:135], v[216:219], v[52:55]
	v_mfma_i32_16x16x64_i8 v[48:51], v[140:143], v[216:219], v[48:51]
	v_mfma_i32_16x16x64_i8 v[44:47], v[132:135], v[224:227], v[44:47]
	v_mfma_i32_16x16x64_i8 v[40:43], v[140:143], v[224:227], v[40:43]
	v_mfma_i32_16x16x64_i8 v[36:39], v[132:135], v[234:237], v[36:39]
	v_mfma_i32_16x16x64_i8 v[32:35], v[140:143], v[234:237], v[32:35]
	v_mfma_i32_16x16x64_i8 v[28:31], v[172:175], v[188:191], v[28:31]
	v_mfma_i32_16x16x64_i8 v[24:27], v[180:183], v[188:191], v[24:27]
	v_mfma_i32_16x16x64_i8 v[20:23], v[172:175], v[212:215], v[20:23]
	v_mfma_i32_16x16x64_i8 v[16:19], v[180:183], v[212:215], v[16:19]
	v_mfma_i32_16x16x64_i8 v[12:15], v[172:175], v[220:223], v[12:15]
	v_mfma_i32_16x16x64_i8 v[8:11], v[180:183], v[220:223], v[8:11]
	v_mfma_i32_16x16x64_i8 v[4:7], v[172:175], v[228:231], v[4:7]
	v_mfma_i32_16x16x64_i8 v[0:3], v[180:183], v[228:231], v[0:3]
	v_mfma_i32_16x16x64_i8 v[28:31], v[176:179], v[208:211], v[28:31]
	v_mfma_i32_16x16x64_i8 v[24:27], v[184:187], v[208:211], v[24:27]
	v_mfma_i32_16x16x64_i8 v[20:23], v[176:179], v[216:219], v[20:23]
	v_mfma_i32_16x16x64_i8 v[16:19], v[184:187], v[216:219], v[16:19]
	v_mfma_i32_16x16x64_i8 v[12:15], v[176:179], v[224:227], v[12:15]
	v_mfma_i32_16x16x64_i8 v[8:11], v[184:187], v[224:227], v[8:11]
	v_mfma_i32_16x16x64_i8 v[4:7], v[176:179], v[234:237], v[4:7]
	v_mfma_i32_16x16x64_i8 v[0:3], v[184:187], v[234:237], v[0:3]
	s_setprio 0
	s_barrier
	s_add_i32 s86, s86, 2
	s_add_u32 s48, s48, 0x100
	s_addc_u32 s49, s49, 0
	s_add_u32 s63, s63, 0x100
	s_addc_u32 s85, s85, 0
	s_cmp_gt_u32 s86, 5
	s_cbranch_scc0 .LBB0_2602
	s_and_b64 vcc, exec, s[42:43]
	s_cbranch_vccz .LBB0_2605
	s_barrier

.LBB0_2985:
	s_add_u32 s58, s56, 0xfffe0080
	s_addc_u32 s59, s57, -1
	s_add_i32 s85, 0, 0x10000
	s_cmp_eq_u32 s84, 4
	s_cselect_b32 s61, s51, s59
	s_cselect_b32 s60, s81, s58
	s_cselect_b32 s59, s43, s83
	s_cselect_b32 s58, s45, s82
	s_add_i32 s88, 0, 0x14000
	v_add_u32_e32 v150, s85, v182
	v_add_u32_e32 v154, s88, v182
	ds_read_b128 v[138:141], v150
	ds_read_b128 v[142:145], v150 offset:1024
	ds_read_b128 v[146:149], v150 offset:2048
	ds_read_b128 v[150:153], v150 offset:3072
	ds_read_b128 v[166:169], v154
	ds_read_b128 v[190:193], v154 offset:1024
	ds_read_b128 v[194:197], v154 offset:2048
	ds_read_b128 v[198:201], v154 offset:3072
	s_add_i32 m0, s12, 0xc000
	ds_read_b128 v[202:205], v185
	ds_read_b128 v[206:209], v185 offset:1024
	ds_read_b128 v[210:213], v185 offset:2048
	ds_read_b128 v[214:217], v185 offset:3072
	ds_read_b128 v[218:221], v185 offset:4096
	ds_read_b128 v[222:225], v185 offset:5120
	ds_read_b128 v[226:229], v185 offset:6144
	ds_read_b128 v[234:237], v185 offset:7168
	global_load_lds_dwordx4 v134, s[56:57]
	s_add_i32 m0, s12, 0xe000
	s_nop 0
	global_load_lds_dwordx4 v136, s[56:57]
	s_waitcnt vmcnt(8)
	s_waitcnt lgkmcnt(0)
	s_barrier
	s_setprio 1
	s_waitcnt lgkmcnt(0)
	v_mfma_i32_16x16x64_i8 v[126:129], v[138:141], v[202:205], v[126:129]
	v_mfma_i32_16x16x64_i8 v[122:125], v[146:149], v[202:205], v[122:125]
	v_mfma_i32_16x16x64_i8 v[110:113], v[138:141], v[210:213], v[110:113]
	v_mfma_i32_16x16x64_i8 v[106:109], v[146:149], v[210:213], v[106:109]
	v_mfma_i32_16x16x64_i8 v[94:97], v[138:141], v[218:221], v[94:97]
	v_mfma_i32_16x16x64_i8 v[90:93], v[146:149], v[218:221], v[90:93]
	v_mfma_i32_16x16x64_i8 v[78:81], v[138:141], v[226:229], v[78:81]
	v_mfma_i32_16x16x64_i8 v[74:77], v[146:149], v[226:229], v[74:77]
	v_mfma_i32_16x16x64_i8 v[126:129], v[142:145], v[206:209], v[126:129]
	v_mfma_i32_16x16x64_i8 v[122:125], v[150:153], v[206:209], v[122:125]
	v_mfma_i32_16x16x64_i8 v[110:113], v[142:145], v[214:217], v[110:113]
	v_mfma_i32_16x16x64_i8 v[106:109], v[150:153], v[214:217], v[106:109]
	v_mfma_i32_16x16x64_i8 v[94:97], v[142:145], v[222:225], v[94:97]
	v_mfma_i32_16x16x64_i8 v[90:93], v[150:153], v[222:225], v[90:93]
	v_mfma_i32_16x16x64_i8 v[78:81], v[142:145], v[234:237], v[78:81]
	v_mfma_i32_16x16x64_i8 v[74:77], v[150:153], v[234:237], v[74:77]
	v_mfma_i32_16x16x64_i8 v[118:121], v[166:169], v[202:205], v[118:121]
	v_mfma_i32_16x16x64_i8 v[114:117], v[194:197], v[202:205], v[114:117]
	v_mfma_i32_16x16x64_i8 v[102:105], v[166:169], v[210:213], v[102:105]
	v_mfma_i32_16x16x64_i8 v[98:101], v[194:197], v[210:213], v[98:101]
	v_mfma_i32_16x16x64_i8 v[86:89], v[166:169], v[218:221], v[86:89]
	v_mfma_i32_16x16x64_i8 v[82:85], v[194:197], v[218:221], v[82:85]
	v_mfma_i32_16x16x64_i8 v[70:73], v[166:169], v[226:229], v[70:73]
	v_mfma_i32_16x16x64_i8 v[66:69], v[194:197], v[226:229], v[66:69]
	v_mfma_i32_16x16x64_i8 v[118:121], v[190:193], v[206:209], v[118:121]
	v_mfma_i32_16x16x64_i8 v[114:117], v[198:201], v[206:209], v[114:117]
	v_mfma_i32_16x16x64_i8 v[102:105], v[190:193], v[214:217], v[102:105]
	v_mfma_i32_16x16x64_i8 v[98:101], v[198:201], v[214:217], v[98:101]
	v_mfma_i32_16x16x64_i8 v[86:89], v[190:193], v[222:225], v[86:89]
	v_mfma_i32_16x16x64_i8 v[82:85], v[198:201], v[222:225], v[82:85]
	v_mfma_i32_16x16x64_i8 v[70:73], v[190:193], v[234:237], v[70:73]
	v_mfma_i32_16x16x64_i8 v[66:69], v[198:201], v[234:237], v[66:69]
	s_setprio 0
	s_barrier
	s_add_i32 s85, s85, s71
	s_mov_b64 s[98:99], s[58:59]
	s_mov_b32 m0, s85
	ds_read_b128 v[202:205], v185 offset:16384
	ds_read_b128 v[206:209], v185 offset:17408
	ds_read_b128 v[210:213], v185 offset:18432
	ds_read_b128 v[214:217], v185 offset:19456
	ds_read_b128 v[218:221], v185 offset:20480
	ds_read_b128 v[222:225], v185 offset:21504
	ds_read_b128 v[226:229], v185 offset:22528
	ds_read_b128 v[234:237], v185 offset:23552
	global_load_lds_dwordx4 v0, s[58:59]
	s_add_i32 m0, s85, 0x2000
	s_add_u32 s86, s58, 0x20000
	s_addc_u32 s87, s59, 0
	s_add_i32 s85, s88, s71
	global_load_lds_dwordx4 v164, s[58:59]
	s_mov_b32 m0, s85
	s_mov_b64 s[100:101], s[60:61]
	global_load_lds_dwordx4 v0, s[86:87]
	s_add_i32 m0, s85, 0x2000
	s_nop 0
	global_load_lds_dwordx4 v164, s[86:87]
	s_mov_b32 m0, s12
	s_nop 0
	global_load_lds_dwordx4 v160, s[60:61]
	s_mov_b32 m0, s49
	s_nop 0
	global_load_lds_dwordx4 v162, s[60:61]
	s_waitcnt vmcnt(8)
	s_waitcnt lgkmcnt(0)
	s_barrier
	s_setprio 1
	s_waitcnt lgkmcnt(0)
	v_mfma_i32_16x16x64_i8 v[62:65], v[138:141], v[202:205], v[62:65]
	v_mfma_i32_16x16x64_i8 v[58:61], v[146:149], v[202:205], v[58:61]
	v_mfma_i32_16x16x64_i8 v[46:49], v[138:141], v[210:213], v[46:49]
	v_mfma_i32_16x16x64_i8 v[42:45], v[146:149], v[210:213], v[42:45]
	v_mfma_i32_16x16x64_i8 v[30:33], v[138:141], v[218:221], v[30:33]
	v_mfma_i32_16x16x64_i8 v[26:29], v[146:149], v[218:221], v[26:29]
	v_mfma_i32_16x16x64_i8 v[10:13], v[138:141], v[226:229], v[10:13]
	v_mfma_i32_16x16x64_i8 v[2:5], v[146:149], v[226:229], v[2:5]
	v_mfma_i32_16x16x64_i8 v[62:65], v[142:145], v[206:209], v[62:65]
	v_mfma_i32_16x16x64_i8 v[58:61], v[150:153], v[206:209], v[58:61]
	v_mfma_i32_16x16x64_i8 v[46:49], v[142:145], v[214:217], v[46:49]
	v_mfma_i32_16x16x64_i8 v[42:45], v[150:153], v[214:217], v[42:45]
	v_mfma_i32_16x16x64_i8 v[30:33], v[142:145], v[222:225], v[30:33]
	v_mfma_i32_16x16x64_i8 v[26:29], v[150:153], v[222:225], v[26:29]
	v_mfma_i32_16x16x64_i8 v[10:13], v[142:145], v[234:237], v[10:13]
	v_mfma_i32_16x16x64_i8 v[2:5], v[150:153], v[234:237], v[2:5]
	v_mfma_i32_16x16x64_i8 v[54:57], v[166:169], v[202:205], v[54:57]
	v_mfma_i32_16x16x64_i8 v[50:53], v[194:197], v[202:205], v[50:53]
	v_mfma_i32_16x16x64_i8 v[38:41], v[166:169], v[210:213], v[38:41]
	v_mfma_i32_16x16x64_i8 v[34:37], v[194:197], v[210:213], v[34:37]
	v_mfma_i32_16x16x64_i8 v[22:25], v[166:169], v[218:221], v[22:25]
	v_mfma_i32_16x16x64_i8 v[18:21], v[194:197], v[218:221], v[18:21]
	v_mfma_i32_16x16x64_i8 v[14:17], v[166:169], v[226:229], v[14:17]
	v_mfma_i32_16x16x64_i8 v[6:9], v[194:197], v[226:229], v[6:9]
	v_mfma_i32_16x16x64_i8 v[54:57], v[190:193], v[206:209], v[54:57]
	v_mfma_i32_16x16x64_i8 v[50:53], v[198:201], v[206:209], v[50:53]
	v_mfma_i32_16x16x64_i8 v[38:41], v[190:193], v[214:217], v[38:41]
	v_mfma_i32_16x16x64_i8 v[34:37], v[198:201], v[214:217], v[34:37]
	v_mfma_i32_16x16x64_i8 v[22:25], v[190:193], v[222:225], v[22:25]
	v_mfma_i32_16x16x64_i8 v[18:21], v[198:201], v[222:225], v[18:21]
	v_mfma_i32_16x16x64_i8 v[14:17], v[190:193], v[234:237], v[14:17]
	v_mfma_i32_16x16x64_i8 v[6:9], v[198:201], v[234:237], v[6:9]
	s_setprio 0
	s_barrier
	s_add_i32 s85, 0, 0x18000
	s_add_i32 s86, 0, 0x1c000
	v_add_u32_e32 v150, s85, v182
	v_add_u32_e32 v189, s86, v182
	ds_read_b128 v[138:141], v150
	ds_read_b128 v[142:145], v150 offset:1024
	ds_read_b128 v[146:149], v150 offset:2048
	ds_read_b128 v[150:153], v150 offset:3072
	ds_read_b128 v[166:169], v189
	ds_read_b128 v[190:193], v189 offset:1024
	ds_read_b128 v[194:197], v189 offset:2048
	ds_read_b128 v[198:201], v189 offset:3072
	s_add_u32 s60, s60, 0x20000
	s_addc_u32 s61, s61, 0
	s_mov_b32 m0, s72
	ds_read_b128 v[202:205], v185 offset:32768
	ds_read_b128 v[206:209], v185 offset:33792
	ds_read_b128 v[210:213], v185 offset:34816
	ds_read_b128 v[214:217], v185 offset:35840
	ds_read_b128 v[218:221], v185 offset:36864
	ds_read_b128 v[222:225], v185 offset:37888
	ds_read_b128 v[226:229], v185 offset:38912
	ds_read_b128 v[234:237], v185 offset:39936
	global_load_lds_dwordx4 v160, s[60:61]
	s_mov_b32 m0, s73
	s_nop 0
	global_load_lds_dwordx4 v162, s[60:61]
	s_waitcnt vmcnt(8)
	s_waitcnt lgkmcnt(0)
	s_barrier
	s_setprio 1
	s_waitcnt lgkmcnt(0)
	v_mfma_i32_16x16x64_i8 v[126:129], v[138:141], v[202:205], v[126:129]
	v_mfma_i32_16x16x64_i8 v[122:125], v[146:149], v[202:205], v[122:125]
	v_mfma_i32_16x16x64_i8 v[110:113], v[138:141], v[210:213], v[110:113]
	v_mfma_i32_16x16x64_i8 v[106:109], v[146:149], v[210:213], v[106:109]
	v_mfma_i32_16x16x64_i8 v[94:97], v[138:141], v[218:221], v[94:97]
	v_mfma_i32_16x16x64_i8 v[90:93], v[146:149], v[218:221], v[90:93]
	v_mfma_i32_16x16x64_i8 v[78:81], v[138:141], v[226:229], v[78:81]
	v_mfma_i32_16x16x64_i8 v[74:77], v[146:149], v[226:229], v[74:77]
	v_mfma_i32_16x16x64_i8 v[126:129], v[142:145], v[206:209], v[126:129]
	v_mfma_i32_16x16x64_i8 v[122:125], v[150:153], v[206:209], v[122:125]
	v_mfma_i32_16x16x64_i8 v[110:113], v[142:145], v[214:217], v[110:113]
	v_mfma_i32_16x16x64_i8 v[106:109], v[150:153], v[214:217], v[106:109]
	v_mfma_i32_16x16x64_i8 v[94:97], v[142:145], v[222:225], v[94:97]
	v_mfma_i32_16x16x64_i8 v[90:93], v[150:153], v[222:225], v[90:93]
	v_mfma_i32_16x16x64_i8 v[78:81], v[142:145], v[234:237], v[78:81]
	v_mfma_i32_16x16x64_i8 v[74:77], v[150:153], v[234:237], v[74:77]
	v_mfma_i32_16x16x64_i8 v[118:121], v[166:169], v[202:205], v[118:121]
	v_mfma_i32_16x16x64_i8 v[114:117], v[194:197], v[202:205], v[114:117]
	v_mfma_i32_16x16x64_i8 v[102:105], v[166:169], v[210:213], v[102:105]
	v_mfma_i32_16x16x64_i8 v[98:101], v[194:197], v[210:213], v[98:101]
	v_mfma_i32_16x16x64_i8 v[86:89], v[166:169], v[218:221], v[86:89]
	v_mfma_i32_16x16x64_i8 v[82:85], v[194:197], v[218:221], v[82:85]
	v_mfma_i32_16x16x64_i8 v[70:73], v[166:169], v[226:229], v[70:73]
	v_mfma_i32_16x16x64_i8 v[66:69], v[194:197], v[226:229], v[66:69]
	v_mfma_i32_16x16x64_i8 v[118:121], v[190:193], v[206:209], v[118:121]
	v_mfma_i32_16x16x64_i8 v[114:117], v[198:201], v[206:209], v[114:117]
	v_mfma_i32_16x16x64_i8 v[102:105], v[190:193], v[214:217], v[102:105]
	v_mfma_i32_16x16x64_i8 v[98:101], v[198:201], v[214:217], v[98:101]
	v_mfma_i32_16x16x64_i8 v[86:89], v[190:193], v[222:225], v[86:89]
	v_mfma_i32_16x16x64_i8 v[82:85], v[198:201], v[222:225], v[82:85]
	v_mfma_i32_16x16x64_i8 v[70:73], v[190:193], v[234:237], v[70:73]
	v_mfma_i32_16x16x64_i8 v[66:69], v[198:201], v[234:237], v[66:69]
	s_setprio 0
	s_barrier
	s_add_i32 s60, s85, s71
	s_add_u32 s98, s98, s14
	s_addc_u32 s99, s99, s15
	s_mov_b32 m0, s60
	ds_read_b128 v[202:205], v185 offset:49152
	ds_read_b128 v[206:209], v185 offset:50176
	ds_read_b128 v[210:213], v185 offset:51200
	ds_read_b128 v[214:217], v185 offset:52224
	ds_read_b128 v[218:221], v185 offset:53248
	ds_read_b128 v[222:225], v185 offset:54272
	ds_read_b128 v[226:229], v185 offset:55296
	ds_read_b128 v[234:237], v185 offset:56320
	global_load_lds_dwordx4 v0, s[98:99]
	s_add_i32 m0, s60, 0x2000
	s_add_u32 s58, s58, 0x20080
	s_addc_u32 s59, s59, 0
	s_add_i32 s60, s86, s71
	global_load_lds_dwordx4 v164, s[98:99]
	s_mov_b32 m0, s60
	s_nop 0
	global_load_lds_dwordx4 v0, s[58:59]
	s_add_i32 m0, s60, 0x2000
	s_nop 0
	global_load_lds_dwordx4 v164, s[58:59]
	s_add_u32 s100, s100, s14
	s_addc_u32 s101, s101, s15
	s_mov_b32 m0, s74
	s_nop 0
	global_load_lds_dwordx4 v160, s[100:101]
	s_mov_b32 m0, s75
	s_nop 0
	global_load_lds_dwordx4 v162, s[100:101]
	s_waitcnt vmcnt(8)
	s_waitcnt lgkmcnt(0)
	s_barrier
	s_setprio 1
	s_waitcnt lgkmcnt(0)
	v_mfma_i32_16x16x64_i8 v[62:65], v[138:141], v[202:205], v[62:65]
	v_mfma_i32_16x16x64_i8 v[58:61], v[146:149], v[202:205], v[58:61]
	v_mfma_i32_16x16x64_i8 v[46:49], v[138:141], v[210:213], v[46:49]
	v_mfma_i32_16x16x64_i8 v[42:45], v[146:149], v[210:213], v[42:45]
	v_mfma_i32_16x16x64_i8 v[30:33], v[138:141], v[218:221], v[30:33]
	v_mfma_i32_16x16x64_i8 v[26:29], v[146:149], v[218:221], v[26:29]
	v_mfma_i32_16x16x64_i8 v[10:13], v[138:141], v[226:229], v[10:13]
	v_mfma_i32_16x16x64_i8 v[2:5], v[146:149], v[226:229], v[2:5]
	v_mfma_i32_16x16x64_i8 v[62:65], v[142:145], v[206:209], v[62:65]
	v_mfma_i32_16x16x64_i8 v[58:61], v[150:153], v[206:209], v[58:61]
	v_mfma_i32_16x16x64_i8 v[46:49], v[142:145], v[214:217], v[46:49]
	v_mfma_i32_16x16x64_i8 v[42:45], v[150:153], v[214:217], v[42:45]
	v_mfma_i32_16x16x64_i8 v[30:33], v[142:145], v[222:225], v[30:33]
	v_mfma_i32_16x16x64_i8 v[26:29], v[150:153], v[222:225], v[26:29]
	v_mfma_i32_16x16x64_i8 v[10:13], v[142:145], v[234:237], v[10:13]
	v_mfma_i32_16x16x64_i8 v[2:5], v[150:153], v[234:237], v[2:5]
	v_mfma_i32_16x16x64_i8 v[54:57], v[166:169], v[202:205], v[54:57]
	v_mfma_i32_16x16x64_i8 v[50:53], v[194:197], v[202:205], v[50:53]
	v_mfma_i32_16x16x64_i8 v[38:41], v[166:169], v[210:213], v[38:41]
	v_mfma_i32_16x16x64_i8 v[34:37], v[194:197], v[210:213], v[34:37]
	v_mfma_i32_16x16x64_i8 v[22:25], v[166:169], v[218:221], v[22:25]
	v_mfma_i32_16x16x64_i8 v[18:21], v[194:197], v[218:221], v[18:21]
	v_mfma_i32_16x16x64_i8 v[14:17], v[166:169], v[226:229], v[14:17]
	v_mfma_i32_16x16x64_i8 v[6:9], v[194:197], v[226:229], v[6:9]
	v_mfma_i32_16x16x64_i8 v[54:57], v[190:193], v[206:209], v[54:57]
	v_mfma_i32_16x16x64_i8 v[50:53], v[198:201], v[206:209], v[50:53]
	v_mfma_i32_16x16x64_i8 v[38:41], v[190:193], v[214:217], v[38:41]
	v_mfma_i32_16x16x64_i8 v[34:37], v[198:201], v[214:217], v[34:37]
	v_mfma_i32_16x16x64_i8 v[22:25], v[190:193], v[222:225], v[22:25]
	v_mfma_i32_16x16x64_i8 v[18:21], v[198:201], v[222:225], v[18:21]
	v_mfma_i32_16x16x64_i8 v[14:17], v[190:193], v[234:237], v[14:17]
	v_mfma_i32_16x16x64_i8 v[6:9], v[198:201], v[234:237], v[6:9]
	s_setprio 0
	s_barrier
	s_add_i32 s84, s84, 2
	s_add_u32 s56, s56, 0x100
	s_addc_u32 s57, s57, 0
	s_add_u32 s82, s82, 0x100
	s_addc_u32 s83, s83, 0
	s_cmp_gt_u32 s84, 5
	s_cbranch_scc0 .LBB0_2985
	s_and_b64 vcc, exec, s[40:41]
	s_cbranch_vccz .LBB0_2988
	s_barrier

.LBB0_3015:
	s_add_u32 s8, s6, 0xfffe0080
	s_addc_u32 s9, s7, -1
	s_add_i32 s72, 0, 0x10000
	s_cmp_eq_u32 s71, 4
	s_cselect_b32 s55, s43, s9
	s_cselect_b32 s54, s49, s8
	v_add_u32_e32 v0, s72, v188
	s_cselect_b32 s9, s39, s70
	s_cselect_b32 s8, s41, s69
	s_add_i32 s74, 0, 0x14000
	ds_read_b128 v[132:135], v0
	ds_read_b128 v[136:139], v0 offset:1024
	ds_read_b128 v[140:143], v0 offset:2048
	ds_read_b128 v[144:147], v0 offset:3072
	v_add_u32_e32 v0, s74, v188
	ds_read_b128 v[148:151], v0
	ds_read_b128 v[152:155], v0 offset:1024
	ds_read_b128 v[176:179], v0 offset:2048
	ds_read_b128 v[180:183], v0 offset:3072
	s_add_i32 m0, s45, 0xc000
	ds_read_b128 v[198:201], v196
	ds_read_b128 v[202:205], v196 offset:1024
	ds_read_b128 v[206:209], v196 offset:2048
	ds_read_b128 v[210:213], v196 offset:3072
	ds_read_b128 v[214:217], v196 offset:4096
	ds_read_b128 v[218:221], v196 offset:5120
	ds_read_b128 v[222:225], v196 offset:6144
	ds_read_b128 v[226:229], v196 offset:7168
	global_load_lds_dwordx4 v172, s[6:7]
	s_add_i32 m0, s45, 0xe000
	s_nop 0
	global_load_lds_dwordx4 v174, s[6:7]
	s_waitcnt vmcnt(8)
	s_waitcnt lgkmcnt(0)
	s_barrier
	s_setprio 1
	s_waitcnt lgkmcnt(0)
	v_mfma_f32_16x16x32_bf16 v[128:131], v[132:135], v[198:201], v[128:131]
	v_mfma_f32_16x16x32_bf16 v[124:127], v[140:143], v[198:201], v[124:127]
	v_mfma_f32_16x16x32_bf16 v[120:123], v[132:135], v[206:209], v[120:123]
	v_mfma_f32_16x16x32_bf16 v[116:119], v[140:143], v[206:209], v[116:119]
	v_mfma_f32_16x16x32_bf16 v[112:115], v[132:135], v[214:217], v[112:115]
	v_mfma_f32_16x16x32_bf16 v[108:111], v[140:143], v[214:217], v[108:111]
	v_mfma_f32_16x16x32_bf16 v[104:107], v[132:135], v[222:225], v[104:107]
	v_mfma_f32_16x16x32_bf16 v[100:103], v[140:143], v[222:225], v[100:103]
	v_mfma_f32_16x16x32_bf16 v[128:131], v[136:139], v[202:205], v[128:131]
	v_mfma_f32_16x16x32_bf16 v[124:127], v[144:147], v[202:205], v[124:127]
	v_mfma_f32_16x16x32_bf16 v[120:123], v[136:139], v[210:213], v[120:123]
	v_mfma_f32_16x16x32_bf16 v[116:119], v[144:147], v[210:213], v[116:119]
	v_mfma_f32_16x16x32_bf16 v[112:115], v[136:139], v[218:221], v[112:115]
	v_mfma_f32_16x16x32_bf16 v[108:111], v[144:147], v[218:221], v[108:111]
	v_mfma_f32_16x16x32_bf16 v[104:107], v[136:139], v[226:229], v[104:107]
	v_mfma_f32_16x16x32_bf16 v[100:103], v[144:147], v[226:229], v[100:103]
	v_mfma_f32_16x16x32_bf16 v[96:99], v[148:151], v[198:201], v[96:99]
	v_mfma_f32_16x16x32_bf16 v[92:95], v[176:179], v[198:201], v[92:95]
	v_mfma_f32_16x16x32_bf16 v[88:91], v[148:151], v[206:209], v[88:91]
	v_mfma_f32_16x16x32_bf16 v[84:87], v[176:179], v[206:209], v[84:87]
	v_mfma_f32_16x16x32_bf16 v[80:83], v[148:151], v[214:217], v[80:83]
	v_mfma_f32_16x16x32_bf16 v[76:79], v[176:179], v[214:217], v[76:79]
	v_mfma_f32_16x16x32_bf16 v[72:75], v[148:151], v[222:225], v[72:75]
	v_mfma_f32_16x16x32_bf16 v[68:71], v[176:179], v[222:225], v[68:71]
	v_mfma_f32_16x16x32_bf16 v[96:99], v[152:155], v[202:205], v[96:99]
	v_mfma_f32_16x16x32_bf16 v[92:95], v[180:183], v[202:205], v[92:95]
	v_mfma_f32_16x16x32_bf16 v[88:91], v[152:155], v[210:213], v[88:91]
	v_mfma_f32_16x16x32_bf16 v[84:87], v[180:183], v[210:213], v[84:87]
	v_mfma_f32_16x16x32_bf16 v[80:83], v[152:155], v[218:221], v[80:83]
	v_mfma_f32_16x16x32_bf16 v[76:79], v[180:183], v[218:221], v[76:79]
	v_mfma_f32_16x16x32_bf16 v[72:75], v[152:155], v[226:229], v[72:75]
	v_mfma_f32_16x16x32_bf16 v[68:71], v[180:183], v[226:229], v[68:71]
	s_setprio 0
	s_barrier
	s_add_i32 s72, s72, s60
	s_mov_b64 s[98:99], s[8:9]
	s_mov_b32 m0, s72
	ds_read_b128 v[198:201], v196 offset:16384
	ds_read_b128 v[202:205], v196 offset:17408
	ds_read_b128 v[206:209], v196 offset:18432
	ds_read_b128 v[210:213], v196 offset:19456
	ds_read_b128 v[214:217], v196 offset:20480
	ds_read_b128 v[218:221], v196 offset:21504
	ds_read_b128 v[222:225], v196 offset:22528
	ds_read_b128 v[226:229], v196 offset:23552
	global_load_lds_dwordx4 v166, s[8:9]
	s_add_i32 m0, s72, 0x2000
	s_add_u32 s72, s8, 0x20000
	s_addc_u32 s73, s9, 0
	s_add_i32 s74, s74, s60
	global_load_lds_dwordx4 v164, s[8:9]
	s_mov_b32 m0, s74
	s_mov_b64 s[100:101], s[54:55]
	global_load_lds_dwordx4 v166, s[72:73]
	s_add_i32 m0, s74, 0x2000
	s_nop 0
	global_load_lds_dwordx4 v164, s[72:73]
	s_mov_b32 m0, s45
	s_nop 0
	global_load_lds_dwordx4 v160, s[54:55]
	s_mov_b32 m0, s61
	s_nop 0
	global_load_lds_dwordx4 v162, s[54:55]
	s_waitcnt vmcnt(8)
	s_waitcnt lgkmcnt(0)
	s_barrier
	s_setprio 1
	s_waitcnt lgkmcnt(0)
	v_mfma_f32_16x16x32_bf16 v[64:67], v[132:135], v[198:201], v[64:67]
	v_mfma_f32_16x16x32_bf16 v[60:63], v[140:143], v[198:201], v[60:63]
	v_mfma_f32_16x16x32_bf16 v[56:59], v[132:135], v[206:209], v[56:59]
	v_mfma_f32_16x16x32_bf16 v[52:55], v[140:143], v[206:209], v[52:55]
	v_mfma_f32_16x16x32_bf16 v[48:51], v[132:135], v[214:217], v[48:51]
	v_mfma_f32_16x16x32_bf16 v[44:47], v[140:143], v[214:217], v[44:47]
	v_mfma_f32_16x16x32_bf16 v[40:43], v[132:135], v[222:225], v[40:43]
	v_mfma_f32_16x16x32_bf16 v[36:39], v[140:143], v[222:225], v[36:39]
	v_mfma_f32_16x16x32_bf16 v[64:67], v[136:139], v[202:205], v[64:67]
	v_mfma_f32_16x16x32_bf16 v[60:63], v[144:147], v[202:205], v[60:63]
	v_mfma_f32_16x16x32_bf16 v[56:59], v[136:139], v[210:213], v[56:59]
	v_mfma_f32_16x16x32_bf16 v[52:55], v[144:147], v[210:213], v[52:55]
	v_mfma_f32_16x16x32_bf16 v[48:51], v[136:139], v[218:221], v[48:51]
	v_mfma_f32_16x16x32_bf16 v[44:47], v[144:147], v[218:221], v[44:47]
	v_mfma_f32_16x16x32_bf16 v[40:43], v[136:139], v[226:229], v[40:43]
	v_mfma_f32_16x16x32_bf16 v[36:39], v[144:147], v[226:229], v[36:39]
	v_mfma_f32_16x16x32_bf16 v[32:35], v[148:151], v[198:201], v[32:35]
	v_mfma_f32_16x16x32_bf16 v[28:31], v[176:179], v[198:201], v[28:31]
	v_mfma_f32_16x16x32_bf16 v[24:27], v[148:151], v[206:209], v[24:27]
	v_mfma_f32_16x16x32_bf16 v[20:23], v[176:179], v[206:209], v[20:23]
	v_mfma_f32_16x16x32_bf16 v[16:19], v[148:151], v[214:217], v[16:19]
	v_mfma_f32_16x16x32_bf16 v[12:15], v[176:179], v[214:217], v[12:15]
	v_mfma_f32_16x16x32_bf16 v[8:11], v[148:151], v[222:225], v[8:11]
	v_mfma_f32_16x16x32_bf16 v[2:5], v[176:179], v[222:225], v[4:7]
	v_mfma_f32_16x16x32_bf16 v[32:35], v[152:155], v[202:205], v[32:35]
	v_mfma_f32_16x16x32_bf16 v[28:31], v[180:183], v[202:205], v[28:31]
	v_mfma_f32_16x16x32_bf16 v[24:27], v[152:155], v[210:213], v[24:27]
	v_mfma_f32_16x16x32_bf16 v[20:23], v[180:183], v[210:213], v[20:23]
	v_mfma_f32_16x16x32_bf16 v[16:19], v[152:155], v[218:221], v[16:19]
	v_mfma_f32_16x16x32_bf16 v[12:15], v[180:183], v[218:221], v[12:15]
	v_mfma_f32_16x16x32_bf16 v[8:11], v[152:155], v[226:229], v[8:11]
	v_mfma_f32_16x16x32_bf16 v[2:5], v[180:183], v[226:229], v[2:5]
	s_setprio 0
	s_barrier
	s_add_i32 s72, 0, 0x18000
	v_add_u32_e32 v0, s72, v188
	s_add_i32 s73, 0, 0x1c000
	ds_read_b128 v[132:135], v0
	ds_read_b128 v[136:139], v0 offset:1024
	ds_read_b128 v[140:143], v0 offset:2048
	ds_read_b128 v[144:147], v0 offset:3072
	v_add_u32_e32 v0, s73, v188
	ds_read_b128 v[148:151], v0
	ds_read_b128 v[152:155], v0 offset:1024
	ds_read_b128 v[176:179], v0 offset:2048
	ds_read_b128 v[180:183], v0 offset:3072
	s_add_u32 s54, s54, 0x20000
	s_addc_u32 s55, s55, 0
	s_mov_b32 m0, s62
	ds_read_b128 v[198:201], v196 offset:32768
	ds_read_b128 v[202:205], v196 offset:33792
	ds_read_b128 v[206:209], v196 offset:34816
	ds_read_b128 v[210:213], v196 offset:35840
	ds_read_b128 v[214:217], v196 offset:36864
	ds_read_b128 v[218:221], v196 offset:37888
	ds_read_b128 v[222:225], v196 offset:38912
	ds_read_b128 v[226:229], v196 offset:39936
	global_load_lds_dwordx4 v160, s[54:55]
	s_mov_b32 m0, s63
	s_nop 0
	global_load_lds_dwordx4 v162, s[54:55]
	s_waitcnt vmcnt(8)
	s_waitcnt lgkmcnt(0)
	s_barrier
	s_setprio 1
	s_waitcnt lgkmcnt(0)
	v_mfma_f32_16x16x32_bf16 v[128:131], v[132:135], v[198:201], v[128:131]
	v_mfma_f32_16x16x32_bf16 v[124:127], v[140:143], v[198:201], v[124:127]
	v_mfma_f32_16x16x32_bf16 v[120:123], v[132:135], v[206:209], v[120:123]
	v_mfma_f32_16x16x32_bf16 v[116:119], v[140:143], v[206:209], v[116:119]
	v_mfma_f32_16x16x32_bf16 v[112:115], v[132:135], v[214:217], v[112:115]
	v_mfma_f32_16x16x32_bf16 v[108:111], v[140:143], v[214:217], v[108:111]
	v_mfma_f32_16x16x32_bf16 v[104:107], v[132:135], v[222:225], v[104:107]
	v_mfma_f32_16x16x32_bf16 v[100:103], v[140:143], v[222:225], v[100:103]
	v_mfma_f32_16x16x32_bf16 v[128:131], v[136:139], v[202:205], v[128:131]
	v_mfma_f32_16x16x32_bf16 v[124:127], v[144:147], v[202:205], v[124:127]
	v_mfma_f32_16x16x32_bf16 v[120:123], v[136:139], v[210:213], v[120:123]
	v_mfma_f32_16x16x32_bf16 v[116:119], v[144:147], v[210:213], v[116:119]
	v_mfma_f32_16x16x32_bf16 v[112:115], v[136:139], v[218:221], v[112:115]
	v_mfma_f32_16x16x32_bf16 v[108:111], v[144:147], v[218:221], v[108:111]
	v_mfma_f32_16x16x32_bf16 v[104:107], v[136:139], v[226:229], v[104:107]
	v_mfma_f32_16x16x32_bf16 v[100:103], v[144:147], v[226:229], v[100:103]
	v_mfma_f32_16x16x32_bf16 v[96:99], v[148:151], v[198:201], v[96:99]
	v_mfma_f32_16x16x32_bf16 v[92:95], v[176:179], v[198:201], v[92:95]
	v_mfma_f32_16x16x32_bf16 v[88:91], v[148:151], v[206:209], v[88:91]
	v_mfma_f32_16x16x32_bf16 v[84:87], v[176:179], v[206:209], v[84:87]
	v_mfma_f32_16x16x32_bf16 v[80:83], v[148:151], v[214:217], v[80:83]
	v_mfma_f32_16x16x32_bf16 v[76:79], v[176:179], v[214:217], v[76:79]
	v_mfma_f32_16x16x32_bf16 v[72:75], v[148:151], v[222:225], v[72:75]
	v_mfma_f32_16x16x32_bf16 v[68:71], v[176:179], v[222:225], v[68:71]
	v_mfma_f32_16x16x32_bf16 v[96:99], v[152:155], v[202:205], v[96:99]
	v_mfma_f32_16x16x32_bf16 v[92:95], v[180:183], v[202:205], v[92:95]
	v_mfma_f32_16x16x32_bf16 v[88:91], v[152:155], v[210:213], v[88:91]
	v_mfma_f32_16x16x32_bf16 v[84:87], v[180:183], v[210:213], v[84:87]
	v_mfma_f32_16x16x32_bf16 v[80:83], v[152:155], v[218:221], v[80:83]
	v_mfma_f32_16x16x32_bf16 v[76:79], v[180:183], v[218:221], v[76:79]
	v_mfma_f32_16x16x32_bf16 v[72:75], v[152:155], v[226:229], v[72:75]
	v_mfma_f32_16x16x32_bf16 v[68:71], v[180:183], v[226:229], v[68:71]
	s_setprio 0
	s_barrier
	s_add_i32 s54, s72, s60
	s_add_u32 s98, s98, s14
	s_addc_u32 s99, s99, s15
	s_mov_b32 m0, s54
	ds_read_b128 v[198:201], v196 offset:49152
	ds_read_b128 v[202:205], v196 offset:50176
	ds_read_b128 v[206:209], v196 offset:51200
	ds_read_b128 v[210:213], v196 offset:52224
	ds_read_b128 v[214:217], v196 offset:53248
	ds_read_b128 v[218:221], v196 offset:54272
	ds_read_b128 v[222:225], v196 offset:55296
	ds_read_b128 v[226:229], v196 offset:56320
	global_load_lds_dwordx4 v166, s[98:99]
	s_add_i32 m0, s54, 0x2000
	s_add_u32 s8, s8, 0x20080
	s_addc_u32 s9, s9, 0
	s_add_i32 s54, s73, s60
	global_load_lds_dwordx4 v164, s[98:99]
	s_mov_b32 m0, s54
	s_nop 0
	global_load_lds_dwordx4 v166, s[8:9]
	s_add_i32 m0, s54, 0x2000
	s_nop 0
	global_load_lds_dwordx4 v164, s[8:9]
	s_add_u32 s100, s100, s14
	s_addc_u32 s101, s101, s15
	s_mov_b32 m0, s65
	s_nop 0
	global_load_lds_dwordx4 v160, s[100:101]
	s_mov_b32 m0, s66
	s_nop 0
	global_load_lds_dwordx4 v162, s[100:101]
	s_waitcnt vmcnt(8)
	s_waitcnt lgkmcnt(0)
	s_barrier
	s_setprio 1
	s_waitcnt lgkmcnt(0)
	v_mfma_f32_16x16x32_bf16 v[64:67], v[132:135], v[198:201], v[64:67]
	v_mfma_f32_16x16x32_bf16 v[60:63], v[140:143], v[198:201], v[60:63]
	v_mfma_f32_16x16x32_bf16 v[56:59], v[132:135], v[206:209], v[56:59]
	v_mfma_f32_16x16x32_bf16 v[52:55], v[140:143], v[206:209], v[52:55]
	v_mfma_f32_16x16x32_bf16 v[48:51], v[132:135], v[214:217], v[48:51]
	v_mfma_f32_16x16x32_bf16 v[44:47], v[140:143], v[214:217], v[44:47]
	v_mfma_f32_16x16x32_bf16 v[40:43], v[132:135], v[222:225], v[40:43]
	v_mfma_f32_16x16x32_bf16 v[36:39], v[140:143], v[222:225], v[36:39]
	v_mfma_f32_16x16x32_bf16 v[64:67], v[136:139], v[202:205], v[64:67]
	v_mfma_f32_16x16x32_bf16 v[60:63], v[144:147], v[202:205], v[60:63]
	v_mfma_f32_16x16x32_bf16 v[56:59], v[136:139], v[210:213], v[56:59]
	v_mfma_f32_16x16x32_bf16 v[52:55], v[144:147], v[210:213], v[52:55]
	v_mfma_f32_16x16x32_bf16 v[48:51], v[136:139], v[218:221], v[48:51]
	v_mfma_f32_16x16x32_bf16 v[44:47], v[144:147], v[218:221], v[44:47]
	v_mfma_f32_16x16x32_bf16 v[40:43], v[136:139], v[226:229], v[40:43]
	v_mfma_f32_16x16x32_bf16 v[36:39], v[144:147], v[226:229], v[36:39]
	v_mfma_f32_16x16x32_bf16 v[32:35], v[148:151], v[198:201], v[32:35]
	v_mfma_f32_16x16x32_bf16 v[28:31], v[176:179], v[198:201], v[28:31]
	v_mfma_f32_16x16x32_bf16 v[24:27], v[148:151], v[206:209], v[24:27]
	v_mfma_f32_16x16x32_bf16 v[20:23], v[176:179], v[206:209], v[20:23]
	v_mfma_f32_16x16x32_bf16 v[16:19], v[148:151], v[214:217], v[16:19]
	v_mfma_f32_16x16x32_bf16 v[12:15], v[176:179], v[214:217], v[12:15]
	v_mfma_f32_16x16x32_bf16 v[6:9], v[148:151], v[222:225], v[8:11]
	v_mfma_f32_16x16x32_bf16 v[2:5], v[176:179], v[222:225], v[2:5]
	v_mfma_f32_16x16x32_bf16 v[32:35], v[152:155], v[202:205], v[32:35]
	v_mfma_f32_16x16x32_bf16 v[28:31], v[180:183], v[202:205], v[28:31]
	v_mfma_f32_16x16x32_bf16 v[24:27], v[152:155], v[210:213], v[24:27]
	v_mfma_f32_16x16x32_bf16 v[20:23], v[180:183], v[210:213], v[20:23]
	v_mfma_f32_16x16x32_bf16 v[16:19], v[152:155], v[218:221], v[16:19]
	v_mfma_f32_16x16x32_bf16 v[12:15], v[180:183], v[218:221], v[12:15]
	v_mfma_f32_16x16x32_bf16 v[8:11], v[152:155], v[226:229], v[6:9]
	v_mfma_f32_16x16x32_bf16 v[4:7], v[180:183], v[226:229], v[2:5]
	s_setprio 0
	s_barrier
	s_add_i32 s71, s71, 2
	s_add_u32 s6, s6, 0x100
	s_addc_u32 s7, s7, 0
	s_add_u32 s69, s69, 0x100
	s_addc_u32 s70, s70, 0
	s_cmp_gt_u32 s71, 5
	s_cbranch_scc0 .LBB0_3015
	s_and_b64 vcc, exec, s[36:37]
	s_cbranch_vccz .LBB0_3018
	s_barrier

.LBB0_3227:
	s_add_u32 s58, s48, 0xfffc0080
	s_addc_u32 s59, s49, -1
	s_add_i32 s64, 0, 0x10000
	s_cmp_eq_u32 s63, 12
	s_cselect_b32 s61, s14, s59
	s_cselect_b32 s60, s45, s58
	v_add_u32_e32 v0, s64, v169
	s_cselect_b32 s59, s43, s62
	s_cselect_b32 s58, s55, s57
	s_add_i32 s66, 0, 0x14000
	ds_read_b128 v[148:151], v0
	ds_read_b128 v[152:155], v0 offset:1024
	ds_read_b128 v[156:159], v0 offset:2048
	ds_read_b128 v[190:193], v0 offset:3072
	v_add_u32_e32 v0, s66, v169
	ds_read_b128 v[194:197], v0
	ds_read_b128 v[198:201], v0 offset:1024
	ds_read_b128 v[202:205], v0 offset:2048
	ds_read_b128 v[206:209], v0 offset:3072
	s_add_i32 m0, s80, 0xc000
	ds_read_b128 v[210:213], v188
	ds_read_b128 v[214:217], v188 offset:1024
	ds_read_b128 v[218:221], v188 offset:2048
	ds_read_b128 v[222:225], v188 offset:3072
	ds_read_b128 v[226:229], v188 offset:4096
	ds_read_b128 v[234:237], v188 offset:5120
	ds_read_b128 v[238:241], v188 offset:6144
	ds_read_b128 v[242:245], v188 offset:7168
	global_load_lds_dwordx4 v144, s[48:49]
	s_add_i32 m0, s80, 0xe000
	s_nop 0
	global_load_lds_dwordx4 v146, s[48:49]
	s_waitcnt vmcnt(8)
	s_waitcnt lgkmcnt(0)
	s_barrier
	s_setprio 1
	s_waitcnt lgkmcnt(0)
	v_mfma_f32_16x16x32_bf16 v[126:129], v[148:151], v[210:213], v[126:129]
	v_mfma_f32_16x16x32_bf16 v[122:125], v[156:159], v[210:213], v[122:125]
	v_mfma_f32_16x16x32_bf16 v[110:113], v[148:151], v[218:221], v[110:113]
	v_mfma_f32_16x16x32_bf16 v[106:109], v[156:159], v[218:221], v[106:109]
	v_mfma_f32_16x16x32_bf16 v[94:97], v[148:151], v[226:229], v[94:97]
	v_mfma_f32_16x16x32_bf16 v[90:93], v[156:159], v[226:229], v[90:93]
	v_mfma_f32_16x16x32_bf16 v[78:81], v[148:151], v[238:241], v[78:81]
	v_mfma_f32_16x16x32_bf16 v[74:77], v[156:159], v[238:241], v[74:77]
	v_mfma_f32_16x16x32_bf16 v[126:129], v[152:155], v[214:217], v[126:129]
	v_mfma_f32_16x16x32_bf16 v[122:125], v[190:193], v[214:217], v[122:125]
	v_mfma_f32_16x16x32_bf16 v[110:113], v[152:155], v[222:225], v[110:113]
	v_mfma_f32_16x16x32_bf16 v[106:109], v[190:193], v[222:225], v[106:109]
	v_mfma_f32_16x16x32_bf16 v[94:97], v[152:155], v[234:237], v[94:97]
	v_mfma_f32_16x16x32_bf16 v[90:93], v[190:193], v[234:237], v[90:93]
	v_mfma_f32_16x16x32_bf16 v[78:81], v[152:155], v[242:245], v[78:81]
	v_mfma_f32_16x16x32_bf16 v[74:77], v[190:193], v[242:245], v[74:77]
	v_mfma_f32_16x16x32_bf16 v[118:121], v[194:197], v[210:213], v[118:121]
	v_mfma_f32_16x16x32_bf16 v[114:117], v[202:205], v[210:213], v[114:117]
	v_mfma_f32_16x16x32_bf16 v[102:105], v[194:197], v[218:221], v[102:105]
	v_mfma_f32_16x16x32_bf16 v[98:101], v[202:205], v[218:221], v[98:101]
	v_mfma_f32_16x16x32_bf16 v[86:89], v[194:197], v[226:229], v[86:89]
	v_mfma_f32_16x16x32_bf16 v[82:85], v[202:205], v[226:229], v[82:85]
	v_mfma_f32_16x16x32_bf16 v[70:73], v[194:197], v[238:241], v[70:73]
	v_mfma_f32_16x16x32_bf16 v[66:69], v[202:205], v[238:241], v[66:69]
	v_mfma_f32_16x16x32_bf16 v[118:121], v[198:201], v[214:217], v[118:121]
	v_mfma_f32_16x16x32_bf16 v[114:117], v[206:209], v[214:217], v[114:117]
	v_mfma_f32_16x16x32_bf16 v[102:105], v[198:201], v[222:225], v[102:105]
	v_mfma_f32_16x16x32_bf16 v[98:101], v[206:209], v[222:225], v[98:101]
	v_mfma_f32_16x16x32_bf16 v[86:89], v[198:201], v[234:237], v[86:89]
	v_mfma_f32_16x16x32_bf16 v[82:85], v[206:209], v[234:237], v[82:85]
	v_mfma_f32_16x16x32_bf16 v[70:73], v[198:201], v[242:245], v[70:73]
	v_mfma_f32_16x16x32_bf16 v[66:69], v[206:209], v[242:245], v[66:69]
	s_setprio 0
	s_barrier
	s_add_i32 s64, s64, s79
	s_mov_b64 s[98:99], s[58:59]
	s_mov_b32 m0, s64
	ds_read_b128 v[210:213], v188 offset:16384
	ds_read_b128 v[214:217], v188 offset:17408
	ds_read_b128 v[218:221], v188 offset:18432
	ds_read_b128 v[222:225], v188 offset:19456
	ds_read_b128 v[226:229], v188 offset:20480
	ds_read_b128 v[234:237], v188 offset:21504
	ds_read_b128 v[238:241], v188 offset:22528
	ds_read_b128 v[242:245], v188 offset:23552
	global_load_lds_dwordx4 v136, s[58:59]
	s_add_i32 m0, s64, 0x2000
	s_add_u32 s64, s58, 0x40000
	s_addc_u32 s65, s59, 0
	s_add_i32 s66, s66, s79
	global_load_lds_dwordx4 v140, s[58:59]
	s_mov_b32 m0, s66
	s_mov_b64 s[100:101], s[60:61]
	global_load_lds_dwordx4 v136, s[64:65]
	s_add_i32 m0, s66, 0x2000
	s_nop 0
	global_load_lds_dwordx4 v140, s[64:65]
	s_mov_b32 m0, s80
	s_nop 0
	global_load_lds_dwordx4 v134, s[60:61]
	s_mov_b32 m0, s81
	s_nop 0
	global_load_lds_dwordx4 v138, s[60:61]
	s_waitcnt vmcnt(8)
	s_waitcnt lgkmcnt(0)
	s_barrier
	s_setprio 1
	s_waitcnt lgkmcnt(0)
	v_mfma_f32_16x16x32_bf16 v[62:65], v[148:151], v[210:213], v[62:65]
	v_mfma_f32_16x16x32_bf16 v[58:61], v[156:159], v[210:213], v[58:61]
	v_mfma_f32_16x16x32_bf16 v[46:49], v[148:151], v[218:221], v[46:49]
	v_mfma_f32_16x16x32_bf16 v[42:45], v[156:159], v[218:221], v[42:45]
	v_mfma_f32_16x16x32_bf16 v[30:33], v[148:151], v[226:229], v[30:33]
	v_mfma_f32_16x16x32_bf16 v[26:29], v[156:159], v[226:229], v[26:29]
	v_mfma_f32_16x16x32_bf16 v[14:17], v[148:151], v[238:241], v[14:17]
	v_mfma_f32_16x16x32_bf16 v[10:13], v[156:159], v[238:241], v[10:13]
	v_mfma_f32_16x16x32_bf16 v[62:65], v[152:155], v[214:217], v[62:65]
	v_mfma_f32_16x16x32_bf16 v[58:61], v[190:193], v[214:217], v[58:61]
	v_mfma_f32_16x16x32_bf16 v[46:49], v[152:155], v[222:225], v[46:49]
	v_mfma_f32_16x16x32_bf16 v[42:45], v[190:193], v[222:225], v[42:45]
	v_mfma_f32_16x16x32_bf16 v[30:33], v[152:155], v[234:237], v[30:33]
	v_mfma_f32_16x16x32_bf16 v[26:29], v[190:193], v[234:237], v[26:29]
	v_mfma_f32_16x16x32_bf16 v[14:17], v[152:155], v[242:245], v[14:17]
	v_mfma_f32_16x16x32_bf16 v[10:13], v[190:193], v[242:245], v[10:13]
	v_mfma_f32_16x16x32_bf16 v[54:57], v[194:197], v[210:213], v[54:57]
	v_mfma_f32_16x16x32_bf16 v[50:53], v[202:205], v[210:213], v[50:53]
	v_mfma_f32_16x16x32_bf16 v[38:41], v[194:197], v[218:221], v[38:41]
	v_mfma_f32_16x16x32_bf16 v[34:37], v[202:205], v[218:221], v[34:37]
	v_mfma_f32_16x16x32_bf16 v[22:25], v[194:197], v[226:229], v[22:25]
	v_mfma_f32_16x16x32_bf16 v[18:21], v[202:205], v[226:229], v[18:21]
	v_mfma_f32_16x16x32_bf16 v[6:9], v[194:197], v[238:241], v[6:9]
	v_mfma_f32_16x16x32_bf16 v[2:5], v[202:205], v[238:241], v[2:5]
	v_mfma_f32_16x16x32_bf16 v[54:57], v[198:201], v[214:217], v[54:57]
	v_mfma_f32_16x16x32_bf16 v[50:53], v[206:209], v[214:217], v[50:53]
	v_mfma_f32_16x16x32_bf16 v[38:41], v[198:201], v[222:225], v[38:41]
	v_mfma_f32_16x16x32_bf16 v[34:37], v[206:209], v[222:225], v[34:37]
	v_mfma_f32_16x16x32_bf16 v[22:25], v[198:201], v[234:237], v[22:25]
	v_mfma_f32_16x16x32_bf16 v[18:21], v[206:209], v[234:237], v[18:21]
	v_mfma_f32_16x16x32_bf16 v[6:9], v[198:201], v[242:245], v[6:9]
	v_mfma_f32_16x16x32_bf16 v[2:5], v[206:209], v[242:245], v[2:5]
	s_setprio 0
	s_barrier
	s_add_i32 s64, 0, 0x18000
	v_add_u32_e32 v0, s64, v169
	s_add_i32 s65, 0, 0x1c000
	ds_read_b128 v[148:151], v0
	ds_read_b128 v[152:155], v0 offset:1024
	ds_read_b128 v[156:159], v0 offset:2048
	ds_read_b128 v[190:193], v0 offset:3072
	v_add_u32_e32 v0, s65, v169
	ds_read_b128 v[194:197], v0
	ds_read_b128 v[198:201], v0 offset:1024
	ds_read_b128 v[202:205], v0 offset:2048
	ds_read_b128 v[206:209], v0 offset:3072
	s_add_u32 s60, s60, 0x40000
	s_addc_u32 s61, s61, 0
	s_mov_b32 m0, s82
	ds_read_b128 v[210:213], v188 offset:32768
	ds_read_b128 v[214:217], v188 offset:33792
	ds_read_b128 v[218:221], v188 offset:34816
	ds_read_b128 v[222:225], v188 offset:35840
	ds_read_b128 v[226:229], v188 offset:36864
	ds_read_b128 v[234:237], v188 offset:37888
	ds_read_b128 v[238:241], v188 offset:38912
	ds_read_b128 v[242:245], v188 offset:39936
	global_load_lds_dwordx4 v134, s[60:61]
	s_mov_b32 m0, s83
	s_nop 0
	global_load_lds_dwordx4 v138, s[60:61]
	s_waitcnt vmcnt(8)
	s_waitcnt lgkmcnt(0)
	s_barrier
	s_setprio 1
	s_waitcnt lgkmcnt(0)
	v_mfma_f32_16x16x32_bf16 v[126:129], v[148:151], v[210:213], v[126:129]
	v_mfma_f32_16x16x32_bf16 v[122:125], v[156:159], v[210:213], v[122:125]
	v_mfma_f32_16x16x32_bf16 v[110:113], v[148:151], v[218:221], v[110:113]
	v_mfma_f32_16x16x32_bf16 v[106:109], v[156:159], v[218:221], v[106:109]
	v_mfma_f32_16x16x32_bf16 v[94:97], v[148:151], v[226:229], v[94:97]
	v_mfma_f32_16x16x32_bf16 v[90:93], v[156:159], v[226:229], v[90:93]
	v_mfma_f32_16x16x32_bf16 v[78:81], v[148:151], v[238:241], v[78:81]
	v_mfma_f32_16x16x32_bf16 v[74:77], v[156:159], v[238:241], v[74:77]
	v_mfma_f32_16x16x32_bf16 v[126:129], v[152:155], v[214:217], v[126:129]
	v_mfma_f32_16x16x32_bf16 v[122:125], v[190:193], v[214:217], v[122:125]
	v_mfma_f32_16x16x32_bf16 v[110:113], v[152:155], v[222:225], v[110:113]
	v_mfma_f32_16x16x32_bf16 v[106:109], v[190:193], v[222:225], v[106:109]
	v_mfma_f32_16x16x32_bf16 v[94:97], v[152:155], v[234:237], v[94:97]
	v_mfma_f32_16x16x32_bf16 v[90:93], v[190:193], v[234:237], v[90:93]
	v_mfma_f32_16x16x32_bf16 v[78:81], v[152:155], v[242:245], v[78:81]
	v_mfma_f32_16x16x32_bf16 v[74:77], v[190:193], v[242:245], v[74:77]
	v_mfma_f32_16x16x32_bf16 v[118:121], v[194:197], v[210:213], v[118:121]
	v_mfma_f32_16x16x32_bf16 v[114:117], v[202:205], v[210:213], v[114:117]
	v_mfma_f32_16x16x32_bf16 v[102:105], v[194:197], v[218:221], v[102:105]
	v_mfma_f32_16x16x32_bf16 v[98:101], v[202:205], v[218:221], v[98:101]
	v_mfma_f32_16x16x32_bf16 v[86:89], v[194:197], v[226:229], v[86:89]
	v_mfma_f32_16x16x32_bf16 v[82:85], v[202:205], v[226:229], v[82:85]
	v_mfma_f32_16x16x32_bf16 v[70:73], v[194:197], v[238:241], v[70:73]
	v_mfma_f32_16x16x32_bf16 v[66:69], v[202:205], v[238:241], v[66:69]
	v_mfma_f32_16x16x32_bf16 v[118:121], v[198:201], v[214:217], v[118:121]
	v_mfma_f32_16x16x32_bf16 v[114:117], v[206:209], v[214:217], v[114:117]
	v_mfma_f32_16x16x32_bf16 v[102:105], v[198:201], v[222:225], v[102:105]
	v_mfma_f32_16x16x32_bf16 v[98:101], v[206:209], v[222:225], v[98:101]
	v_mfma_f32_16x16x32_bf16 v[86:89], v[198:201], v[234:237], v[86:89]
	v_mfma_f32_16x16x32_bf16 v[82:85], v[206:209], v[234:237], v[82:85]
	v_mfma_f32_16x16x32_bf16 v[70:73], v[198:201], v[242:245], v[70:73]
	v_mfma_f32_16x16x32_bf16 v[66:69], v[206:209], v[242:245], v[66:69]
	s_setprio 0
	s_barrier
	s_add_i32 s60, s64, s79
	s_add_u32 s98, s98, s16
	s_addc_u32 s99, s99, s17
	s_mov_b32 m0, s60
	ds_read_b128 v[210:213], v188 offset:49152
	ds_read_b128 v[214:217], v188 offset:50176
	ds_read_b128 v[218:221], v188 offset:51200
	ds_read_b128 v[222:225], v188 offset:52224
	ds_read_b128 v[226:229], v188 offset:53248
	ds_read_b128 v[234:237], v188 offset:54272
	ds_read_b128 v[238:241], v188 offset:55296
	ds_read_b128 v[242:245], v188 offset:56320
	global_load_lds_dwordx4 v136, s[98:99]
	s_add_i32 m0, s60, 0x2000
	s_add_u32 s58, s58, 0x40080
	s_addc_u32 s59, s59, 0
	s_add_i32 s60, s65, s79
	global_load_lds_dwordx4 v140, s[98:99]
	s_mov_b32 m0, s60
	s_nop 0
	global_load_lds_dwordx4 v136, s[58:59]
	s_add_i32 m0, s60, 0x2000
	s_nop 0
	global_load_lds_dwordx4 v140, s[58:59]
	s_add_u32 s100, s100, s16
	s_addc_u32 s101, s101, s17
	s_mov_b32 m0, s86
	s_nop 0
	global_load_lds_dwordx4 v134, s[100:101]
	s_mov_b32 m0, s87
	s_nop 0
	global_load_lds_dwordx4 v138, s[100:101]
	s_waitcnt vmcnt(8)
	s_waitcnt lgkmcnt(0)
	s_barrier
	s_setprio 1
	s_waitcnt lgkmcnt(0)
	v_mfma_f32_16x16x32_bf16 v[62:65], v[148:151], v[210:213], v[62:65]
	v_mfma_f32_16x16x32_bf16 v[58:61], v[156:159], v[210:213], v[58:61]
	v_mfma_f32_16x16x32_bf16 v[46:49], v[148:151], v[218:221], v[46:49]
	v_mfma_f32_16x16x32_bf16 v[42:45], v[156:159], v[218:221], v[42:45]
	v_mfma_f32_16x16x32_bf16 v[30:33], v[148:151], v[226:229], v[30:33]
	v_mfma_f32_16x16x32_bf16 v[26:29], v[156:159], v[226:229], v[26:29]
	v_mfma_f32_16x16x32_bf16 v[14:17], v[148:151], v[238:241], v[14:17]
	v_mfma_f32_16x16x32_bf16 v[10:13], v[156:159], v[238:241], v[10:13]
	v_mfma_f32_16x16x32_bf16 v[62:65], v[152:155], v[214:217], v[62:65]
	v_mfma_f32_16x16x32_bf16 v[58:61], v[190:193], v[214:217], v[58:61]
	v_mfma_f32_16x16x32_bf16 v[46:49], v[152:155], v[222:225], v[46:49]
	v_mfma_f32_16x16x32_bf16 v[42:45], v[190:193], v[222:225], v[42:45]
	v_mfma_f32_16x16x32_bf16 v[30:33], v[152:155], v[234:237], v[30:33]
	v_mfma_f32_16x16x32_bf16 v[26:29], v[190:193], v[234:237], v[26:29]
	v_mfma_f32_16x16x32_bf16 v[14:17], v[152:155], v[242:245], v[14:17]
	v_mfma_f32_16x16x32_bf16 v[10:13], v[190:193], v[242:245], v[10:13]
	v_mfma_f32_16x16x32_bf16 v[54:57], v[194:197], v[210:213], v[54:57]
	v_mfma_f32_16x16x32_bf16 v[50:53], v[202:205], v[210:213], v[50:53]
	v_mfma_f32_16x16x32_bf16 v[38:41], v[194:197], v[218:221], v[38:41]
	v_mfma_f32_16x16x32_bf16 v[34:37], v[202:205], v[218:221], v[34:37]
	v_mfma_f32_16x16x32_bf16 v[22:25], v[194:197], v[226:229], v[22:25]
	v_mfma_f32_16x16x32_bf16 v[18:21], v[202:205], v[226:229], v[18:21]
	v_mfma_f32_16x16x32_bf16 v[6:9], v[194:197], v[238:241], v[6:9]
	v_mfma_f32_16x16x32_bf16 v[2:5], v[202:205], v[238:241], v[2:5]
	v_mfma_f32_16x16x32_bf16 v[54:57], v[198:201], v[214:217], v[54:57]
	v_mfma_f32_16x16x32_bf16 v[50:53], v[206:209], v[214:217], v[50:53]
	v_mfma_f32_16x16x32_bf16 v[38:41], v[198:201], v[222:225], v[38:41]
	v_mfma_f32_16x16x32_bf16 v[34:37], v[206:209], v[222:225], v[34:37]
	v_mfma_f32_16x16x32_bf16 v[22:25], v[198:201], v[234:237], v[22:25]
	v_mfma_f32_16x16x32_bf16 v[18:21], v[206:209], v[234:237], v[18:21]
	v_mfma_f32_16x16x32_bf16 v[6:9], v[198:201], v[242:245], v[6:9]
	v_mfma_f32_16x16x32_bf16 v[2:5], v[206:209], v[242:245], v[2:5]
	s_setprio 0
	s_barrier
	s_add_i32 s63, s63, 2
	s_add_u32 s48, s48, 0x100
	s_addc_u32 s49, s49, 0
	s_add_u32 s57, s57, 0x100
	s_addc_u32 s62, s62, 0
	s_cmp_gt_u32 s63, 13
	s_cbranch_scc0 .LBB0_3227
	s_and_b64 vcc, exec, s[36:37]
	s_cbranch_vccz .LBB0_3231
	s_barrier
	s_andn2_b64 vcc, exec, s[20:21]
	s_cbranch_vccz .LBB0_3232

.LBB0_3538:
	s_add_i32 m0, s49, 0xc000
	s_and_b64 vcc, exec, s[6:7]
	global_load_lds_dwordx4 v210, s[54:55]
	s_add_i32 m0, s49, 0xe000
	s_nop 0
	global_load_lds_dwordx4 v212, s[54:55]
	s_waitcnt vmcnt(8)
	s_waitcnt lgkmcnt(0)
	s_barrier
	s_cbranch_vccnz .LBB0_3540
	s_setprio 1
	s_waitcnt lgkmcnt(0)
	v_mfma_i32_16x16x64_i8 v[176:179], v[180:183], v[4:7], v[176:179]
	v_mfma_i32_16x16x64_i8 v[168:171], v[188:191], v[4:7], v[168:171]
	v_mfma_i32_16x16x64_i8 v[160:163], v[180:183], v[12:15], v[160:163]
	v_mfma_i32_16x16x64_i8 v[152:155], v[188:191], v[12:15], v[152:155]
	v_mfma_i32_16x16x64_i8 v[144:147], v[180:183], v[20:23], v[144:147]
	v_mfma_i32_16x16x64_i8 v[136:139], v[188:191], v[20:23], v[136:139]
	v_mfma_i32_16x16x64_i8 v[120:123], v[180:183], v[28:31], v[120:123]
	v_mfma_i32_16x16x64_i8 v[104:107], v[188:191], v[28:31], v[104:107]
	v_mfma_i32_16x16x64_i8 v[176:179], v[184:187], v[8:11], v[176:179]
	v_mfma_i32_16x16x64_i8 v[168:171], v[192:195], v[8:11], v[168:171]
	v_mfma_i32_16x16x64_i8 v[160:163], v[184:187], v[16:19], v[160:163]
	v_mfma_i32_16x16x64_i8 v[152:155], v[192:195], v[16:19], v[152:155]
	v_mfma_i32_16x16x64_i8 v[144:147], v[184:187], v[24:27], v[144:147]
	v_mfma_i32_16x16x64_i8 v[136:139], v[192:195], v[24:27], v[136:139]
	v_mfma_i32_16x16x64_i8 v[120:123], v[184:187], v[32:35], v[120:123]
	v_mfma_i32_16x16x64_i8 v[104:107], v[192:195], v[32:35], v[104:107]
	v_mfma_i32_16x16x64_i8 v[172:175], v[108:111], v[4:7], v[172:175]
	v_mfma_i32_16x16x64_i8 v[164:167], v[124:127], v[4:7], v[164:167]
	v_mfma_i32_16x16x64_i8 v[156:159], v[108:111], v[12:15], v[156:159]
	v_mfma_i32_16x16x64_i8 v[148:151], v[124:127], v[12:15], v[148:151]
	v_mfma_i32_16x16x64_i8 v[140:143], v[108:111], v[20:23], v[140:143]
	v_mfma_i32_16x16x64_i8 v[132:135], v[124:127], v[20:23], v[132:135]
	v_mfma_i32_16x16x64_i8 v[116:119], v[108:111], v[28:31], v[116:119]
	v_mfma_i32_16x16x64_i8 v[100:103], v[124:127], v[28:31], v[100:103]
	v_mfma_i32_16x16x64_i8 v[172:175], v[112:115], v[8:11], v[172:175]
	v_mfma_i32_16x16x64_i8 v[164:167], v[128:131], v[8:11], v[164:167]
	v_mfma_i32_16x16x64_i8 v[156:159], v[112:115], v[16:19], v[156:159]
	v_mfma_i32_16x16x64_i8 v[148:151], v[128:131], v[16:19], v[148:151]
	v_mfma_i32_16x16x64_i8 v[140:143], v[112:115], v[24:27], v[140:143]
	v_mfma_i32_16x16x64_i8 v[132:135], v[128:131], v[24:27], v[132:135]
	v_mfma_i32_16x16x64_i8 v[116:119], v[112:115], v[32:35], v[116:119]
	v_mfma_i32_16x16x64_i8 v[100:103], v[128:131], v[32:35], v[100:103]
	s_setprio 0

.LBB0_3542:
	s_add_u32 s56, s54, 0xfffe0080
	s_addc_u32 s57, s55, -1
	s_cmp_eq_u32 s97, 4
	s_cselect_b32 s59, s39, s57
	s_cselect_b32 s58, s93, s56
	s_cselect_b32 s57, s37, s96
	s_cselect_b32 s56, s94, s95
	s_mov_b32 m0, s51
	s_mov_b64 s[98:99], s[56:57]
	s_add_u32 vcc_lo, s56, 0x20000
	global_load_lds_dwordx4 v200, s[56:57]
	s_mov_b32 m0, s73
	s_addc_u32 vcc_hi, s57, 0
	global_load_lds_dwordx4 v204, s[56:57]
	v_lshl_add_u64 v[216:217], vcc, 0, v[200:201]
	s_mov_b32 m0, s74
	s_mov_b64 s[100:101], s[58:59]
	global_load_lds_dwordx4 v[216:217], off
	v_lshl_add_u64 v[216:217], vcc, 0, v[204:205]
	s_mov_b32 m0, s75
	s_and_b64 vcc, exec, s[4:5]
	global_load_lds_dwordx4 v[216:217], off
	s_mov_b32 m0, s49
	s_nop 0
	global_load_lds_dwordx4 v198, s[58:59]
	s_mov_b32 m0, s76
	s_nop 0
	global_load_lds_dwordx4 v202, s[58:59]
	s_waitcnt vmcnt(8)
	s_waitcnt lgkmcnt(0)
	s_barrier
	s_cbranch_vccnz .LBB0_3544
	s_setprio 1
	s_waitcnt lgkmcnt(0)
	v_mfma_i32_16x16x64_i8 v[96:99], v[180:183], v[4:7], v[96:99]
	v_mfma_i32_16x16x64_i8 v[88:91], v[188:191], v[4:7], v[88:91]
	v_mfma_i32_16x16x64_i8 v[80:83], v[180:183], v[12:15], v[80:83]
	v_mfma_i32_16x16x64_i8 v[72:75], v[188:191], v[12:15], v[72:75]
	v_mfma_i32_16x16x64_i8 v[64:67], v[180:183], v[20:23], v[64:67]
	v_mfma_i32_16x16x64_i8 v[56:59], v[188:191], v[20:23], v[56:59]
	v_mfma_i32_16x16x64_i8 v[48:51], v[180:183], v[28:31], v[48:51]
	v_mfma_i32_16x16x64_i8 v[40:43], v[188:191], v[28:31], v[40:43]
	v_mfma_i32_16x16x64_i8 v[96:99], v[184:187], v[8:11], v[96:99]
	v_mfma_i32_16x16x64_i8 v[88:91], v[192:195], v[8:11], v[88:91]
	v_mfma_i32_16x16x64_i8 v[80:83], v[184:187], v[16:19], v[80:83]
	v_mfma_i32_16x16x64_i8 v[72:75], v[192:195], v[16:19], v[72:75]
	v_mfma_i32_16x16x64_i8 v[64:67], v[184:187], v[24:27], v[64:67]
	v_mfma_i32_16x16x64_i8 v[56:59], v[192:195], v[24:27], v[56:59]
	v_mfma_i32_16x16x64_i8 v[48:51], v[184:187], v[32:35], v[48:51]
	v_mfma_i32_16x16x64_i8 v[40:43], v[192:195], v[32:35], v[40:43]
	v_mfma_i32_16x16x64_i8 v[92:95], v[108:111], v[4:7], v[92:95]
	v_mfma_i32_16x16x64_i8 v[84:87], v[124:127], v[4:7], v[84:87]
	v_mfma_i32_16x16x64_i8 v[76:79], v[108:111], v[12:15], v[76:79]
	v_mfma_i32_16x16x64_i8 v[68:71], v[124:127], v[12:15], v[68:71]
	v_mfma_i32_16x16x64_i8 v[60:63], v[108:111], v[20:23], v[60:63]
	v_mfma_i32_16x16x64_i8 v[52:55], v[124:127], v[20:23], v[52:55]
	v_mfma_i32_16x16x64_i8 v[44:47], v[108:111], v[28:31], v[44:47]
	v_mfma_i32_16x16x64_i8 v[36:39], v[124:127], v[28:31], v[36:39]
	v_mfma_i32_16x16x64_i8 v[92:95], v[112:115], v[8:11], v[92:95]
	v_mfma_i32_16x16x64_i8 v[84:87], v[128:131], v[8:11], v[84:87]
	v_mfma_i32_16x16x64_i8 v[76:79], v[112:115], v[16:19], v[76:79]
	v_mfma_i32_16x16x64_i8 v[68:71], v[128:131], v[16:19], v[68:71]
	v_mfma_i32_16x16x64_i8 v[60:63], v[112:115], v[24:27], v[60:63]
	v_mfma_i32_16x16x64_i8 v[52:55], v[128:131], v[24:27], v[52:55]
	v_mfma_i32_16x16x64_i8 v[44:47], v[112:115], v[32:35], v[44:47]
	v_mfma_i32_16x16x64_i8 v[36:39], v[128:131], v[32:35], v[36:39]
	s_setprio 0

.LBB0_3546:
	s_add_u32 s58, s58, 0x20000
	s_addc_u32 s59, s59, 0
	s_mov_b32 m0, s77
	s_nop 0
	global_load_lds_dwordx4 v198, s[58:59]
	s_mov_b32 m0, s78
	s_and_b64 vcc, exec, s[6:7]
	global_load_lds_dwordx4 v202, s[58:59]
	s_waitcnt vmcnt(8)
	s_waitcnt lgkmcnt(0)
	s_barrier
	s_cbranch_vccnz .LBB0_3548
	s_setprio 1
	s_waitcnt lgkmcnt(0)
	v_mfma_i32_16x16x64_i8 v[176:179], v[180:183], v[4:7], v[176:179]
	v_mfma_i32_16x16x64_i8 v[168:171], v[188:191], v[4:7], v[168:171]
	v_mfma_i32_16x16x64_i8 v[160:163], v[180:183], v[12:15], v[160:163]
	v_mfma_i32_16x16x64_i8 v[152:155], v[188:191], v[12:15], v[152:155]
	v_mfma_i32_16x16x64_i8 v[144:147], v[180:183], v[20:23], v[144:147]
	v_mfma_i32_16x16x64_i8 v[136:139], v[188:191], v[20:23], v[136:139]
	v_mfma_i32_16x16x64_i8 v[120:123], v[180:183], v[28:31], v[120:123]
	v_mfma_i32_16x16x64_i8 v[104:107], v[188:191], v[28:31], v[104:107]
	v_mfma_i32_16x16x64_i8 v[176:179], v[184:187], v[8:11], v[176:179]
	v_mfma_i32_16x16x64_i8 v[168:171], v[192:195], v[8:11], v[168:171]
	v_mfma_i32_16x16x64_i8 v[160:163], v[184:187], v[16:19], v[160:163]
	v_mfma_i32_16x16x64_i8 v[152:155], v[192:195], v[16:19], v[152:155]
	v_mfma_i32_16x16x64_i8 v[144:147], v[184:187], v[24:27], v[144:147]
	v_mfma_i32_16x16x64_i8 v[136:139], v[192:195], v[24:27], v[136:139]
	v_mfma_i32_16x16x64_i8 v[120:123], v[184:187], v[32:35], v[120:123]
	v_mfma_i32_16x16x64_i8 v[104:107], v[192:195], v[32:35], v[104:107]
	v_mfma_i32_16x16x64_i8 v[172:175], v[108:111], v[4:7], v[172:175]
	v_mfma_i32_16x16x64_i8 v[164:167], v[124:127], v[4:7], v[164:167]
	v_mfma_i32_16x16x64_i8 v[156:159], v[108:111], v[12:15], v[156:159]
	v_mfma_i32_16x16x64_i8 v[148:151], v[124:127], v[12:15], v[148:151]
	v_mfma_i32_16x16x64_i8 v[140:143], v[108:111], v[20:23], v[140:143]
	v_mfma_i32_16x16x64_i8 v[132:135], v[124:127], v[20:23], v[132:135]
	v_mfma_i32_16x16x64_i8 v[116:119], v[108:111], v[28:31], v[116:119]
	v_mfma_i32_16x16x64_i8 v[100:103], v[124:127], v[28:31], v[100:103]
	v_mfma_i32_16x16x64_i8 v[172:175], v[112:115], v[8:11], v[172:175]
	v_mfma_i32_16x16x64_i8 v[164:167], v[128:131], v[8:11], v[164:167]
	v_mfma_i32_16x16x64_i8 v[156:159], v[112:115], v[16:19], v[156:159]
	v_mfma_i32_16x16x64_i8 v[148:151], v[128:131], v[16:19], v[148:151]
	v_mfma_i32_16x16x64_i8 v[140:143], v[112:115], v[24:27], v[140:143]
	v_mfma_i32_16x16x64_i8 v[132:135], v[128:131], v[24:27], v[132:135]
	v_mfma_i32_16x16x64_i8 v[116:119], v[112:115], v[32:35], v[116:119]
	v_mfma_i32_16x16x64_i8 v[100:103], v[128:131], v[32:35], v[100:103]
	s_setprio 0

.LBB0_3550:
	s_mov_b32 m0, s80
	s_add_u32 s98, s98, s18
	s_addc_u32 s99, s99, s19
	s_add_u32 s6, s56, 0x20080
	global_load_lds_dwordx4 v200, s[98:99]
	s_mov_b32 m0, s81
	s_addc_u32 s7, s57, 0
	global_load_lds_dwordx4 v204, s[98:99]
	s_mov_b32 m0, s84
	s_and_b64 vcc, exec, s[4:5]
	global_load_lds_dwordx4 v200, s[6:7]
	s_mov_b32 m0, s85
	s_nop 0
	global_load_lds_dwordx4 v204, s[6:7]
	s_add_u32 s100, s100, s18
	s_addc_u32 s101, s101, s19
	s_mov_b32 m0, s82
	s_nop 0
	global_load_lds_dwordx4 v198, s[100:101]
	s_mov_b32 m0, s83
	s_nop 0
	global_load_lds_dwordx4 v202, s[100:101]
	s_waitcnt vmcnt(8)
	s_waitcnt lgkmcnt(0)
	s_barrier
	s_cbranch_vccnz .LBB0_3535
	s_setprio 1
	s_waitcnt lgkmcnt(0)
	v_mfma_i32_16x16x64_i8 v[96:99], v[180:183], v[4:7], v[96:99]
	v_mfma_i32_16x16x64_i8 v[88:91], v[188:191], v[4:7], v[88:91]
	v_mfma_i32_16x16x64_i8 v[80:83], v[180:183], v[12:15], v[80:83]
	v_mfma_i32_16x16x64_i8 v[72:75], v[188:191], v[12:15], v[72:75]
	v_mfma_i32_16x16x64_i8 v[64:67], v[180:183], v[20:23], v[64:67]
	v_mfma_i32_16x16x64_i8 v[56:59], v[188:191], v[20:23], v[56:59]
	v_mfma_i32_16x16x64_i8 v[48:51], v[180:183], v[28:31], v[48:51]
	v_mfma_i32_16x16x64_i8 v[40:43], v[188:191], v[28:31], v[40:43]
	v_mfma_i32_16x16x64_i8 v[96:99], v[184:187], v[8:11], v[96:99]
	v_mfma_i32_16x16x64_i8 v[88:91], v[192:195], v[8:11], v[88:91]
	v_mfma_i32_16x16x64_i8 v[80:83], v[184:187], v[16:19], v[80:83]
	v_mfma_i32_16x16x64_i8 v[72:75], v[192:195], v[16:19], v[72:75]
	v_mfma_i32_16x16x64_i8 v[64:67], v[184:187], v[24:27], v[64:67]
	v_mfma_i32_16x16x64_i8 v[56:59], v[192:195], v[24:27], v[56:59]
	v_mfma_i32_16x16x64_i8 v[48:51], v[184:187], v[32:35], v[48:51]
	v_mfma_i32_16x16x64_i8 v[40:43], v[192:195], v[32:35], v[40:43]
	v_mfma_i32_16x16x64_i8 v[92:95], v[108:111], v[4:7], v[92:95]
	v_mfma_i32_16x16x64_i8 v[84:87], v[124:127], v[4:7], v[84:87]
	v_mfma_i32_16x16x64_i8 v[76:79], v[108:111], v[12:15], v[76:79]
	v_mfma_i32_16x16x64_i8 v[68:71], v[124:127], v[12:15], v[68:71]
	v_mfma_i32_16x16x64_i8 v[60:63], v[108:111], v[20:23], v[60:63]
	v_mfma_i32_16x16x64_i8 v[52:55], v[124:127], v[20:23], v[52:55]
	v_mfma_i32_16x16x64_i8 v[44:47], v[108:111], v[28:31], v[44:47]
	v_mfma_i32_16x16x64_i8 v[36:39], v[124:127], v[28:31], v[36:39]
	v_mfma_i32_16x16x64_i8 v[92:95], v[112:115], v[8:11], v[92:95]
	v_mfma_i32_16x16x64_i8 v[84:87], v[128:131], v[8:11], v[84:87]
	v_mfma_i32_16x16x64_i8 v[76:79], v[112:115], v[16:19], v[76:79]
	v_mfma_i32_16x16x64_i8 v[68:71], v[128:131], v[16:19], v[68:71]
	v_mfma_i32_16x16x64_i8 v[60:63], v[112:115], v[24:27], v[60:63]
	v_mfma_i32_16x16x64_i8 v[52:55], v[128:131], v[24:27], v[52:55]
	v_mfma_i32_16x16x64_i8 v[44:47], v[112:115], v[32:35], v[44:47]
	v_mfma_i32_16x16x64_i8 v[36:39], v[128:131], v[32:35], v[36:39]
	s_setprio 0
	s_branch .LBB0_3535

.LBB0_3694:
	s_add_u32 s22, s20, 0xfff50080
	s_addc_u32 s23, s21, -1
	s_add_i32 s57, 0, 0x10000
	s_cmp_eq_u32 s56, 40
	s_cselect_b32 s25, s5, s23
	s_cselect_b32 s24, s4, s22
	v_add_u32_e32 v153, s57, v151
	s_cselect_b32 s23, s19, s55
	s_cselect_b32 s22, s18, s54
	s_add_i32 s60, 0, 0x14000
	ds_read_b128 v[146:149], v153
	ds_read_b128 v[154:157], v153 offset:1024
	ds_read_b128 v[158:161], v153 offset:2048
	ds_read_b128 v[162:165], v153 offset:3072
	v_add_u32_e32 v153, s60, v151
	ds_read_b128 v[166:169], v153
	ds_read_b128 v[170:173], v153 offset:1024
	ds_read_b128 v[174:177], v153 offset:2048
	ds_read_b128 v[178:181], v153 offset:3072
	s_add_i32 m0, s41, 0xc000
	ds_read_b128 v[182:185], v152
	ds_read_b128 v[186:189], v152 offset:1024
	ds_read_b128 v[190:193], v152 offset:2048
	ds_read_b128 v[194:197], v152 offset:3072
	ds_read_b128 v[198:201], v152 offset:4096
	ds_read_b128 v[202:205], v152 offset:5120
	ds_read_b128 v[206:209], v152 offset:6144
	ds_read_b128 v[210:213], v152 offset:7168
	global_load_lds_dwordx4 v142, s[20:21]
	s_add_i32 m0, s41, 0xe000
	s_nop 0
	global_load_lds_dwordx4 v144, s[20:21]
	s_waitcnt vmcnt(8)
	s_waitcnt lgkmcnt(0)
	s_barrier
	s_setprio 1
	s_waitcnt lgkmcnt(0)
	v_mfma_f32_16x16x32_bf16 v[124:127], v[146:149], v[182:185], v[124:127]
	v_mfma_f32_16x16x32_bf16 v[120:123], v[158:161], v[182:185], v[120:123]
	v_mfma_f32_16x16x32_bf16 v[108:111], v[146:149], v[190:193], v[108:111]
	v_mfma_f32_16x16x32_bf16 v[104:107], v[158:161], v[190:193], v[104:107]
	v_mfma_f32_16x16x32_bf16 v[92:95], v[146:149], v[198:201], v[92:95]
	v_mfma_f32_16x16x32_bf16 v[88:91], v[158:161], v[198:201], v[88:91]
	v_mfma_f32_16x16x32_bf16 v[76:79], v[146:149], v[206:209], v[76:79]
	v_mfma_f32_16x16x32_bf16 v[72:75], v[158:161], v[206:209], v[72:75]
	v_mfma_f32_16x16x32_bf16 v[124:127], v[154:157], v[186:189], v[124:127]
	v_mfma_f32_16x16x32_bf16 v[120:123], v[162:165], v[186:189], v[120:123]
	v_mfma_f32_16x16x32_bf16 v[108:111], v[154:157], v[194:197], v[108:111]
	v_mfma_f32_16x16x32_bf16 v[104:107], v[162:165], v[194:197], v[104:107]
	v_mfma_f32_16x16x32_bf16 v[92:95], v[154:157], v[202:205], v[92:95]
	v_mfma_f32_16x16x32_bf16 v[88:91], v[162:165], v[202:205], v[88:91]
	v_mfma_f32_16x16x32_bf16 v[76:79], v[154:157], v[210:213], v[76:79]
	v_mfma_f32_16x16x32_bf16 v[72:75], v[162:165], v[210:213], v[72:75]
	v_mfma_f32_16x16x32_bf16 v[116:119], v[166:169], v[182:185], v[116:119]
	v_mfma_f32_16x16x32_bf16 v[112:115], v[174:177], v[182:185], v[112:115]
	v_mfma_f32_16x16x32_bf16 v[100:103], v[166:169], v[190:193], v[100:103]
	v_mfma_f32_16x16x32_bf16 v[96:99], v[174:177], v[190:193], v[96:99]
	v_mfma_f32_16x16x32_bf16 v[84:87], v[166:169], v[198:201], v[84:87]
	v_mfma_f32_16x16x32_bf16 v[80:83], v[174:177], v[198:201], v[80:83]
	v_mfma_f32_16x16x32_bf16 v[68:71], v[166:169], v[206:209], v[68:71]
	v_mfma_f32_16x16x32_bf16 v[64:67], v[174:177], v[206:209], v[64:67]
	v_mfma_f32_16x16x32_bf16 v[116:119], v[170:173], v[186:189], v[116:119]
	v_mfma_f32_16x16x32_bf16 v[112:115], v[178:181], v[186:189], v[112:115]
	v_mfma_f32_16x16x32_bf16 v[100:103], v[170:173], v[194:197], v[100:103]
	v_mfma_f32_16x16x32_bf16 v[96:99], v[178:181], v[194:197], v[96:99]
	v_mfma_f32_16x16x32_bf16 v[84:87], v[170:173], v[202:205], v[84:87]
	v_mfma_f32_16x16x32_bf16 v[80:83], v[178:181], v[202:205], v[80:83]
	v_mfma_f32_16x16x32_bf16 v[68:71], v[170:173], v[210:213], v[68:71]
	v_mfma_f32_16x16x32_bf16 v[64:67], v[178:181], v[210:213], v[64:67]
	s_setprio 0
	s_barrier
	s_add_i32 s57, s57, s40
	s_mov_b64 s[98:99], s[22:23]
	s_mov_b32 m0, s57
	ds_read_b128 v[182:185], v152 offset:16384
	ds_read_b128 v[186:189], v152 offset:17408
	ds_read_b128 v[190:193], v152 offset:18432
	ds_read_b128 v[194:197], v152 offset:19456
	ds_read_b128 v[198:201], v152 offset:20480
	ds_read_b128 v[202:205], v152 offset:21504
	ds_read_b128 v[206:209], v152 offset:22528
	ds_read_b128 v[210:213], v152 offset:23552
	global_load_lds_dwordx4 v128, s[22:23]
	s_add_i32 m0, s57, 0x2000
	s_add_u32 s58, s22, 0xb0000
	s_addc_u32 s59, s23, 0
	s_add_i32 s57, s60, s40
	global_load_lds_dwordx4 v138, s[22:23]
	s_mov_b32 m0, s57
	s_mov_b64 s[100:101], s[24:25]
	global_load_lds_dwordx4 v128, s[58:59]
	s_add_i32 m0, s57, 0x2000
	s_nop 0
	global_load_lds_dwordx4 v138, s[58:59]
	s_mov_b32 m0, s41
	s_nop 0
	global_load_lds_dwordx4 v134, s[24:25]
	s_mov_b32 m0, s42
	s_nop 0
	global_load_lds_dwordx4 v136, s[24:25]
	s_waitcnt vmcnt(8)
	s_waitcnt lgkmcnt(0)
	s_barrier
	s_setprio 1
	s_waitcnt lgkmcnt(0)
	v_mfma_f32_16x16x32_bf16 v[60:63], v[146:149], v[182:185], v[60:63]
	v_mfma_f32_16x16x32_bf16 v[56:59], v[158:161], v[182:185], v[56:59]
	v_mfma_f32_16x16x32_bf16 v[44:47], v[146:149], v[190:193], v[44:47]
	v_mfma_f32_16x16x32_bf16 v[40:43], v[158:161], v[190:193], v[40:43]
	v_mfma_f32_16x16x32_bf16 v[28:31], v[146:149], v[198:201], v[28:31]
	v_mfma_f32_16x16x32_bf16 v[24:27], v[158:161], v[198:201], v[24:27]
	v_mfma_f32_16x16x32_bf16 v[12:15], v[146:149], v[206:209], v[12:15]
	v_mfma_f32_16x16x32_bf16 v[8:11], v[158:161], v[206:209], v[8:11]
	v_mfma_f32_16x16x32_bf16 v[60:63], v[154:157], v[186:189], v[60:63]
	v_mfma_f32_16x16x32_bf16 v[56:59], v[162:165], v[186:189], v[56:59]
	v_mfma_f32_16x16x32_bf16 v[44:47], v[154:157], v[194:197], v[44:47]
	v_mfma_f32_16x16x32_bf16 v[40:43], v[162:165], v[194:197], v[40:43]
	v_mfma_f32_16x16x32_bf16 v[28:31], v[154:157], v[202:205], v[28:31]
	v_mfma_f32_16x16x32_bf16 v[24:27], v[162:165], v[202:205], v[24:27]
	v_mfma_f32_16x16x32_bf16 v[12:15], v[154:157], v[210:213], v[12:15]
	v_mfma_f32_16x16x32_bf16 v[8:11], v[162:165], v[210:213], v[8:11]
	v_mfma_f32_16x16x32_bf16 v[52:55], v[166:169], v[182:185], v[52:55]
	v_mfma_f32_16x16x32_bf16 v[48:51], v[174:177], v[182:185], v[48:51]
	v_mfma_f32_16x16x32_bf16 v[36:39], v[166:169], v[190:193], v[36:39]
	v_mfma_f32_16x16x32_bf16 v[32:35], v[174:177], v[190:193], v[32:35]
	v_mfma_f32_16x16x32_bf16 v[20:23], v[166:169], v[198:201], v[20:23]
	v_mfma_f32_16x16x32_bf16 v[16:19], v[174:177], v[198:201], v[16:19]
	v_mfma_f32_16x16x32_bf16 v[4:7], v[166:169], v[206:209], v[4:7]
	v_mfma_f32_16x16x32_bf16 v[0:3], v[174:177], v[206:209], v[0:3]
	v_mfma_f32_16x16x32_bf16 v[52:55], v[170:173], v[186:189], v[52:55]
	v_mfma_f32_16x16x32_bf16 v[48:51], v[178:181], v[186:189], v[48:51]
	v_mfma_f32_16x16x32_bf16 v[36:39], v[170:173], v[194:197], v[36:39]
	v_mfma_f32_16x16x32_bf16 v[32:35], v[178:181], v[194:197], v[32:35]
	v_mfma_f32_16x16x32_bf16 v[20:23], v[170:173], v[202:205], v[20:23]
	v_mfma_f32_16x16x32_bf16 v[16:19], v[178:181], v[202:205], v[16:19]
	v_mfma_f32_16x16x32_bf16 v[4:7], v[170:173], v[210:213], v[4:7]
	v_mfma_f32_16x16x32_bf16 v[0:3], v[178:181], v[210:213], v[0:3]
	s_setprio 0
	s_barrier
	s_add_i32 s57, 0, 0x18000
	v_add_u32_e32 v153, s57, v151
	s_add_i32 s58, 0, 0x1c000
	ds_read_b128 v[146:149], v153
	ds_read_b128 v[154:157], v153 offset:1024
	ds_read_b128 v[158:161], v153 offset:2048
	ds_read_b128 v[162:165], v153 offset:3072
	v_add_u32_e32 v153, s58, v151
	ds_read_b128 v[166:169], v153
	ds_read_b128 v[170:173], v153 offset:1024
	ds_read_b128 v[174:177], v153 offset:2048
	ds_read_b128 v[178:181], v153 offset:3072
	s_add_u32 s24, s24, 0xb0000
	s_addc_u32 s25, s25, 0
	s_mov_b32 m0, s43
	ds_read_b128 v[182:185], v152 offset:32768
	ds_read_b128 v[186:189], v152 offset:33792
	ds_read_b128 v[190:193], v152 offset:34816
	ds_read_b128 v[194:197], v152 offset:35840
	ds_read_b128 v[198:201], v152 offset:36864
	ds_read_b128 v[202:205], v152 offset:37888
	ds_read_b128 v[206:209], v152 offset:38912
	ds_read_b128 v[210:213], v152 offset:39936
	global_load_lds_dwordx4 v134, s[24:25]
	s_mov_b32 m0, s44
	s_nop 0
	global_load_lds_dwordx4 v136, s[24:25]
	s_waitcnt vmcnt(8)
	s_waitcnt lgkmcnt(0)
	s_barrier
	s_setprio 1
	s_waitcnt lgkmcnt(0)
	v_mfma_f32_16x16x32_bf16 v[124:127], v[146:149], v[182:185], v[124:127]
	v_mfma_f32_16x16x32_bf16 v[120:123], v[158:161], v[182:185], v[120:123]
	v_mfma_f32_16x16x32_bf16 v[108:111], v[146:149], v[190:193], v[108:111]
	v_mfma_f32_16x16x32_bf16 v[104:107], v[158:161], v[190:193], v[104:107]
	v_mfma_f32_16x16x32_bf16 v[92:95], v[146:149], v[198:201], v[92:95]
	v_mfma_f32_16x16x32_bf16 v[88:91], v[158:161], v[198:201], v[88:91]
	v_mfma_f32_16x16x32_bf16 v[76:79], v[146:149], v[206:209], v[76:79]
	v_mfma_f32_16x16x32_bf16 v[72:75], v[158:161], v[206:209], v[72:75]
	v_mfma_f32_16x16x32_bf16 v[124:127], v[154:157], v[186:189], v[124:127]
	v_mfma_f32_16x16x32_bf16 v[120:123], v[162:165], v[186:189], v[120:123]
	v_mfma_f32_16x16x32_bf16 v[108:111], v[154:157], v[194:197], v[108:111]
	v_mfma_f32_16x16x32_bf16 v[104:107], v[162:165], v[194:197], v[104:107]
	v_mfma_f32_16x16x32_bf16 v[92:95], v[154:157], v[202:205], v[92:95]
	v_mfma_f32_16x16x32_bf16 v[88:91], v[162:165], v[202:205], v[88:91]
	v_mfma_f32_16x16x32_bf16 v[76:79], v[154:157], v[210:213], v[76:79]
	v_mfma_f32_16x16x32_bf16 v[72:75], v[162:165], v[210:213], v[72:75]
	v_mfma_f32_16x16x32_bf16 v[116:119], v[166:169], v[182:185], v[116:119]
	v_mfma_f32_16x16x32_bf16 v[112:115], v[174:177], v[182:185], v[112:115]
	v_mfma_f32_16x16x32_bf16 v[100:103], v[166:169], v[190:193], v[100:103]
	v_mfma_f32_16x16x32_bf16 v[96:99], v[174:177], v[190:193], v[96:99]
	v_mfma_f32_16x16x32_bf16 v[84:87], v[166:169], v[198:201], v[84:87]
	v_mfma_f32_16x16x32_bf16 v[80:83], v[174:177], v[198:201], v[80:83]
	v_mfma_f32_16x16x32_bf16 v[68:71], v[166:169], v[206:209], v[68:71]
	v_mfma_f32_16x16x32_bf16 v[64:67], v[174:177], v[206:209], v[64:67]
	v_mfma_f32_16x16x32_bf16 v[116:119], v[170:173], v[186:189], v[116:119]
	v_mfma_f32_16x16x32_bf16 v[112:115], v[178:181], v[186:189], v[112:115]
	v_mfma_f32_16x16x32_bf16 v[100:103], v[170:173], v[194:197], v[100:103]
	v_mfma_f32_16x16x32_bf16 v[96:99], v[178:181], v[194:197], v[96:99]
	v_mfma_f32_16x16x32_bf16 v[84:87], v[170:173], v[202:205], v[84:87]
	v_mfma_f32_16x16x32_bf16 v[80:83], v[178:181], v[202:205], v[80:83]
	v_mfma_f32_16x16x32_bf16 v[68:71], v[170:173], v[210:213], v[68:71]
	v_mfma_f32_16x16x32_bf16 v[64:67], v[178:181], v[210:213], v[64:67]
	s_setprio 0
	s_barrier
	s_add_i32 s24, s57, s40
	s_add_u32 s98, s98, s6
	s_addc_u32 s99, s99, s7
	s_mov_b32 m0, s24
	ds_read_b128 v[182:185], v152 offset:49152
	ds_read_b128 v[186:189], v152 offset:50176
	ds_read_b128 v[190:193], v152 offset:51200
	ds_read_b128 v[194:197], v152 offset:52224
	ds_read_b128 v[198:201], v152 offset:53248
	ds_read_b128 v[202:205], v152 offset:54272
	ds_read_b128 v[206:209], v152 offset:55296
	ds_read_b128 v[210:213], v152 offset:56320
	global_load_lds_dwordx4 v128, s[98:99]
	s_add_i32 m0, s24, 0x2000
	s_add_u32 s22, s22, 0xb0080
	s_addc_u32 s23, s23, 0
	s_add_i32 s24, s58, s40
	global_load_lds_dwordx4 v138, s[98:99]
	s_mov_b32 m0, s24
	s_nop 0
	global_load_lds_dwordx4 v128, s[22:23]
	s_add_i32 m0, s24, 0x2000
	s_nop 0
	global_load_lds_dwordx4 v138, s[22:23]
	s_add_u32 s100, s100, s6
	s_addc_u32 s101, s101, s7
	s_mov_b32 m0, s45
	s_nop 0
	global_load_lds_dwordx4 v134, s[100:101]
	s_mov_b32 m0, s48
	s_nop 0
	global_load_lds_dwordx4 v136, s[100:101]
	s_waitcnt vmcnt(8)
	s_waitcnt lgkmcnt(0)
	s_barrier
	s_setprio 1
	s_waitcnt lgkmcnt(0)
	v_mfma_f32_16x16x32_bf16 v[60:63], v[146:149], v[182:185], v[60:63]
	v_mfma_f32_16x16x32_bf16 v[56:59], v[158:161], v[182:185], v[56:59]
	v_mfma_f32_16x16x32_bf16 v[44:47], v[146:149], v[190:193], v[44:47]
	v_mfma_f32_16x16x32_bf16 v[40:43], v[158:161], v[190:193], v[40:43]
	v_mfma_f32_16x16x32_bf16 v[28:31], v[146:149], v[198:201], v[28:31]
	v_mfma_f32_16x16x32_bf16 v[24:27], v[158:161], v[198:201], v[24:27]
	v_mfma_f32_16x16x32_bf16 v[12:15], v[146:149], v[206:209], v[12:15]
	v_mfma_f32_16x16x32_bf16 v[8:11], v[158:161], v[206:209], v[8:11]
	v_mfma_f32_16x16x32_bf16 v[60:63], v[154:157], v[186:189], v[60:63]
	v_mfma_f32_16x16x32_bf16 v[56:59], v[162:165], v[186:189], v[56:59]
	v_mfma_f32_16x16x32_bf16 v[44:47], v[154:157], v[194:197], v[44:47]
	v_mfma_f32_16x16x32_bf16 v[40:43], v[162:165], v[194:197], v[40:43]
	v_mfma_f32_16x16x32_bf16 v[28:31], v[154:157], v[202:205], v[28:31]
	v_mfma_f32_16x16x32_bf16 v[24:27], v[162:165], v[202:205], v[24:27]
	v_mfma_f32_16x16x32_bf16 v[12:15], v[154:157], v[210:213], v[12:15]
	v_mfma_f32_16x16x32_bf16 v[8:11], v[162:165], v[210:213], v[8:11]
	v_mfma_f32_16x16x32_bf16 v[52:55], v[166:169], v[182:185], v[52:55]
	v_mfma_f32_16x16x32_bf16 v[48:51], v[174:177], v[182:185], v[48:51]
	v_mfma_f32_16x16x32_bf16 v[36:39], v[166:169], v[190:193], v[36:39]
	v_mfma_f32_16x16x32_bf16 v[32:35], v[174:177], v[190:193], v[32:35]
	v_mfma_f32_16x16x32_bf16 v[20:23], v[166:169], v[198:201], v[20:23]
	v_mfma_f32_16x16x32_bf16 v[16:19], v[174:177], v[198:201], v[16:19]
	v_mfma_f32_16x16x32_bf16 v[4:7], v[166:169], v[206:209], v[4:7]
	v_mfma_f32_16x16x32_bf16 v[0:3], v[174:177], v[206:209], v[0:3]
	v_mfma_f32_16x16x32_bf16 v[52:55], v[170:173], v[186:189], v[52:55]
	v_mfma_f32_16x16x32_bf16 v[48:51], v[178:181], v[186:189], v[48:51]
	v_mfma_f32_16x16x32_bf16 v[36:39], v[170:173], v[194:197], v[36:39]
	v_mfma_f32_16x16x32_bf16 v[32:35], v[178:181], v[194:197], v[32:35]
	v_mfma_f32_16x16x32_bf16 v[20:23], v[170:173], v[202:205], v[20:23]
	v_mfma_f32_16x16x32_bf16 v[16:19], v[178:181], v[202:205], v[16:19]
	v_mfma_f32_16x16x32_bf16 v[4:7], v[170:173], v[210:213], v[4:7]
	v_mfma_f32_16x16x32_bf16 v[0:3], v[178:181], v[210:213], v[0:3]
	s_setprio 0
	s_barrier
	s_add_i32 s56, s56, 2
	s_add_u32 s20, s20, 0x100
	s_addc_u32 s21, s21, 0
	s_add_u32 s54, s54, 0x100
	s_addc_u32 s55, s55, 0
	s_cmp_gt_u32 s56, 41
	s_cbranch_scc0 .LBB0_3694
	s_and_b64 vcc, exec, s[16:17]
	s_cbranch_vccz .LBB0_3698
	s_barrier
	s_andn2_b64 vcc, exec, s[12:13]
	s_cbranch_vccz .LBB0_3699
